# m0-hazard s_nops in K-loop load segments replaced by moved ds_reads (38 slots removed)
# speedup vs baseline: 1.0032x; 1.0016x over previous
; #define PG8_STAGE(bufoff, gbase, voff) do { _Pragma("unroll") for (int _i = 0; _i < 2; ++_i) \
;         __builtin_amdgcn_global_load_lds((const unsigned*)((const char*)(gbase) + (voff)[_i]), (LAS unsigned*)(lds + (bufoff) + ldsw + _i * 8192), 16, 0, 0); } while (0)
; #define PG8_LDA(dst, b, h) do { _Pragma("unroll") for (int m = 0; m < 4; ++m) _Pragma("unroll") for (int k = 0; k < 2; ++k) dst[m][k] = *(const LAS bf16x8*)(lds + PG8_SA(b, h) + aoff + m * 2048 + k * 1024); } while (0)
; #define PG8_LDB(dst, b, h) do { _Pragma("unroll") for (int n = 0; n < 2; ++n) _Pragma("unroll") for (int k = 0; k < 2; ++k) dst[n][k] = *(const LAS bf16x8*)(lds + PG8_SB(b, h) + boff + n * 2048 + k * 1024); } while (0)
; #define PG8_SCHED __builtin_amdgcn_sched_barrier(0)
; template <class Epi, bool ALIGN_EPI>
; __device__ __forceinline__ void gemm_phase(LAS unsigned char* lds, const Gemm g, const StaticOrder& S, const Epi& E, const int tid) {
;     ...
;             const bool last = (t == nt - 2);
;             const char* a1 = cA + (size_t)(t + 1) * kstepA;
;             const char* a2 = last ? nA : cA + (size_t)(t + 2) * kstepA; const char* b2 = last ? nB : cB + (size_t)(t + 2) * kstepB;
;             const char* a3 = a2 + kstepA; const char* b3 = b2 + kstepB;
;             PG8_LDB(B0, 0, 0); PG8_LDB(B1, 0, 1); PG8_SCHED; PG8_LDA(At, 0, 0); PG8_STAGE(PG8_SA(1, 1), a1 + hstepA, voffA);
.LBB0_211:
	s_add_u32 s50, s48, 0x4000
	s_addc_u32 s51, s49, 0
	s_cmp_eq_u32 s89, 28
	s_cselect_b32 s54, s87, s50
	s_cselect_b32 s55, s43, s51
	s_cselect_b32 s52, vcc_lo, vcc_hi
	s_cselect_b32 s53, s35, s88
	s_add_u32 s50, s54, 0x8000
	s_addc_u32 s51, s55, 0
	s_add_i32 s90, 0, 0x10000
	v_add_u32_e32 v0, s90, v160
	s_add_i32 s92, 0, 0x14000
	ds_read_b128 v[132:135], v0
	ds_read_b128 v[136:139], v0 offset:1024
	ds_read_b128 v[152:155], v0 offset:2048
	ds_read_b128 v[156:159], v0 offset:3072
	v_add_u32_e32 v0, s92, v160
	ds_read_b128 v[162:165], v0
	ds_read_b128 v[166:169], v0 offset:1024
	ds_read_b128 v[170:173], v0 offset:2048
	ds_read_b128 v[174:177], v0 offset:3072
	s_add_i32 m0, s72, 0xc000
	ds_read_b128 v[178:181], v161
	ds_read_b128 v[182:185], v161 offset:1024
	ds_read_b128 v[186:189], v161 offset:2048
	ds_read_b128 v[190:193], v161 offset:3072
	ds_read_b128 v[194:197], v161 offset:4096
	ds_read_b128 v[198:201], v161 offset:5120
	ds_read_b128 v[214:217], v161 offset:6144

; #define PG8_STAGE(bufoff, gbase, voff) do { _Pragma("unroll") for (int _i = 0; _i < 2; ++_i) \
;         __builtin_amdgcn_global_load_lds((const unsigned*)((const char*)(gbase) + (voff)[_i]), (LAS unsigned*)(lds + (bufoff) + ldsw + _i * 8192), 16, 0, 0); } while (0)
; #define PG8_LDA(dst, b, h) do { _Pragma("unroll") for (int m = 0; m < 4; ++m) _Pragma("unroll") for (int k = 0; k < 2; ++k) dst[m][k] = *(const LAS bf16x8*)(lds + PG8_SA(b, h) + aoff + m * 2048 + k * 1024); } while (0)
; #define PG8_LDB(dst, b, h) do { _Pragma("unroll") for (int n = 0; n < 2; ++n) _Pragma("unroll") for (int k = 0; k < 2; ++k) dst[n][k] = *(const LAS bf16x8*)(lds + PG8_SB(b, h) + boff + n * 2048 + k * 1024); } while (0)
; #define PG8_MMA(ai, bj, At, Bt) do { __builtin_amdgcn_s_setprio(1); _Pragma("unroll") for (int m = 0; m < 4; ++m) _Pragma("unroll") for (int n = 0; n < 2; ++n) _Pragma("unroll") for (int k = 0; k < 2; ++k) \
;         acc[ai][bj][m][n] = __builtin_amdgcn_mfma_f32_16x16x32_bf16(Bt[n][k], At[m][k], acc[ai][bj][m][n], 0, 0, 0); __builtin_amdgcn_s_setprio(0); } while (0)
; #define PG8_WAIT_V(n) asm volatile("s_waitcnt vmcnt(" #n ")" ::: "memory")
; #define PG8_WAIT_L(n) asm volatile("s_waitcnt lgkmcnt(" #n ")" ::: "memory")
; #define PG8_BAR __builtin_amdgcn_s_barrier()
; #define PG8_SCHED __builtin_amdgcn_sched_barrier(0)
; template <class Epi, bool ALIGN_EPI>
; __device__ __forceinline__ void gemm_phase(LAS unsigned char* lds, const Gemm g, const StaticOrder& S, const Epi& E, const int tid) {
;     ...
;             PG8_LDB(B0, 0, 0); PG8_LDB(B1, 0, 1); PG8_SCHED; PG8_LDA(At, 0, 0); PG8_STAGE(PG8_SA(1, 1), a1 + hstepA, voffA);
;             PG8_WAIT_V(8); PG8_WAIT_L(0); PG8_BAR; PG8_MMA(0, 0, At, B0); PG8_MMA(0, 1, At, B1); PG8_BAR; PG8_SCHED;
	global_load_lds_dwordx4 v148, s[48:49]
	s_add_i32 m0, s72, 0xe000
	ds_read_b128 v[218:221], v161 offset:7168
	global_load_lds_dwordx4 v150, s[48:49]
	s_waitcnt vmcnt(8)
	s_waitcnt lgkmcnt(0)
	s_barrier


; #define PG8_MMA(ai, bj, At, Bt) do { __builtin_amdgcn_s_setprio(1); _Pragma("unroll") for (int m = 0; m < 4; ++m) _Pragma("unroll") for (int n = 0; n < 2; ++n) _Pragma("unroll") for (int k = 0; k < 2; ++k) \
;         acc[ai][bj][m][n] = __builtin_amdgcn_mfma_f32_16x16x32_bf16(Bt[n][k], At[m][k], acc[ai][bj][m][n], 0, 0, 0); __builtin_amdgcn_s_setprio(0); } while (0)
; #define PG8_WAIT_V(n) asm volatile("s_waitcnt vmcnt(" #n ")" ::: "memory")
; #define PG8_WAIT_L(n) asm volatile("s_waitcnt lgkmcnt(" #n ")" ::: "memory")
; #define PG8_BAR __builtin_amdgcn_s_barrier()
; #define PG8_SCHED __builtin_amdgcn_sched_barrier(0)
; template <class Epi, bool ALIGN_EPI>
; __device__ __forceinline__ void gemm_phase(LAS unsigned char* lds, const Gemm g, const StaticOrder& S, const Epi& E, const int tid) {
;     ...
;             PG8_WAIT_V(8); PG8_WAIT_L(0); PG8_BAR; PG8_MMA(0, 0, At, B0); PG8_MMA(0, 1, At, B1); PG8_BAR; PG8_SCHED;
	v_mfma_f32_16x16x32_bf16 v[88:91], v[132:135], v[178:181], v[88:91]
	v_mfma_f32_16x16x32_bf16 v[124:127], v[152:155], v[178:181], v[124:127]
	v_mfma_f32_16x16x32_bf16 v[52:55], v[132:135], v[186:189], v[52:55]
	v_mfma_f32_16x16x32_bf16 v[120:123], v[152:155], v[186:189], v[120:123]
	v_mfma_f32_16x16x32_bf16 v[40:43], v[132:135], v[194:197], v[40:43]
	v_mfma_f32_16x16x32_bf16 v[116:119], v[152:155], v[194:197], v[116:119]
	v_mfma_f32_16x16x32_bf16 v[36:39], v[132:135], v[214:217], v[36:39]
	v_mfma_f32_16x16x32_bf16 v[112:115], v[152:155], v[214:217], v[112:115]
	v_mfma_f32_16x16x32_bf16 v[88:91], v[136:139], v[182:185], v[88:91]
	v_mfma_f32_16x16x32_bf16 v[124:127], v[156:159], v[182:185], v[124:127]
	v_mfma_f32_16x16x32_bf16 v[52:55], v[136:139], v[190:193], v[52:55]
	v_mfma_f32_16x16x32_bf16 v[120:123], v[156:159], v[190:193], v[120:123]
	v_mfma_f32_16x16x32_bf16 v[40:43], v[136:139], v[198:201], v[40:43]
	v_mfma_f32_16x16x32_bf16 v[116:119], v[156:159], v[198:201], v[116:119]
	v_mfma_f32_16x16x32_bf16 v[36:39], v[136:139], v[218:221], v[36:39]
	v_mfma_f32_16x16x32_bf16 v[112:115], v[156:159], v[218:221], v[112:115]


; #define PG8_MMA(ai, bj, At, Bt) do { __builtin_amdgcn_s_setprio(1); _Pragma("unroll") for (int m = 0; m < 4; ++m) _Pragma("unroll") for (int n = 0; n < 2; ++n) _Pragma("unroll") for (int k = 0; k < 2; ++k) \
;         acc[ai][bj][m][n] = __builtin_amdgcn_mfma_f32_16x16x32_bf16(Bt[n][k], At[m][k], acc[ai][bj][m][n], 0, 0, 0); __builtin_amdgcn_s_setprio(0); } while (0)
; #define PG8_WAIT_V(n) asm volatile("s_waitcnt vmcnt(" #n ")" ::: "memory")
; #define PG8_WAIT_L(n) asm volatile("s_waitcnt lgkmcnt(" #n ")" ::: "memory")
; #define PG8_BAR __builtin_amdgcn_s_barrier()
; #define PG8_SCHED __builtin_amdgcn_sched_barrier(0)
; template <class Epi, bool ALIGN_EPI>
; __device__ __forceinline__ void gemm_phase(LAS unsigned char* lds, const Gemm g, const StaticOrder& S, const Epi& E, const int tid) {
;     ...
;             PG8_WAIT_V(8); PG8_WAIT_L(0); PG8_BAR; PG8_MMA(0, 0, At, B0); PG8_MMA(0, 1, At, B1); PG8_BAR; PG8_SCHED;
	v_mfma_f32_16x16x32_bf16 v[80:83], v[162:165], v[178:181], v[80:83]
	v_mfma_f32_16x16x32_bf16 v[128:131], v[170:173], v[178:181], v[128:131]
	v_mfma_f32_16x16x32_bf16 v[68:71], v[162:165], v[186:189], v[68:71]
	v_mfma_f32_16x16x32_bf16 v[108:111], v[170:173], v[186:189], v[108:111]
	v_mfma_f32_16x16x32_bf16 v[60:63], v[162:165], v[194:197], v[60:63]
	v_mfma_f32_16x16x32_bf16 v[104:107], v[170:173], v[194:197], v[104:107]
	v_mfma_f32_16x16x32_bf16 v[48:51], v[162:165], v[214:217], v[48:51]
	v_mfma_f32_16x16x32_bf16 v[100:103], v[170:173], v[214:217], v[100:103]
	v_mfma_f32_16x16x32_bf16 v[80:83], v[166:169], v[182:185], v[80:83]
	v_mfma_f32_16x16x32_bf16 v[128:131], v[174:177], v[182:185], v[128:131]
	v_mfma_f32_16x16x32_bf16 v[68:71], v[166:169], v[190:193], v[68:71]
	v_mfma_f32_16x16x32_bf16 v[108:111], v[174:177], v[190:193], v[108:111]
	v_mfma_f32_16x16x32_bf16 v[60:63], v[166:169], v[198:201], v[60:63]
	v_mfma_f32_16x16x32_bf16 v[104:107], v[174:177], v[198:201], v[104:107]
	v_mfma_f32_16x16x32_bf16 v[48:51], v[166:169], v[218:221], v[48:51]
	v_mfma_f32_16x16x32_bf16 v[100:103], v[174:177], v[218:221], v[100:103]

; #define PG8_STAGE(bufoff, gbase, voff) do { _Pragma("unroll") for (int _i = 0; _i < 2; ++_i) \
;         __builtin_amdgcn_global_load_lds((const unsigned*)((const char*)(gbase) + (voff)[_i]), (LAS unsigned*)(lds + (bufoff) + ldsw + _i * 8192), 16, 0, 0); } while (0)
; #define PG8_LDA(dst, b, h) do { _Pragma("unroll") for (int m = 0; m < 4; ++m) _Pragma("unroll") for (int k = 0; k < 2; ++k) dst[m][k] = *(const LAS bf16x8*)(lds + PG8_SA(b, h) + aoff + m * 2048 + k * 1024); } while (0)
; #define PG8_MMA(ai, bj, At, Bt) do { __builtin_amdgcn_s_setprio(1); _Pragma("unroll") for (int m = 0; m < 4; ++m) _Pragma("unroll") for (int n = 0; n < 2; ++n) _Pragma("unroll") for (int k = 0; k < 2; ++k) \
;         acc[ai][bj][m][n] = __builtin_amdgcn_mfma_f32_16x16x32_bf16(Bt[n][k], At[m][k], acc[ai][bj][m][n], 0, 0, 0); __builtin_amdgcn_s_setprio(0); } while (0)
; #define PG8_WAIT_V(n) asm volatile("s_waitcnt vmcnt(" #n ")" ::: "memory")
; #define PG8_WAIT_L(n) asm volatile("s_waitcnt lgkmcnt(" #n ")" ::: "memory")
; #define PG8_BAR __builtin_amdgcn_s_barrier()
; #define PG8_SCHED __builtin_amdgcn_sched_barrier(0)
; template <class Epi, bool ALIGN_EPI>
; __device__ __forceinline__ void gemm_phase(LAS unsigned char* lds, const Gemm g, const StaticOrder& S, const Epi& E, const int tid) {
;     ...
;             PG8_WAIT_V(8); PG8_WAIT_L(0); PG8_BAR; PG8_MMA(0, 0, At, B0); PG8_MMA(0, 1, At, B1); PG8_BAR; PG8_SCHED;
;             PG8_LDA(At, 0, 1); PG8_STAGE(PG8_SB(0, 0), b2, voffB); PG8_STAGE(PG8_SB(0, 1), b2 + hstepB, voffB); PG8_STAGE(PG8_SA(0, 0), a2, voffA);
	s_barrier
	s_add_i32 s90, s90, s71
	s_mov_b32 m0, s90
	ds_read_b128 v[178:181], v161 offset:16384
	ds_read_b128 v[182:185], v161 offset:17408
	ds_read_b128 v[186:189], v161 offset:18432
	ds_read_b128 v[190:193], v161 offset:19456


; #define PG8_STAGE(bufoff, gbase, voff) do { _Pragma("unroll") for (int _i = 0; _i < 2; ++_i) \
;         __builtin_amdgcn_global_load_lds((const unsigned*)((const char*)(gbase) + (voff)[_i]), (LAS unsigned*)(lds + (bufoff) + ldsw + _i * 8192), 16, 0, 0); } while (0)
; #define PG8_LDA(dst, b, h) do { _Pragma("unroll") for (int m = 0; m < 4; ++m) _Pragma("unroll") for (int k = 0; k < 2; ++k) dst[m][k] = *(const LAS bf16x8*)(lds + PG8_SA(b, h) + aoff + m * 2048 + k * 1024); } while (0)
; #define PG8_MMA(ai, bj, At, Bt) do { __builtin_amdgcn_s_setprio(1); _Pragma("unroll") for (int m = 0; m < 4; ++m) _Pragma("unroll") for (int n = 0; n < 2; ++n) _Pragma("unroll") for (int k = 0; k < 2; ++k) \
;         acc[ai][bj][m][n] = __builtin_amdgcn_mfma_f32_16x16x32_bf16(Bt[n][k], At[m][k], acc[ai][bj][m][n], 0, 0, 0); __builtin_amdgcn_s_setprio(0); } while (0)
; #define PG8_WAIT_V(n) asm volatile("s_waitcnt vmcnt(" #n ")" ::: "memory")
; #define PG8_WAIT_L(n) asm volatile("s_waitcnt lgkmcnt(" #n ")" ::: "memory")
; #define PG8_BAR __builtin_amdgcn_s_barrier()
; #define PG8_SCHED __builtin_amdgcn_sched_barrier(0)
; template <class Epi, bool ALIGN_EPI>
; __device__ __forceinline__ void gemm_phase(LAS unsigned char* lds, const Gemm g, const StaticOrder& S, const Epi& E, const int tid) {
;     ...
;             PG8_LDA(At, 0, 1); PG8_STAGE(PG8_SB(0, 0), b2, voffB); PG8_STAGE(PG8_SB(0, 1), b2 + hstepB, voffB); PG8_STAGE(PG8_SA(0, 0), a2, voffA);
;             PG8_WAIT_V(8); PG8_WAIT_L(0); PG8_BAR; PG8_MMA(1, 0, At, B0); PG8_MMA(1, 1, At, B1); PG8_BAR; PG8_SCHED;
	global_load_lds_dwordx4 v144, s[52:53]
	s_add_i32 m0, s90, 0x2000
	s_add_u32 s90, s52, 0x4000
	s_addc_u32 s91, s53, 0
	s_add_i32 s92, s92, s71
	global_load_lds_dwordx4 v140, s[52:53]
	s_mov_b32 m0, s92
	ds_read_b128 v[218:221], v161 offset:23552
	global_load_lds_dwordx4 v144, s[90:91]
	s_add_i32 m0, s92, 0x2000
	ds_read_b128 v[214:217], v161 offset:22528
	global_load_lds_dwordx4 v140, s[90:91]
	s_mov_b32 m0, s72
	ds_read_b128 v[198:201], v161 offset:21504
	global_load_lds_dwordx4 v146, s[54:55]
	s_mov_b32 m0, s73
	ds_read_b128 v[194:197], v161 offset:20480
	global_load_lds_dwordx4 v142, s[54:55]
	s_waitcnt vmcnt(8)
	s_waitcnt lgkmcnt(0)
	s_barrier


; #define PG8_MMA(ai, bj, At, Bt) do { __builtin_amdgcn_s_setprio(1); _Pragma("unroll") for (int m = 0; m < 4; ++m) _Pragma("unroll") for (int n = 0; n < 2; ++n) _Pragma("unroll") for (int k = 0; k < 2; ++k) \
;         acc[ai][bj][m][n] = __builtin_amdgcn_mfma_f32_16x16x32_bf16(Bt[n][k], At[m][k], acc[ai][bj][m][n], 0, 0, 0); __builtin_amdgcn_s_setprio(0); } while (0)
; #define PG8_WAIT_V(n) asm volatile("s_waitcnt vmcnt(" #n ")" ::: "memory")
; #define PG8_WAIT_L(n) asm volatile("s_waitcnt lgkmcnt(" #n ")" ::: "memory")
; #define PG8_BAR __builtin_amdgcn_s_barrier()
; #define PG8_SCHED __builtin_amdgcn_sched_barrier(0)
; template <class Epi, bool ALIGN_EPI>
; __device__ __forceinline__ void gemm_phase(LAS unsigned char* lds, const Gemm g, const StaticOrder& S, const Epi& E, const int tid) {
;     ...
;             PG8_WAIT_V(8); PG8_WAIT_L(0); PG8_BAR; PG8_MMA(1, 0, At, B0); PG8_MMA(1, 1, At, B1); PG8_BAR; PG8_SCHED;
	v_mfma_f32_16x16x32_bf16 v[24:27], v[132:135], v[178:181], v[24:27]
	v_mfma_f32_16x16x32_bf16 v[92:95], v[152:155], v[178:181], v[92:95]
	v_mfma_f32_16x16x32_bf16 v[16:19], v[132:135], v[186:189], v[16:19]
	v_mfma_f32_16x16x32_bf16 v[84:87], v[152:155], v[186:189], v[84:87]
	v_mfma_f32_16x16x32_bf16 v[8:11], v[132:135], v[194:197], v[8:11]
	v_mfma_f32_16x16x32_bf16 v[76:79], v[152:155], v[194:197], v[76:79]
	v_mfma_f32_16x16x32_bf16 v[2:5], v[132:135], v[214:217], v[4:7]
	v_mfma_f32_16x16x32_bf16 v[64:67], v[152:155], v[214:217], v[64:67]
	v_mfma_f32_16x16x32_bf16 v[24:27], v[136:139], v[182:185], v[24:27]
	v_mfma_f32_16x16x32_bf16 v[92:95], v[156:159], v[182:185], v[92:95]
	v_mfma_f32_16x16x32_bf16 v[16:19], v[136:139], v[190:193], v[16:19]
	v_mfma_f32_16x16x32_bf16 v[84:87], v[156:159], v[190:193], v[84:87]
	v_mfma_f32_16x16x32_bf16 v[8:11], v[136:139], v[198:201], v[8:11]
	v_mfma_f32_16x16x32_bf16 v[76:79], v[156:159], v[198:201], v[76:79]
	v_mfma_f32_16x16x32_bf16 v[2:5], v[136:139], v[218:221], v[2:5]
	v_mfma_f32_16x16x32_bf16 v[64:67], v[156:159], v[218:221], v[64:67]


; #define PG8_MMA(ai, bj, At, Bt) do { __builtin_amdgcn_s_setprio(1); _Pragma("unroll") for (int m = 0; m < 4; ++m) _Pragma("unroll") for (int n = 0; n < 2; ++n) _Pragma("unroll") for (int k = 0; k < 2; ++k) \
;         acc[ai][bj][m][n] = __builtin_amdgcn_mfma_f32_16x16x32_bf16(Bt[n][k], At[m][k], acc[ai][bj][m][n], 0, 0, 0); __builtin_amdgcn_s_setprio(0); } while (0)
; #define PG8_WAIT_V(n) asm volatile("s_waitcnt vmcnt(" #n ")" ::: "memory")
; #define PG8_WAIT_L(n) asm volatile("s_waitcnt lgkmcnt(" #n ")" ::: "memory")
; #define PG8_BAR __builtin_amdgcn_s_barrier()
; #define PG8_SCHED __builtin_amdgcn_sched_barrier(0)
; template <class Epi, bool ALIGN_EPI>
; __device__ __forceinline__ void gemm_phase(LAS unsigned char* lds, const Gemm g, const StaticOrder& S, const Epi& E, const int tid) {
;     ...
;             PG8_WAIT_V(8); PG8_WAIT_L(0); PG8_BAR; PG8_MMA(1, 0, At, B0); PG8_MMA(1, 1, At, B1); PG8_BAR; PG8_SCHED;
	v_mfma_f32_16x16x32_bf16 v[32:35], v[162:165], v[178:181], v[32:35]
	v_mfma_f32_16x16x32_bf16 v[72:75], v[170:173], v[178:181], v[72:75]
	v_mfma_f32_16x16x32_bf16 v[28:31], v[162:165], v[186:189], v[28:31]
	v_mfma_f32_16x16x32_bf16 v[96:99], v[170:173], v[186:189], v[96:99]
	v_mfma_f32_16x16x32_bf16 v[20:23], v[162:165], v[194:197], v[20:23]
	v_mfma_f32_16x16x32_bf16 v[56:59], v[170:173], v[194:197], v[56:59]
	v_mfma_f32_16x16x32_bf16 v[12:15], v[162:165], v[214:217], v[12:15]
	v_mfma_f32_16x16x32_bf16 v[44:47], v[170:173], v[214:217], v[44:47]
	v_mfma_f32_16x16x32_bf16 v[32:35], v[166:169], v[182:185], v[32:35]
	v_mfma_f32_16x16x32_bf16 v[72:75], v[174:177], v[182:185], v[72:75]
	v_mfma_f32_16x16x32_bf16 v[28:31], v[166:169], v[190:193], v[28:31]
	v_mfma_f32_16x16x32_bf16 v[96:99], v[174:177], v[190:193], v[96:99]
	v_mfma_f32_16x16x32_bf16 v[20:23], v[166:169], v[198:201], v[20:23]
	v_mfma_f32_16x16x32_bf16 v[56:59], v[174:177], v[198:201], v[56:59]
	v_mfma_f32_16x16x32_bf16 v[12:15], v[166:169], v[218:221], v[12:15]
	v_mfma_f32_16x16x32_bf16 v[44:47], v[174:177], v[218:221], v[44:47]

; #define PG8_STAGE(bufoff, gbase, voff) do { _Pragma("unroll") for (int _i = 0; _i < 2; ++_i) \
;         __builtin_amdgcn_global_load_lds((const unsigned*)((const char*)(gbase) + (voff)[_i]), (LAS unsigned*)(lds + (bufoff) + ldsw + _i * 8192), 16, 0, 0); } while (0)
; #define PG8_LDA(dst, b, h) do { _Pragma("unroll") for (int m = 0; m < 4; ++m) _Pragma("unroll") for (int k = 0; k < 2; ++k) dst[m][k] = *(const LAS bf16x8*)(lds + PG8_SA(b, h) + aoff + m * 2048 + k * 1024); } while (0)
; #define PG8_LDB(dst, b, h) do { _Pragma("unroll") for (int n = 0; n < 2; ++n) _Pragma("unroll") for (int k = 0; k < 2; ++k) dst[n][k] = *(const LAS bf16x8*)(lds + PG8_SB(b, h) + boff + n * 2048 + k * 1024); } while (0)
; #define PG8_MMA(ai, bj, At, Bt) do { __builtin_amdgcn_s_setprio(1); _Pragma("unroll") for (int m = 0; m < 4; ++m) _Pragma("unroll") for (int n = 0; n < 2; ++n) _Pragma("unroll") for (int k = 0; k < 2; ++k) \
;         acc[ai][bj][m][n] = __builtin_amdgcn_mfma_f32_16x16x32_bf16(Bt[n][k], At[m][k], acc[ai][bj][m][n], 0, 0, 0); __builtin_amdgcn_s_setprio(0); } while (0)
; #define PG8_WAIT_V(n) asm volatile("s_waitcnt vmcnt(" #n ")" ::: "memory")
; #define PG8_WAIT_L(n) asm volatile("s_waitcnt lgkmcnt(" #n ")" ::: "memory")
; #define PG8_BAR __builtin_amdgcn_s_barrier()
; #define PG8_SCHED __builtin_amdgcn_sched_barrier(0)
; template <class Epi, bool ALIGN_EPI>
; __device__ __forceinline__ void gemm_phase(LAS unsigned char* lds, const Gemm g, const StaticOrder& S, const Epi& E, const int tid) {
;     ...
;             PG8_WAIT_V(8); PG8_WAIT_L(0); PG8_BAR; PG8_MMA(1, 0, At, B0); PG8_MMA(1, 1, At, B1); PG8_BAR; PG8_SCHED;
;             PG8_LDB(B0, 1, 0); PG8_LDB(B1, 1, 1); PG8_SCHED; PG8_LDA(At, 1, 0); PG8_STAGE(PG8_SA(0, 1), a2 + hstepA, voffA);
	s_barrier
	s_add_i32 s90, 0, 0x18000
	v_add_u32_e32 v0, s90, v160
	s_add_i32 s91, 0, 0x1c000
	ds_read_b128 v[132:135], v0
	ds_read_b128 v[136:139], v0 offset:1024
	ds_read_b128 v[152:155], v0 offset:2048
	ds_read_b128 v[156:159], v0 offset:3072
	v_add_u32_e32 v0, s91, v160
	ds_read_b128 v[162:165], v0
	ds_read_b128 v[166:169], v0 offset:1024
	ds_read_b128 v[170:173], v0 offset:2048
	ds_read_b128 v[174:177], v0 offset:3072
	s_add_u32 s54, s54, 0x4000
	s_addc_u32 s55, s55, 0
	s_mov_b32 m0, s74
	ds_read_b128 v[178:181], v161 offset:32768
	ds_read_b128 v[182:185], v161 offset:33792
	ds_read_b128 v[186:189], v161 offset:34816
	ds_read_b128 v[190:193], v161 offset:35840
	ds_read_b128 v[194:197], v161 offset:36864
	ds_read_b128 v[198:201], v161 offset:37888
	ds_read_b128 v[214:217], v161 offset:38912

; #define PG8_STAGE(bufoff, gbase, voff) do { _Pragma("unroll") for (int _i = 0; _i < 2; ++_i) \
;         __builtin_amdgcn_global_load_lds((const unsigned*)((const char*)(gbase) + (voff)[_i]), (LAS unsigned*)(lds + (bufoff) + ldsw + _i * 8192), 16, 0, 0); } while (0)
; #define PG8_LDA(dst, b, h) do { _Pragma("unroll") for (int m = 0; m < 4; ++m) _Pragma("unroll") for (int k = 0; k < 2; ++k) dst[m][k] = *(const LAS bf16x8*)(lds + PG8_SA(b, h) + aoff + m * 2048 + k * 1024); } while (0)
; #define PG8_LDB(dst, b, h) do { _Pragma("unroll") for (int n = 0; n < 2; ++n) _Pragma("unroll") for (int k = 0; k < 2; ++k) dst[n][k] = *(const LAS bf16x8*)(lds + PG8_SB(b, h) + boff + n * 2048 + k * 1024); } while (0)
; #define PG8_MMA(ai, bj, At, Bt) do { __builtin_amdgcn_s_setprio(1); _Pragma("unroll") for (int m = 0; m < 4; ++m) _Pragma("unroll") for (int n = 0; n < 2; ++n) _Pragma("unroll") for (int k = 0; k < 2; ++k) \
;         acc[ai][bj][m][n] = __builtin_amdgcn_mfma_f32_16x16x32_bf16(Bt[n][k], At[m][k], acc[ai][bj][m][n], 0, 0, 0); __builtin_amdgcn_s_setprio(0); } while (0)
; #define PG8_WAIT_V(n) asm volatile("s_waitcnt vmcnt(" #n ")" ::: "memory")
; #define PG8_WAIT_L(n) asm volatile("s_waitcnt lgkmcnt(" #n ")" ::: "memory")
; #define PG8_BAR __builtin_amdgcn_s_barrier()
; #define PG8_SCHED __builtin_amdgcn_sched_barrier(0)
; template <class Epi, bool ALIGN_EPI>
; __device__ __forceinline__ void gemm_phase(LAS unsigned char* lds, const Gemm g, const StaticOrder& S, const Epi& E, const int tid) {
;     ...
;             PG8_LDB(B0, 1, 0); PG8_LDB(B1, 1, 1); PG8_SCHED; PG8_LDA(At, 1, 0); PG8_STAGE(PG8_SA(0, 1), a2 + hstepA, voffA);
;             PG8_WAIT_V(8); PG8_WAIT_L(0); PG8_BAR; PG8_MMA(0, 0, At, B0); PG8_MMA(0, 1, At, B1); PG8_BAR; PG8_SCHED;
	global_load_lds_dwordx4 v146, s[54:55]
	s_mov_b32 m0, s75
	ds_read_b128 v[218:221], v161 offset:39936
	global_load_lds_dwordx4 v142, s[54:55]
	s_waitcnt vmcnt(8)
	s_waitcnt lgkmcnt(0)
	s_barrier


; #define PG8_MMA(ai, bj, At, Bt) do { __builtin_amdgcn_s_setprio(1); _Pragma("unroll") for (int m = 0; m < 4; ++m) _Pragma("unroll") for (int n = 0; n < 2; ++n) _Pragma("unroll") for (int k = 0; k < 2; ++k) \
;         acc[ai][bj][m][n] = __builtin_amdgcn_mfma_f32_16x16x32_bf16(Bt[n][k], At[m][k], acc[ai][bj][m][n], 0, 0, 0); __builtin_amdgcn_s_setprio(0); } while (0)
; #define PG8_WAIT_V(n) asm volatile("s_waitcnt vmcnt(" #n ")" ::: "memory")
; #define PG8_WAIT_L(n) asm volatile("s_waitcnt lgkmcnt(" #n ")" ::: "memory")
; #define PG8_BAR __builtin_amdgcn_s_barrier()
; #define PG8_SCHED __builtin_amdgcn_sched_barrier(0)
; template <class Epi, bool ALIGN_EPI>
; __device__ __forceinline__ void gemm_phase(LAS unsigned char* lds, const Gemm g, const StaticOrder& S, const Epi& E, const int tid) {
;     ...
;             PG8_WAIT_V(8); PG8_WAIT_L(0); PG8_BAR; PG8_MMA(0, 0, At, B0); PG8_MMA(0, 1, At, B1); PG8_BAR; PG8_SCHED;
	v_mfma_f32_16x16x32_bf16 v[88:91], v[132:135], v[178:181], v[88:91]
	v_mfma_f32_16x16x32_bf16 v[124:127], v[152:155], v[178:181], v[124:127]
	v_mfma_f32_16x16x32_bf16 v[52:55], v[132:135], v[186:189], v[52:55]
	v_mfma_f32_16x16x32_bf16 v[120:123], v[152:155], v[186:189], v[120:123]
	v_mfma_f32_16x16x32_bf16 v[40:43], v[132:135], v[194:197], v[40:43]
	v_mfma_f32_16x16x32_bf16 v[116:119], v[152:155], v[194:197], v[116:119]
	v_mfma_f32_16x16x32_bf16 v[36:39], v[132:135], v[214:217], v[36:39]
	v_mfma_f32_16x16x32_bf16 v[112:115], v[152:155], v[214:217], v[112:115]
	v_mfma_f32_16x16x32_bf16 v[88:91], v[136:139], v[182:185], v[88:91]
	v_mfma_f32_16x16x32_bf16 v[124:127], v[156:159], v[182:185], v[124:127]
	v_mfma_f32_16x16x32_bf16 v[52:55], v[136:139], v[190:193], v[52:55]
	v_mfma_f32_16x16x32_bf16 v[120:123], v[156:159], v[190:193], v[120:123]
	v_mfma_f32_16x16x32_bf16 v[40:43], v[136:139], v[198:201], v[40:43]
	v_mfma_f32_16x16x32_bf16 v[116:119], v[156:159], v[198:201], v[116:119]
	v_mfma_f32_16x16x32_bf16 v[36:39], v[136:139], v[218:221], v[36:39]
	v_mfma_f32_16x16x32_bf16 v[112:115], v[156:159], v[218:221], v[112:115]


; #define PG8_MMA(ai, bj, At, Bt) do { __builtin_amdgcn_s_setprio(1); _Pragma("unroll") for (int m = 0; m < 4; ++m) _Pragma("unroll") for (int n = 0; n < 2; ++n) _Pragma("unroll") for (int k = 0; k < 2; ++k) \
;         acc[ai][bj][m][n] = __builtin_amdgcn_mfma_f32_16x16x32_bf16(Bt[n][k], At[m][k], acc[ai][bj][m][n], 0, 0, 0); __builtin_amdgcn_s_setprio(0); } while (0)
; #define PG8_WAIT_V(n) asm volatile("s_waitcnt vmcnt(" #n ")" ::: "memory")
; #define PG8_WAIT_L(n) asm volatile("s_waitcnt lgkmcnt(" #n ")" ::: "memory")
; #define PG8_BAR __builtin_amdgcn_s_barrier()
; #define PG8_SCHED __builtin_amdgcn_sched_barrier(0)
; template <class Epi, bool ALIGN_EPI>
; __device__ __forceinline__ void gemm_phase(LAS unsigned char* lds, const Gemm g, const StaticOrder& S, const Epi& E, const int tid) {
;     ...
;             PG8_WAIT_V(8); PG8_WAIT_L(0); PG8_BAR; PG8_MMA(0, 0, At, B0); PG8_MMA(0, 1, At, B1); PG8_BAR; PG8_SCHED;
	v_mfma_f32_16x16x32_bf16 v[80:83], v[162:165], v[178:181], v[80:83]
	v_mfma_f32_16x16x32_bf16 v[128:131], v[170:173], v[178:181], v[128:131]
	v_mfma_f32_16x16x32_bf16 v[68:71], v[162:165], v[186:189], v[68:71]
	v_mfma_f32_16x16x32_bf16 v[108:111], v[170:173], v[186:189], v[108:111]
	v_mfma_f32_16x16x32_bf16 v[60:63], v[162:165], v[194:197], v[60:63]
	v_mfma_f32_16x16x32_bf16 v[104:107], v[170:173], v[194:197], v[104:107]
	v_mfma_f32_16x16x32_bf16 v[48:51], v[162:165], v[214:217], v[48:51]
	v_mfma_f32_16x16x32_bf16 v[100:103], v[170:173], v[214:217], v[100:103]
	v_mfma_f32_16x16x32_bf16 v[80:83], v[166:169], v[182:185], v[80:83]
	v_mfma_f32_16x16x32_bf16 v[128:131], v[174:177], v[182:185], v[128:131]
	v_mfma_f32_16x16x32_bf16 v[68:71], v[166:169], v[190:193], v[68:71]
	v_mfma_f32_16x16x32_bf16 v[108:111], v[174:177], v[190:193], v[108:111]
	v_mfma_f32_16x16x32_bf16 v[60:63], v[166:169], v[198:201], v[60:63]
	v_mfma_f32_16x16x32_bf16 v[104:107], v[174:177], v[198:201], v[104:107]
	v_mfma_f32_16x16x32_bf16 v[48:51], v[166:169], v[218:221], v[48:51]
	v_mfma_f32_16x16x32_bf16 v[100:103], v[174:177], v[218:221], v[100:103]

; #define PG8_STAGE(bufoff, gbase, voff) do { _Pragma("unroll") for (int _i = 0; _i < 2; ++_i) \
;         __builtin_amdgcn_global_load_lds((const unsigned*)((const char*)(gbase) + (voff)[_i]), (LAS unsigned*)(lds + (bufoff) + ldsw + _i * 8192), 16, 0, 0); } while (0)
; #define PG8_LDA(dst, b, h) do { _Pragma("unroll") for (int m = 0; m < 4; ++m) _Pragma("unroll") for (int k = 0; k < 2; ++k) dst[m][k] = *(const LAS bf16x8*)(lds + PG8_SA(b, h) + aoff + m * 2048 + k * 1024); } while (0)
; #define PG8_MMA(ai, bj, At, Bt) do { __builtin_amdgcn_s_setprio(1); _Pragma("unroll") for (int m = 0; m < 4; ++m) _Pragma("unroll") for (int n = 0; n < 2; ++n) _Pragma("unroll") for (int k = 0; k < 2; ++k) \
;         acc[ai][bj][m][n] = __builtin_amdgcn_mfma_f32_16x16x32_bf16(Bt[n][k], At[m][k], acc[ai][bj][m][n], 0, 0, 0); __builtin_amdgcn_s_setprio(0); } while (0)
; #define PG8_WAIT_V(n) asm volatile("s_waitcnt vmcnt(" #n ")" ::: "memory")
; #define PG8_WAIT_L(n) asm volatile("s_waitcnt lgkmcnt(" #n ")" ::: "memory")
; #define PG8_BAR __builtin_amdgcn_s_barrier()
; #define PG8_SCHED __builtin_amdgcn_sched_barrier(0)
; template <class Epi, bool ALIGN_EPI>
; __device__ __forceinline__ void gemm_phase(LAS unsigned char* lds, const Gemm g, const StaticOrder& S, const Epi& E, const int tid) {
;     ...
;             PG8_WAIT_V(8); PG8_WAIT_L(0); PG8_BAR; PG8_MMA(0, 0, At, B0); PG8_MMA(0, 1, At, B1); PG8_BAR; PG8_SCHED;
;             PG8_LDA(At, 1, 1); PG8_STAGE(PG8_SB(1, 0), b3, voffB); PG8_STAGE(PG8_SB(1, 1), b3 + hstepB, voffB); PG8_STAGE(PG8_SA(1, 0), a3, voffA);
	s_barrier
	s_add_u32 s54, s52, 0x8000
	s_addc_u32 s55, s53, 0
	s_add_i32 s90, s90, s71
	s_mov_b32 m0, s90
	ds_read_b128 v[178:181], v161 offset:49152
	ds_read_b128 v[182:185], v161 offset:50176
	ds_read_b128 v[186:189], v161 offset:51200
	ds_read_b128 v[190:193], v161 offset:52224


; #define PG8_STAGE(bufoff, gbase, voff) do { _Pragma("unroll") for (int _i = 0; _i < 2; ++_i) \
;         __builtin_amdgcn_global_load_lds((const unsigned*)((const char*)(gbase) + (voff)[_i]), (LAS unsigned*)(lds + (bufoff) + ldsw + _i * 8192), 16, 0, 0); } while (0)
; #define PG8_LDA(dst, b, h) do { _Pragma("unroll") for (int m = 0; m < 4; ++m) _Pragma("unroll") for (int k = 0; k < 2; ++k) dst[m][k] = *(const LAS bf16x8*)(lds + PG8_SA(b, h) + aoff + m * 2048 + k * 1024); } while (0)
; #define PG8_MMA(ai, bj, At, Bt) do { __builtin_amdgcn_s_setprio(1); _Pragma("unroll") for (int m = 0; m < 4; ++m) _Pragma("unroll") for (int n = 0; n < 2; ++n) _Pragma("unroll") for (int k = 0; k < 2; ++k) \
;         acc[ai][bj][m][n] = __builtin_amdgcn_mfma_f32_16x16x32_bf16(Bt[n][k], At[m][k], acc[ai][bj][m][n], 0, 0, 0); __builtin_amdgcn_s_setprio(0); } while (0)
; #define PG8_WAIT_V(n) asm volatile("s_waitcnt vmcnt(" #n ")" ::: "memory")
; #define PG8_WAIT_L(n) asm volatile("s_waitcnt lgkmcnt(" #n ")" ::: "memory")
; #define PG8_BAR __builtin_amdgcn_s_barrier()
; #define PG8_SCHED __builtin_amdgcn_sched_barrier(0)
; template <class Epi, bool ALIGN_EPI>
; __device__ __forceinline__ void gemm_phase(LAS unsigned char* lds, const Gemm g, const StaticOrder& S, const Epi& E, const int tid) {
;     ...
;             PG8_LDA(At, 1, 1); PG8_STAGE(PG8_SB(1, 0), b3, voffB); PG8_STAGE(PG8_SB(1, 1), b3 + hstepB, voffB); PG8_STAGE(PG8_SA(1, 0), a3, voffA);
;             PG8_WAIT_V(8); PG8_WAIT_L(0); PG8_BAR; PG8_MMA(1, 0, At, B0); PG8_MMA(1, 1, At, B1); PG8_BAR; PG8_SCHED;
	global_load_lds_dwordx4 v144, s[54:55]
	s_add_i32 m0, s90, 0x2000
	s_add_u32 s52, s52, 0xc000
	s_addc_u32 s53, s53, 0
	global_load_lds_dwordx4 v140, s[54:55]
	s_add_i32 s54, s91, s71
	s_mov_b32 m0, s54
	ds_read_b128 v[218:221], v161 offset:56320
	global_load_lds_dwordx4 v144, s[52:53]
	s_add_i32 m0, s54, 0x2000
	ds_read_b128 v[214:217], v161 offset:55296
	global_load_lds_dwordx4 v140, s[52:53]
	s_mov_b32 m0, s79
	ds_read_b128 v[198:201], v161 offset:54272
	global_load_lds_dwordx4 v146, s[50:51]
	s_mov_b32 m0, s80
	ds_read_b128 v[194:197], v161 offset:53248
	global_load_lds_dwordx4 v142, s[50:51]
	s_waitcnt vmcnt(8)
	s_waitcnt lgkmcnt(0)
	s_barrier


; #define PG8_MMA(ai, bj, At, Bt) do { __builtin_amdgcn_s_setprio(1); _Pragma("unroll") for (int m = 0; m < 4; ++m) _Pragma("unroll") for (int n = 0; n < 2; ++n) _Pragma("unroll") for (int k = 0; k < 2; ++k) \
;         acc[ai][bj][m][n] = __builtin_amdgcn_mfma_f32_16x16x32_bf16(Bt[n][k], At[m][k], acc[ai][bj][m][n], 0, 0, 0); __builtin_amdgcn_s_setprio(0); } while (0)
; #define PG8_WAIT_V(n) asm volatile("s_waitcnt vmcnt(" #n ")" ::: "memory")
; #define PG8_WAIT_L(n) asm volatile("s_waitcnt lgkmcnt(" #n ")" ::: "memory")
; #define PG8_BAR __builtin_amdgcn_s_barrier()
; #define PG8_SCHED __builtin_amdgcn_sched_barrier(0)
; template <class Epi, bool ALIGN_EPI>
; __device__ __forceinline__ void gemm_phase(LAS unsigned char* lds, const Gemm g, const StaticOrder& S, const Epi& E, const int tid) {
;     ...
;             PG8_WAIT_V(8); PG8_WAIT_L(0); PG8_BAR; PG8_MMA(1, 0, At, B0); PG8_MMA(1, 1, At, B1); PG8_BAR; PG8_SCHED;
	v_mfma_f32_16x16x32_bf16 v[24:27], v[132:135], v[178:181], v[24:27]
	v_mfma_f32_16x16x32_bf16 v[92:95], v[152:155], v[178:181], v[92:95]
	v_mfma_f32_16x16x32_bf16 v[16:19], v[132:135], v[186:189], v[16:19]
	v_mfma_f32_16x16x32_bf16 v[84:87], v[152:155], v[186:189], v[84:87]
	v_mfma_f32_16x16x32_bf16 v[6:9], v[132:135], v[194:197], v[8:11]
	v_mfma_f32_16x16x32_bf16 v[76:79], v[152:155], v[194:197], v[76:79]
	v_mfma_f32_16x16x32_bf16 v[2:5], v[132:135], v[214:217], v[2:5]
	v_mfma_f32_16x16x32_bf16 v[64:67], v[152:155], v[214:217], v[64:67]
	v_mfma_f32_16x16x32_bf16 v[24:27], v[136:139], v[182:185], v[24:27]
	v_mfma_f32_16x16x32_bf16 v[92:95], v[156:159], v[182:185], v[92:95]
	v_mfma_f32_16x16x32_bf16 v[16:19], v[136:139], v[190:193], v[16:19]
	v_mfma_f32_16x16x32_bf16 v[84:87], v[156:159], v[190:193], v[84:87]
	v_mfma_f32_16x16x32_bf16 v[8:11], v[136:139], v[198:201], v[6:9]
	v_mfma_f32_16x16x32_bf16 v[76:79], v[156:159], v[198:201], v[76:79]
	v_mfma_f32_16x16x32_bf16 v[4:7], v[136:139], v[218:221], v[2:5]
	v_mfma_f32_16x16x32_bf16 v[64:67], v[156:159], v[218:221], v[64:67]


; #define PG8_MMA(ai, bj, At, Bt) do { __builtin_amdgcn_s_setprio(1); _Pragma("unroll") for (int m = 0; m < 4; ++m) _Pragma("unroll") for (int n = 0; n < 2; ++n) _Pragma("unroll") for (int k = 0; k < 2; ++k) \
;         acc[ai][bj][m][n] = __builtin_amdgcn_mfma_f32_16x16x32_bf16(Bt[n][k], At[m][k], acc[ai][bj][m][n], 0, 0, 0); __builtin_amdgcn_s_setprio(0); } while (0)
; #define PG8_WAIT_V(n) asm volatile("s_waitcnt vmcnt(" #n ")" ::: "memory")
; #define PG8_WAIT_L(n) asm volatile("s_waitcnt lgkmcnt(" #n ")" ::: "memory")
; #define PG8_BAR __builtin_amdgcn_s_barrier()
; #define PG8_SCHED __builtin_amdgcn_sched_barrier(0)
; template <class Epi, bool ALIGN_EPI>
; __device__ __forceinline__ void gemm_phase(LAS unsigned char* lds, const Gemm g, const StaticOrder& S, const Epi& E, const int tid) {
;     ...
;             PG8_WAIT_V(8); PG8_WAIT_L(0); PG8_BAR; PG8_MMA(1, 0, At, B0); PG8_MMA(1, 1, At, B1); PG8_BAR; PG8_SCHED;
	v_mfma_f32_16x16x32_bf16 v[32:35], v[162:165], v[178:181], v[32:35]
	v_mfma_f32_16x16x32_bf16 v[72:75], v[170:173], v[178:181], v[72:75]
	v_mfma_f32_16x16x32_bf16 v[28:31], v[162:165], v[186:189], v[28:31]
	v_mfma_f32_16x16x32_bf16 v[96:99], v[170:173], v[186:189], v[96:99]
	v_mfma_f32_16x16x32_bf16 v[20:23], v[162:165], v[194:197], v[20:23]
	v_mfma_f32_16x16x32_bf16 v[56:59], v[170:173], v[194:197], v[56:59]
	v_mfma_f32_16x16x32_bf16 v[12:15], v[162:165], v[214:217], v[12:15]
	v_mfma_f32_16x16x32_bf16 v[44:47], v[170:173], v[214:217], v[44:47]
	v_mfma_f32_16x16x32_bf16 v[32:35], v[166:169], v[182:185], v[32:35]
	v_mfma_f32_16x16x32_bf16 v[72:75], v[174:177], v[182:185], v[72:75]
	v_mfma_f32_16x16x32_bf16 v[28:31], v[166:169], v[190:193], v[28:31]
	v_mfma_f32_16x16x32_bf16 v[96:99], v[174:177], v[190:193], v[96:99]
	v_mfma_f32_16x16x32_bf16 v[20:23], v[166:169], v[198:201], v[20:23]
	v_mfma_f32_16x16x32_bf16 v[56:59], v[174:177], v[198:201], v[56:59]
	v_mfma_f32_16x16x32_bf16 v[12:15], v[166:169], v[218:221], v[12:15]
	v_mfma_f32_16x16x32_bf16 v[44:47], v[174:177], v[218:221], v[44:47]

; #define PG8_MMA(ai, bj, At, Bt) do { __builtin_amdgcn_s_setprio(1); _Pragma("unroll") for (int m = 0; m < 4; ++m) _Pragma("unroll") for (int n = 0; n < 2; ++n) _Pragma("unroll") for (int k = 0; k < 2; ++k) \
;         acc[ai][bj][m][n] = __builtin_amdgcn_mfma_f32_16x16x32_bf16(Bt[n][k], At[m][k], acc[ai][bj][m][n], 0, 0, 0); __builtin_amdgcn_s_setprio(0); } while (0)
; #define PG8_WAIT_V(n) asm volatile("s_waitcnt vmcnt(" #n ")" ::: "memory")
; #define PG8_WAIT_L(n) asm volatile("s_waitcnt lgkmcnt(" #n ")" ::: "memory")
; #define PG8_BAR __builtin_amdgcn_s_barrier()
; #define PG8_SCHED __builtin_amdgcn_sched_barrier(0)
; template <class Epi, bool ALIGN_EPI>
; __device__ __forceinline__ void gemm_phase(LAS unsigned char* lds, const Gemm g, const StaticOrder& S, const Epi& E, const int tid) {
;     ...
;         for (int t = 0; t < nt; t += 2) {
;     ...
;             PG8_WAIT_V(8); PG8_WAIT_L(0); PG8_BAR; PG8_MMA(1, 0, At, B0); PG8_MMA(1, 1, At, B1); PG8_BAR; PG8_SCHED;
;         }
;         if constexpr (ALIGN_EPI) { if (wr == 0) PG8_BAR; }
	s_barrier
	s_add_i32 s89, s89, 2
	s_add_u32 s48, s48, 0x10000
	s_addc_u32 s49, s49, 0
	s_add_u32 vcc_hi, vcc_hi, 0x10000
	s_addc_u32 s88, s88, 0
	s_cmp_gt_u32 s89, 29
	s_cbranch_scc0 .LBB0_211
	s_and_b64 vcc, exec, s[22:23]
	s_cbranch_vccz .LBB0_214
	s_barrier

; #define PG8_STAGE(bufoff, gbase, voff) do { _Pragma("unroll") for (int _i = 0; _i < 2; ++_i) \
;         __builtin_amdgcn_global_load_lds((const unsigned*)((const char*)(gbase) + (voff)[_i]), (LAS unsigned*)(lds + (bufoff) + ldsw + _i * 8192), 16, 0, 0); } while (0)
; #define PG8_LDA(dst, b, h) do { _Pragma("unroll") for (int m = 0; m < 4; ++m) _Pragma("unroll") for (int k = 0; k < 2; ++k) dst[m][k] = *(const LAS bf16x8*)(lds + PG8_SA(b, h) + aoff + m * 2048 + k * 1024); } while (0)
; #define PG8_LDB(dst, b, h) do { _Pragma("unroll") for (int n = 0; n < 2; ++n) _Pragma("unroll") for (int k = 0; k < 2; ++k) dst[n][k] = *(const LAS bf16x8*)(lds + PG8_SB(b, h) + boff + n * 2048 + k * 1024); } while (0)
; #define PG8_SCHED __builtin_amdgcn_sched_barrier(0)
; template <class Epi, bool ALIGN_EPI>
; __device__ __forceinline__ void gemm_phase(LAS unsigned char* lds, const Gemm g, const StaticOrder& S, const Epi& E, const int tid) {
;     ...
;             const bool last = (t == nt - 2);
;             const char* a1 = cA + (size_t)(t + 1) * kstepA;
;             const char* a2 = last ? nA : cA + (size_t)(t + 2) * kstepA; const char* b2 = last ? nB : cB + (size_t)(t + 2) * kstepB;
;             const char* a3 = a2 + kstepA; const char* b3 = b2 + kstepB;
;             PG8_LDB(B0, 0, 0); PG8_LDB(B1, 0, 1); PG8_SCHED; PG8_LDA(At, 0, 0); PG8_STAGE(PG8_SA(1, 1), a1 + hstepA, voffA);
.LBB0_294:
	s_add_u32 s22, s10, 0x4000
	s_addc_u32 s23, s11, 0
	s_cmpk_eq_i32 s86, 0x54
	s_cselect_b32 s42, s48, s22
	s_cselect_b32 s43, s49, s23
	s_cselect_b32 s34, s50, s84
	s_cselect_b32 s35, s51, s85
	s_add_u32 s22, s42, 0x8000
	s_addc_u32 s23, s43, 0
	s_add_i32 s87, 0, 0x10000
	v_add_u32_e32 v0, s87, v154
	s_add_i32 s90, 0, 0x14000
	s_waitcnt lgkmcnt(0)
	ds_read_b128 v[132:135], v0
	ds_read_b128 v[148:151], v0 offset:1024
	ds_read_b128 v[156:159], v0 offset:2048
	ds_read_b128 v[160:163], v0 offset:3072
	v_add_u32_e32 v0, s90, v154
	ds_read_b128 v[164:167], v0
	ds_read_b128 v[168:171], v0 offset:1024
	ds_read_b128 v[172:175], v0 offset:2048
	ds_read_b128 v[176:179], v0 offset:3072
	s_add_i32 m0, s57, 0xc000
	ds_read_b128 v[180:183], v155
	ds_read_b128 v[184:187], v155 offset:1024
	ds_read_b128 v[188:191], v155 offset:2048
	ds_read_b128 v[192:195], v155 offset:3072
	ds_read_b128 v[196:199], v155 offset:4096
	ds_read_b128 v[214:217], v155 offset:5120
	ds_read_b128 v[218:221], v155 offset:6144

; #define PG8_STAGE(bufoff, gbase, voff) do { _Pragma("unroll") for (int _i = 0; _i < 2; ++_i) \
;         __builtin_amdgcn_global_load_lds((const unsigned*)((const char*)(gbase) + (voff)[_i]), (LAS unsigned*)(lds + (bufoff) + ldsw + _i * 8192), 16, 0, 0); } while (0)
; #define PG8_LDA(dst, b, h) do { _Pragma("unroll") for (int m = 0; m < 4; ++m) _Pragma("unroll") for (int k = 0; k < 2; ++k) dst[m][k] = *(const LAS bf16x8*)(lds + PG8_SA(b, h) + aoff + m * 2048 + k * 1024); } while (0)
; #define PG8_LDB(dst, b, h) do { _Pragma("unroll") for (int n = 0; n < 2; ++n) _Pragma("unroll") for (int k = 0; k < 2; ++k) dst[n][k] = *(const LAS bf16x8*)(lds + PG8_SB(b, h) + boff + n * 2048 + k * 1024); } while (0)
; #define PG8_MMA(ai, bj, At, Bt) do { __builtin_amdgcn_s_setprio(1); _Pragma("unroll") for (int m = 0; m < 4; ++m) _Pragma("unroll") for (int n = 0; n < 2; ++n) _Pragma("unroll") for (int k = 0; k < 2; ++k) \
;         acc[ai][bj][m][n] = __builtin_amdgcn_mfma_f32_16x16x32_bf16(Bt[n][k], At[m][k], acc[ai][bj][m][n], 0, 0, 0); __builtin_amdgcn_s_setprio(0); } while (0)
; #define PG8_WAIT_V(n) asm volatile("s_waitcnt vmcnt(" #n ")" ::: "memory")
; #define PG8_WAIT_L(n) asm volatile("s_waitcnt lgkmcnt(" #n ")" ::: "memory")
; #define PG8_BAR __builtin_amdgcn_s_barrier()
; #define PG8_SCHED __builtin_amdgcn_sched_barrier(0)
; template <class Epi, bool ALIGN_EPI>
; __device__ __forceinline__ void gemm_phase(LAS unsigned char* lds, const Gemm g, const StaticOrder& S, const Epi& E, const int tid) {
;     ...
;             PG8_LDB(B0, 0, 0); PG8_LDB(B1, 0, 1); PG8_SCHED; PG8_LDA(At, 0, 0); PG8_STAGE(PG8_SA(1, 1), a1 + hstepA, voffA);
;             PG8_WAIT_V(8); PG8_WAIT_L(0); PG8_BAR; PG8_MMA(0, 0, At, B0); PG8_MMA(0, 1, At, B1); PG8_BAR; PG8_SCHED;
	global_load_lds_dwordx4 v144, s[10:11]
	s_add_i32 m0, s57, 0xe000
	ds_read_b128 v[222:225], v155 offset:7168
	global_load_lds_dwordx4 v146, s[10:11]
	s_waitcnt vmcnt(8)
	s_waitcnt lgkmcnt(0)
	s_barrier


; #define PG8_MMA(ai, bj, At, Bt) do { __builtin_amdgcn_s_setprio(1); _Pragma("unroll") for (int m = 0; m < 4; ++m) _Pragma("unroll") for (int n = 0; n < 2; ++n) _Pragma("unroll") for (int k = 0; k < 2; ++k) \
;         acc[ai][bj][m][n] = __builtin_amdgcn_mfma_f32_16x16x32_bf16(Bt[n][k], At[m][k], acc[ai][bj][m][n], 0, 0, 0); __builtin_amdgcn_s_setprio(0); } while (0)
; #define PG8_WAIT_V(n) asm volatile("s_waitcnt vmcnt(" #n ")" ::: "memory")
; #define PG8_WAIT_L(n) asm volatile("s_waitcnt lgkmcnt(" #n ")" ::: "memory")
; #define PG8_BAR __builtin_amdgcn_s_barrier()
; #define PG8_SCHED __builtin_amdgcn_sched_barrier(0)
; template <class Epi, bool ALIGN_EPI>
; __device__ __forceinline__ void gemm_phase(LAS unsigned char* lds, const Gemm g, const StaticOrder& S, const Epi& E, const int tid) {
;     ...
;             PG8_WAIT_V(8); PG8_WAIT_L(0); PG8_BAR; PG8_MMA(0, 0, At, B0); PG8_MMA(0, 1, At, B1); PG8_BAR; PG8_SCHED;
	v_mfma_f32_16x16x32_bf16 v[8:11], v[132:135], v[180:183], v[8:11]
	v_mfma_f32_16x16x32_bf16 v[56:59], v[156:159], v[180:183], v[56:59]
	v_mfma_f32_16x16x32_bf16 v[52:55], v[132:135], v[188:191], v[52:55]
	v_mfma_f32_16x16x32_bf16 v[48:51], v[156:159], v[188:191], v[48:51]
	v_mfma_f32_16x16x32_bf16 v[44:47], v[132:135], v[196:199], v[44:47]
	v_mfma_f32_16x16x32_bf16 v[40:43], v[156:159], v[196:199], v[40:43]
	v_mfma_f32_16x16x32_bf16 v[36:39], v[132:135], v[218:221], v[36:39]
	v_mfma_f32_16x16x32_bf16 v[32:35], v[156:159], v[218:221], v[32:35]
	v_mfma_f32_16x16x32_bf16 v[8:11], v[148:151], v[184:187], v[8:11]
	v_mfma_f32_16x16x32_bf16 v[56:59], v[160:163], v[184:187], v[56:59]
	v_mfma_f32_16x16x32_bf16 v[52:55], v[148:151], v[192:195], v[52:55]
	v_mfma_f32_16x16x32_bf16 v[48:51], v[160:163], v[192:195], v[48:51]
	v_mfma_f32_16x16x32_bf16 v[44:47], v[148:151], v[214:217], v[44:47]
	v_mfma_f32_16x16x32_bf16 v[40:43], v[160:163], v[214:217], v[40:43]
	v_mfma_f32_16x16x32_bf16 v[36:39], v[148:151], v[222:225], v[36:39]
	v_mfma_f32_16x16x32_bf16 v[32:35], v[160:163], v[222:225], v[32:35]


; #define PG8_MMA(ai, bj, At, Bt) do { __builtin_amdgcn_s_setprio(1); _Pragma("unroll") for (int m = 0; m < 4; ++m) _Pragma("unroll") for (int n = 0; n < 2; ++n) _Pragma("unroll") for (int k = 0; k < 2; ++k) \
;         acc[ai][bj][m][n] = __builtin_amdgcn_mfma_f32_16x16x32_bf16(Bt[n][k], At[m][k], acc[ai][bj][m][n], 0, 0, 0); __builtin_amdgcn_s_setprio(0); } while (0)
; #define PG8_WAIT_V(n) asm volatile("s_waitcnt vmcnt(" #n ")" ::: "memory")
; #define PG8_WAIT_L(n) asm volatile("s_waitcnt lgkmcnt(" #n ")" ::: "memory")
; #define PG8_BAR __builtin_amdgcn_s_barrier()
; #define PG8_SCHED __builtin_amdgcn_sched_barrier(0)
; template <class Epi, bool ALIGN_EPI>
; __device__ __forceinline__ void gemm_phase(LAS unsigned char* lds, const Gemm g, const StaticOrder& S, const Epi& E, const int tid) {
;     ...
;             PG8_WAIT_V(8); PG8_WAIT_L(0); PG8_BAR; PG8_MMA(0, 0, At, B0); PG8_MMA(0, 1, At, B1); PG8_BAR; PG8_SCHED;
	v_mfma_f32_16x16x32_bf16 v[2:5], v[164:167], v[180:183], v[4:7]
	v_mfma_f32_16x16x32_bf16 v[28:31], v[172:175], v[180:183], v[28:31]
	v_mfma_f32_16x16x32_bf16 v[96:99], v[164:167], v[188:191], v[96:99]
	v_mfma_f32_16x16x32_bf16 v[92:95], v[172:175], v[188:191], v[92:95]
	v_mfma_f32_16x16x32_bf16 v[88:91], v[164:167], v[196:199], v[88:91]
	v_mfma_f32_16x16x32_bf16 v[84:87], v[172:175], v[196:199], v[84:87]
	v_mfma_f32_16x16x32_bf16 v[80:83], v[164:167], v[218:221], v[80:83]
	v_mfma_f32_16x16x32_bf16 v[76:79], v[172:175], v[218:221], v[76:79]
	v_mfma_f32_16x16x32_bf16 v[2:5], v[168:171], v[184:187], v[2:5]
	v_mfma_f32_16x16x32_bf16 v[28:31], v[176:179], v[184:187], v[28:31]
	v_mfma_f32_16x16x32_bf16 v[96:99], v[168:171], v[192:195], v[96:99]
	v_mfma_f32_16x16x32_bf16 v[92:95], v[176:179], v[192:195], v[92:95]
	v_mfma_f32_16x16x32_bf16 v[88:91], v[168:171], v[214:217], v[88:91]
	v_mfma_f32_16x16x32_bf16 v[84:87], v[176:179], v[214:217], v[84:87]
	v_mfma_f32_16x16x32_bf16 v[80:83], v[168:171], v[222:225], v[80:83]
	v_mfma_f32_16x16x32_bf16 v[76:79], v[176:179], v[222:225], v[76:79]

; #define PG8_STAGE(bufoff, gbase, voff) do { _Pragma("unroll") for (int _i = 0; _i < 2; ++_i) \
;         __builtin_amdgcn_global_load_lds((const unsigned*)((const char*)(gbase) + (voff)[_i]), (LAS unsigned*)(lds + (bufoff) + ldsw + _i * 8192), 16, 0, 0); } while (0)
; #define PG8_LDA(dst, b, h) do { _Pragma("unroll") for (int m = 0; m < 4; ++m) _Pragma("unroll") for (int k = 0; k < 2; ++k) dst[m][k] = *(const LAS bf16x8*)(lds + PG8_SA(b, h) + aoff + m * 2048 + k * 1024); } while (0)
; #define PG8_MMA(ai, bj, At, Bt) do { __builtin_amdgcn_s_setprio(1); _Pragma("unroll") for (int m = 0; m < 4; ++m) _Pragma("unroll") for (int n = 0; n < 2; ++n) _Pragma("unroll") for (int k = 0; k < 2; ++k) \
;         acc[ai][bj][m][n] = __builtin_amdgcn_mfma_f32_16x16x32_bf16(Bt[n][k], At[m][k], acc[ai][bj][m][n], 0, 0, 0); __builtin_amdgcn_s_setprio(0); } while (0)
; #define PG8_WAIT_V(n) asm volatile("s_waitcnt vmcnt(" #n ")" ::: "memory")
; #define PG8_WAIT_L(n) asm volatile("s_waitcnt lgkmcnt(" #n ")" ::: "memory")
; #define PG8_BAR __builtin_amdgcn_s_barrier()
; #define PG8_SCHED __builtin_amdgcn_sched_barrier(0)
; template <class Epi, bool ALIGN_EPI>
; __device__ __forceinline__ void gemm_phase(LAS unsigned char* lds, const Gemm g, const StaticOrder& S, const Epi& E, const int tid) {
;     ...
;             PG8_WAIT_V(8); PG8_WAIT_L(0); PG8_BAR; PG8_MMA(0, 0, At, B0); PG8_MMA(0, 1, At, B1); PG8_BAR; PG8_SCHED;
;             PG8_LDA(At, 0, 1); PG8_STAGE(PG8_SB(0, 0), b2, voffB); PG8_STAGE(PG8_SB(0, 1), b2 + hstepB, voffB); PG8_STAGE(PG8_SA(0, 0), a2, voffA);
	s_barrier
	s_add_i32 s87, s87, s56
	s_mov_b32 m0, s87
	ds_read_b128 v[180:183], v155 offset:16384
	ds_read_b128 v[184:187], v155 offset:17408
	ds_read_b128 v[188:191], v155 offset:18432
	ds_read_b128 v[192:195], v155 offset:19456


; #define PG8_STAGE(bufoff, gbase, voff) do { _Pragma("unroll") for (int _i = 0; _i < 2; ++_i) \
;         __builtin_amdgcn_global_load_lds((const unsigned*)((const char*)(gbase) + (voff)[_i]), (LAS unsigned*)(lds + (bufoff) + ldsw + _i * 8192), 16, 0, 0); } while (0)
; #define PG8_LDA(dst, b, h) do { _Pragma("unroll") for (int m = 0; m < 4; ++m) _Pragma("unroll") for (int k = 0; k < 2; ++k) dst[m][k] = *(const LAS bf16x8*)(lds + PG8_SA(b, h) + aoff + m * 2048 + k * 1024); } while (0)
; #define PG8_MMA(ai, bj, At, Bt) do { __builtin_amdgcn_s_setprio(1); _Pragma("unroll") for (int m = 0; m < 4; ++m) _Pragma("unroll") for (int n = 0; n < 2; ++n) _Pragma("unroll") for (int k = 0; k < 2; ++k) \
;         acc[ai][bj][m][n] = __builtin_amdgcn_mfma_f32_16x16x32_bf16(Bt[n][k], At[m][k], acc[ai][bj][m][n], 0, 0, 0); __builtin_amdgcn_s_setprio(0); } while (0)
; #define PG8_WAIT_V(n) asm volatile("s_waitcnt vmcnt(" #n ")" ::: "memory")
; #define PG8_WAIT_L(n) asm volatile("s_waitcnt lgkmcnt(" #n ")" ::: "memory")
; #define PG8_BAR __builtin_amdgcn_s_barrier()
; #define PG8_SCHED __builtin_amdgcn_sched_barrier(0)
; template <class Epi, bool ALIGN_EPI>
; __device__ __forceinline__ void gemm_phase(LAS unsigned char* lds, const Gemm g, const StaticOrder& S, const Epi& E, const int tid) {
;     ...
;             PG8_LDA(At, 0, 1); PG8_STAGE(PG8_SB(0, 0), b2, voffB); PG8_STAGE(PG8_SB(0, 1), b2 + hstepB, voffB); PG8_STAGE(PG8_SA(0, 0), a2, voffA);
;             PG8_WAIT_V(8); PG8_WAIT_L(0); PG8_BAR; PG8_MMA(1, 0, At, B0); PG8_MMA(1, 1, At, B1); PG8_BAR; PG8_SCHED;
	global_load_lds_dwordx4 v140, s[34:35]
	s_add_i32 m0, s87, 0x2000
	s_add_u32 s88, s34, 0x4000
	s_addc_u32 s89, s35, 0
	s_add_i32 s87, s90, s56
	global_load_lds_dwordx4 v136, s[34:35]
	s_mov_b32 m0, s87
	ds_read_b128 v[222:225], v155 offset:23552
	global_load_lds_dwordx4 v140, s[88:89]
	s_add_i32 m0, s87, 0x2000
	ds_read_b128 v[218:221], v155 offset:22528
	global_load_lds_dwordx4 v136, s[88:89]
	s_mov_b32 m0, s57
	ds_read_b128 v[214:217], v155 offset:21504
	global_load_lds_dwordx4 v142, s[42:43]
	s_mov_b32 m0, s60
	ds_read_b128 v[196:199], v155 offset:20480
	global_load_lds_dwordx4 v138, s[42:43]
	s_waitcnt vmcnt(8)
	s_waitcnt lgkmcnt(0)
	s_barrier


; #define PG8_MMA(ai, bj, At, Bt) do { __builtin_amdgcn_s_setprio(1); _Pragma("unroll") for (int m = 0; m < 4; ++m) _Pragma("unroll") for (int n = 0; n < 2; ++n) _Pragma("unroll") for (int k = 0; k < 2; ++k) \
;         acc[ai][bj][m][n] = __builtin_amdgcn_mfma_f32_16x16x32_bf16(Bt[n][k], At[m][k], acc[ai][bj][m][n], 0, 0, 0); __builtin_amdgcn_s_setprio(0); } while (0)
; #define PG8_WAIT_V(n) asm volatile("s_waitcnt vmcnt(" #n ")" ::: "memory")
; #define PG8_WAIT_L(n) asm volatile("s_waitcnt lgkmcnt(" #n ")" ::: "memory")
; #define PG8_BAR __builtin_amdgcn_s_barrier()
; #define PG8_SCHED __builtin_amdgcn_sched_barrier(0)
; template <class Epi, bool ALIGN_EPI>
; __device__ __forceinline__ void gemm_phase(LAS unsigned char* lds, const Gemm g, const StaticOrder& S, const Epi& E, const int tid) {
;     ...
;             PG8_WAIT_V(8); PG8_WAIT_L(0); PG8_BAR; PG8_MMA(1, 0, At, B0); PG8_MMA(1, 1, At, B1); PG8_BAR; PG8_SCHED;
	v_mfma_f32_16x16x32_bf16 v[24:27], v[132:135], v[180:183], v[24:27]
	v_mfma_f32_16x16x32_bf16 v[20:23], v[156:159], v[180:183], v[20:23]
	v_mfma_f32_16x16x32_bf16 v[64:67], v[132:135], v[188:191], v[64:67]
	v_mfma_f32_16x16x32_bf16 v[72:75], v[156:159], v[188:191], v[72:75]
	v_mfma_f32_16x16x32_bf16 v[16:19], v[132:135], v[196:199], v[16:19]
	v_mfma_f32_16x16x32_bf16 v[12:15], v[156:159], v[196:199], v[12:15]
	v_mfma_f32_16x16x32_bf16 v[60:63], v[132:135], v[218:221], v[60:63]
	v_mfma_f32_16x16x32_bf16 v[68:71], v[156:159], v[218:221], v[68:71]
	v_mfma_f32_16x16x32_bf16 v[24:27], v[148:151], v[184:187], v[24:27]
	v_mfma_f32_16x16x32_bf16 v[20:23], v[160:163], v[184:187], v[20:23]
	v_mfma_f32_16x16x32_bf16 v[64:67], v[148:151], v[192:195], v[64:67]
	v_mfma_f32_16x16x32_bf16 v[72:75], v[160:163], v[192:195], v[72:75]
	v_mfma_f32_16x16x32_bf16 v[16:19], v[148:151], v[214:217], v[16:19]
	v_mfma_f32_16x16x32_bf16 v[12:15], v[160:163], v[214:217], v[12:15]
	v_mfma_f32_16x16x32_bf16 v[60:63], v[148:151], v[222:225], v[60:63]
	v_mfma_f32_16x16x32_bf16 v[68:71], v[160:163], v[222:225], v[68:71]


; #define PG8_MMA(ai, bj, At, Bt) do { __builtin_amdgcn_s_setprio(1); _Pragma("unroll") for (int m = 0; m < 4; ++m) _Pragma("unroll") for (int n = 0; n < 2; ++n) _Pragma("unroll") for (int k = 0; k < 2; ++k) \
;         acc[ai][bj][m][n] = __builtin_amdgcn_mfma_f32_16x16x32_bf16(Bt[n][k], At[m][k], acc[ai][bj][m][n], 0, 0, 0); __builtin_amdgcn_s_setprio(0); } while (0)
; #define PG8_WAIT_V(n) asm volatile("s_waitcnt vmcnt(" #n ")" ::: "memory")
; #define PG8_WAIT_L(n) asm volatile("s_waitcnt lgkmcnt(" #n ")" ::: "memory")
; #define PG8_BAR __builtin_amdgcn_s_barrier()
; #define PG8_SCHED __builtin_amdgcn_sched_barrier(0)
; template <class Epi, bool ALIGN_EPI>
; __device__ __forceinline__ void gemm_phase(LAS unsigned char* lds, const Gemm g, const StaticOrder& S, const Epi& E, const int tid) {
;     ...
;             PG8_WAIT_V(8); PG8_WAIT_L(0); PG8_BAR; PG8_MMA(1, 0, At, B0); PG8_MMA(1, 1, At, B1); PG8_BAR; PG8_SCHED;
	v_mfma_f32_16x16x32_bf16 v[128:131], v[164:167], v[180:183], v[128:131]
	v_mfma_f32_16x16x32_bf16 v[124:127], v[172:175], v[180:183], v[124:127]
	v_mfma_f32_16x16x32_bf16 v[120:123], v[164:167], v[188:191], v[120:123]
	v_mfma_f32_16x16x32_bf16 v[116:119], v[172:175], v[188:191], v[116:119]
	v_mfma_f32_16x16x32_bf16 v[112:115], v[164:167], v[196:199], v[112:115]
	v_mfma_f32_16x16x32_bf16 v[108:111], v[172:175], v[196:199], v[108:111]
	v_mfma_f32_16x16x32_bf16 v[104:107], v[164:167], v[218:221], v[104:107]
	v_mfma_f32_16x16x32_bf16 v[100:103], v[172:175], v[218:221], v[100:103]
	v_mfma_f32_16x16x32_bf16 v[128:131], v[168:171], v[184:187], v[128:131]
	v_mfma_f32_16x16x32_bf16 v[124:127], v[176:179], v[184:187], v[124:127]
	v_mfma_f32_16x16x32_bf16 v[120:123], v[168:171], v[192:195], v[120:123]
	v_mfma_f32_16x16x32_bf16 v[116:119], v[176:179], v[192:195], v[116:119]
	v_mfma_f32_16x16x32_bf16 v[112:115], v[168:171], v[214:217], v[112:115]
	v_mfma_f32_16x16x32_bf16 v[108:111], v[176:179], v[214:217], v[108:111]
	v_mfma_f32_16x16x32_bf16 v[104:107], v[168:171], v[222:225], v[104:107]
	v_mfma_f32_16x16x32_bf16 v[100:103], v[176:179], v[222:225], v[100:103]

; #define PG8_STAGE(bufoff, gbase, voff) do { _Pragma("unroll") for (int _i = 0; _i < 2; ++_i) \
;         __builtin_amdgcn_global_load_lds((const unsigned*)((const char*)(gbase) + (voff)[_i]), (LAS unsigned*)(lds + (bufoff) + ldsw + _i * 8192), 16, 0, 0); } while (0)
; #define PG8_LDA(dst, b, h) do { _Pragma("unroll") for (int m = 0; m < 4; ++m) _Pragma("unroll") for (int k = 0; k < 2; ++k) dst[m][k] = *(const LAS bf16x8*)(lds + PG8_SA(b, h) + aoff + m * 2048 + k * 1024); } while (0)
; #define PG8_LDB(dst, b, h) do { _Pragma("unroll") for (int n = 0; n < 2; ++n) _Pragma("unroll") for (int k = 0; k < 2; ++k) dst[n][k] = *(const LAS bf16x8*)(lds + PG8_SB(b, h) + boff + n * 2048 + k * 1024); } while (0)
; #define PG8_MMA(ai, bj, At, Bt) do { __builtin_amdgcn_s_setprio(1); _Pragma("unroll") for (int m = 0; m < 4; ++m) _Pragma("unroll") for (int n = 0; n < 2; ++n) _Pragma("unroll") for (int k = 0; k < 2; ++k) \
;         acc[ai][bj][m][n] = __builtin_amdgcn_mfma_f32_16x16x32_bf16(Bt[n][k], At[m][k], acc[ai][bj][m][n], 0, 0, 0); __builtin_amdgcn_s_setprio(0); } while (0)
; #define PG8_WAIT_V(n) asm volatile("s_waitcnt vmcnt(" #n ")" ::: "memory")
; #define PG8_WAIT_L(n) asm volatile("s_waitcnt lgkmcnt(" #n ")" ::: "memory")
; #define PG8_BAR __builtin_amdgcn_s_barrier()
; #define PG8_SCHED __builtin_amdgcn_sched_barrier(0)
; template <class Epi, bool ALIGN_EPI>
; __device__ __forceinline__ void gemm_phase(LAS unsigned char* lds, const Gemm g, const StaticOrder& S, const Epi& E, const int tid) {
;     ...
;             PG8_WAIT_V(8); PG8_WAIT_L(0); PG8_BAR; PG8_MMA(1, 0, At, B0); PG8_MMA(1, 1, At, B1); PG8_BAR; PG8_SCHED;
;             PG8_LDB(B0, 1, 0); PG8_LDB(B1, 1, 1); PG8_SCHED; PG8_LDA(At, 1, 0); PG8_STAGE(PG8_SA(0, 1), a2 + hstepA, voffA);
	s_barrier
	s_add_i32 s87, 0, 0x18000
	v_add_u32_e32 v0, s87, v154
	s_add_i32 s88, 0, 0x1c000
	ds_read_b128 v[132:135], v0
	ds_read_b128 v[148:151], v0 offset:1024
	ds_read_b128 v[156:159], v0 offset:2048
	ds_read_b128 v[160:163], v0 offset:3072
	v_add_u32_e32 v0, s88, v154
	ds_read_b128 v[164:167], v0
	ds_read_b128 v[168:171], v0 offset:1024
	ds_read_b128 v[172:175], v0 offset:2048
	ds_read_b128 v[176:179], v0 offset:3072
	s_add_u32 s42, s42, 0x4000
	s_addc_u32 s43, s43, 0
	s_mov_b32 m0, s61
	ds_read_b128 v[180:183], v155 offset:32768
	ds_read_b128 v[184:187], v155 offset:33792
	ds_read_b128 v[188:191], v155 offset:34816
	ds_read_b128 v[192:195], v155 offset:35840
	ds_read_b128 v[196:199], v155 offset:36864
	ds_read_b128 v[214:217], v155 offset:37888
	ds_read_b128 v[218:221], v155 offset:38912

; #define PG8_STAGE(bufoff, gbase, voff) do { _Pragma("unroll") for (int _i = 0; _i < 2; ++_i) \
;         __builtin_amdgcn_global_load_lds((const unsigned*)((const char*)(gbase) + (voff)[_i]), (LAS unsigned*)(lds + (bufoff) + ldsw + _i * 8192), 16, 0, 0); } while (0)
; #define PG8_LDA(dst, b, h) do { _Pragma("unroll") for (int m = 0; m < 4; ++m) _Pragma("unroll") for (int k = 0; k < 2; ++k) dst[m][k] = *(const LAS bf16x8*)(lds + PG8_SA(b, h) + aoff + m * 2048 + k * 1024); } while (0)
; #define PG8_LDB(dst, b, h) do { _Pragma("unroll") for (int n = 0; n < 2; ++n) _Pragma("unroll") for (int k = 0; k < 2; ++k) dst[n][k] = *(const LAS bf16x8*)(lds + PG8_SB(b, h) + boff + n * 2048 + k * 1024); } while (0)
; #define PG8_MMA(ai, bj, At, Bt) do { __builtin_amdgcn_s_setprio(1); _Pragma("unroll") for (int m = 0; m < 4; ++m) _Pragma("unroll") for (int n = 0; n < 2; ++n) _Pragma("unroll") for (int k = 0; k < 2; ++k) \
;         acc[ai][bj][m][n] = __builtin_amdgcn_mfma_f32_16x16x32_bf16(Bt[n][k], At[m][k], acc[ai][bj][m][n], 0, 0, 0); __builtin_amdgcn_s_setprio(0); } while (0)
; #define PG8_WAIT_V(n) asm volatile("s_waitcnt vmcnt(" #n ")" ::: "memory")
; #define PG8_WAIT_L(n) asm volatile("s_waitcnt lgkmcnt(" #n ")" ::: "memory")
; #define PG8_BAR __builtin_amdgcn_s_barrier()
; #define PG8_SCHED __builtin_amdgcn_sched_barrier(0)
; template <class Epi, bool ALIGN_EPI>
; __device__ __forceinline__ void gemm_phase(LAS unsigned char* lds, const Gemm g, const StaticOrder& S, const Epi& E, const int tid) {
;     ...
;             PG8_LDB(B0, 1, 0); PG8_LDB(B1, 1, 1); PG8_SCHED; PG8_LDA(At, 1, 0); PG8_STAGE(PG8_SA(0, 1), a2 + hstepA, voffA);
;             PG8_WAIT_V(8); PG8_WAIT_L(0); PG8_BAR; PG8_MMA(0, 0, At, B0); PG8_MMA(0, 1, At, B1); PG8_BAR; PG8_SCHED;
	global_load_lds_dwordx4 v142, s[42:43]
	s_mov_b32 m0, s71
	ds_read_b128 v[222:225], v155 offset:39936
	global_load_lds_dwordx4 v138, s[42:43]
	s_waitcnt vmcnt(8)
	s_waitcnt lgkmcnt(0)
	s_barrier


; #define PG8_MMA(ai, bj, At, Bt) do { __builtin_amdgcn_s_setprio(1); _Pragma("unroll") for (int m = 0; m < 4; ++m) _Pragma("unroll") for (int n = 0; n < 2; ++n) _Pragma("unroll") for (int k = 0; k < 2; ++k) \
;         acc[ai][bj][m][n] = __builtin_amdgcn_mfma_f32_16x16x32_bf16(Bt[n][k], At[m][k], acc[ai][bj][m][n], 0, 0, 0); __builtin_amdgcn_s_setprio(0); } while (0)
; #define PG8_WAIT_V(n) asm volatile("s_waitcnt vmcnt(" #n ")" ::: "memory")
; #define PG8_WAIT_L(n) asm volatile("s_waitcnt lgkmcnt(" #n ")" ::: "memory")
; #define PG8_BAR __builtin_amdgcn_s_barrier()
; #define PG8_SCHED __builtin_amdgcn_sched_barrier(0)
; template <class Epi, bool ALIGN_EPI>
; __device__ __forceinline__ void gemm_phase(LAS unsigned char* lds, const Gemm g, const StaticOrder& S, const Epi& E, const int tid) {
;     ...
;             PG8_WAIT_V(8); PG8_WAIT_L(0); PG8_BAR; PG8_MMA(0, 0, At, B0); PG8_MMA(0, 1, At, B1); PG8_BAR; PG8_SCHED;
	v_mfma_f32_16x16x32_bf16 v[6:9], v[132:135], v[180:183], v[8:11]
	v_mfma_f32_16x16x32_bf16 v[56:59], v[156:159], v[180:183], v[56:59]
	v_mfma_f32_16x16x32_bf16 v[52:55], v[132:135], v[188:191], v[52:55]
	v_mfma_f32_16x16x32_bf16 v[48:51], v[156:159], v[188:191], v[48:51]
	v_mfma_f32_16x16x32_bf16 v[44:47], v[132:135], v[196:199], v[44:47]
	v_mfma_f32_16x16x32_bf16 v[40:43], v[156:159], v[196:199], v[40:43]
	v_mfma_f32_16x16x32_bf16 v[36:39], v[132:135], v[218:221], v[36:39]
	v_mfma_f32_16x16x32_bf16 v[32:35], v[156:159], v[218:221], v[32:35]
	v_mfma_f32_16x16x32_bf16 v[8:11], v[148:151], v[184:187], v[6:9]
	v_mfma_f32_16x16x32_bf16 v[56:59], v[160:163], v[184:187], v[56:59]
	v_mfma_f32_16x16x32_bf16 v[52:55], v[148:151], v[192:195], v[52:55]
	v_mfma_f32_16x16x32_bf16 v[48:51], v[160:163], v[192:195], v[48:51]
	v_mfma_f32_16x16x32_bf16 v[44:47], v[148:151], v[214:217], v[44:47]
	v_mfma_f32_16x16x32_bf16 v[40:43], v[160:163], v[214:217], v[40:43]
	v_mfma_f32_16x16x32_bf16 v[36:39], v[148:151], v[222:225], v[36:39]
	v_mfma_f32_16x16x32_bf16 v[32:35], v[160:163], v[222:225], v[32:35]


; #define PG8_MMA(ai, bj, At, Bt) do { __builtin_amdgcn_s_setprio(1); _Pragma("unroll") for (int m = 0; m < 4; ++m) _Pragma("unroll") for (int n = 0; n < 2; ++n) _Pragma("unroll") for (int k = 0; k < 2; ++k) \
;         acc[ai][bj][m][n] = __builtin_amdgcn_mfma_f32_16x16x32_bf16(Bt[n][k], At[m][k], acc[ai][bj][m][n], 0, 0, 0); __builtin_amdgcn_s_setprio(0); } while (0)
; #define PG8_WAIT_V(n) asm volatile("s_waitcnt vmcnt(" #n ")" ::: "memory")
; #define PG8_WAIT_L(n) asm volatile("s_waitcnt lgkmcnt(" #n ")" ::: "memory")
; #define PG8_BAR __builtin_amdgcn_s_barrier()
; #define PG8_SCHED __builtin_amdgcn_sched_barrier(0)
; template <class Epi, bool ALIGN_EPI>
; __device__ __forceinline__ void gemm_phase(LAS unsigned char* lds, const Gemm g, const StaticOrder& S, const Epi& E, const int tid) {
;     ...
;             PG8_WAIT_V(8); PG8_WAIT_L(0); PG8_BAR; PG8_MMA(0, 0, At, B0); PG8_MMA(0, 1, At, B1); PG8_BAR; PG8_SCHED;
	v_mfma_f32_16x16x32_bf16 v[2:5], v[164:167], v[180:183], v[2:5]
	v_mfma_f32_16x16x32_bf16 v[28:31], v[172:175], v[180:183], v[28:31]
	v_mfma_f32_16x16x32_bf16 v[96:99], v[164:167], v[188:191], v[96:99]
	v_mfma_f32_16x16x32_bf16 v[92:95], v[172:175], v[188:191], v[92:95]
	v_mfma_f32_16x16x32_bf16 v[88:91], v[164:167], v[196:199], v[88:91]
	v_mfma_f32_16x16x32_bf16 v[84:87], v[172:175], v[196:199], v[84:87]
	v_mfma_f32_16x16x32_bf16 v[80:83], v[164:167], v[218:221], v[80:83]
	v_mfma_f32_16x16x32_bf16 v[76:79], v[172:175], v[218:221], v[76:79]
	v_mfma_f32_16x16x32_bf16 v[4:7], v[168:171], v[184:187], v[2:5]
	v_mfma_f32_16x16x32_bf16 v[28:31], v[176:179], v[184:187], v[28:31]
	v_mfma_f32_16x16x32_bf16 v[96:99], v[168:171], v[192:195], v[96:99]
	v_mfma_f32_16x16x32_bf16 v[92:95], v[176:179], v[192:195], v[92:95]
	v_mfma_f32_16x16x32_bf16 v[88:91], v[168:171], v[214:217], v[88:91]
	v_mfma_f32_16x16x32_bf16 v[84:87], v[176:179], v[214:217], v[84:87]
	v_mfma_f32_16x16x32_bf16 v[80:83], v[168:171], v[222:225], v[80:83]
	v_mfma_f32_16x16x32_bf16 v[76:79], v[176:179], v[222:225], v[76:79]

; #define PG8_STAGE(bufoff, gbase, voff) do { _Pragma("unroll") for (int _i = 0; _i < 2; ++_i) \
;         __builtin_amdgcn_global_load_lds((const unsigned*)((const char*)(gbase) + (voff)[_i]), (LAS unsigned*)(lds + (bufoff) + ldsw + _i * 8192), 16, 0, 0); } while (0)
; #define PG8_LDA(dst, b, h) do { _Pragma("unroll") for (int m = 0; m < 4; ++m) _Pragma("unroll") for (int k = 0; k < 2; ++k) dst[m][k] = *(const LAS bf16x8*)(lds + PG8_SA(b, h) + aoff + m * 2048 + k * 1024); } while (0)
; #define PG8_MMA(ai, bj, At, Bt) do { __builtin_amdgcn_s_setprio(1); _Pragma("unroll") for (int m = 0; m < 4; ++m) _Pragma("unroll") for (int n = 0; n < 2; ++n) _Pragma("unroll") for (int k = 0; k < 2; ++k) \
;         acc[ai][bj][m][n] = __builtin_amdgcn_mfma_f32_16x16x32_bf16(Bt[n][k], At[m][k], acc[ai][bj][m][n], 0, 0, 0); __builtin_amdgcn_s_setprio(0); } while (0)
; #define PG8_WAIT_V(n) asm volatile("s_waitcnt vmcnt(" #n ")" ::: "memory")
; #define PG8_WAIT_L(n) asm volatile("s_waitcnt lgkmcnt(" #n ")" ::: "memory")
; #define PG8_BAR __builtin_amdgcn_s_barrier()
; #define PG8_SCHED __builtin_amdgcn_sched_barrier(0)
; template <class Epi, bool ALIGN_EPI>
; __device__ __forceinline__ void gemm_phase(LAS unsigned char* lds, const Gemm g, const StaticOrder& S, const Epi& E, const int tid) {
;     ...
;             PG8_WAIT_V(8); PG8_WAIT_L(0); PG8_BAR; PG8_MMA(0, 0, At, B0); PG8_MMA(0, 1, At, B1); PG8_BAR; PG8_SCHED;
;             PG8_LDA(At, 1, 1); PG8_STAGE(PG8_SB(1, 0), b3, voffB); PG8_STAGE(PG8_SB(1, 1), b3 + hstepB, voffB); PG8_STAGE(PG8_SA(1, 0), a3, voffA);
	s_barrier
	s_add_u32 s42, s34, 0x8000
	s_addc_u32 s43, s35, 0
	s_add_i32 s87, s87, s56
	s_mov_b32 m0, s87
	ds_read_b128 v[180:183], v155 offset:49152
	ds_read_b128 v[184:187], v155 offset:50176
	ds_read_b128 v[188:191], v155 offset:51200
	ds_read_b128 v[192:195], v155 offset:52224


; #define PG8_STAGE(bufoff, gbase, voff) do { _Pragma("unroll") for (int _i = 0; _i < 2; ++_i) \
;         __builtin_amdgcn_global_load_lds((const unsigned*)((const char*)(gbase) + (voff)[_i]), (LAS unsigned*)(lds + (bufoff) + ldsw + _i * 8192), 16, 0, 0); } while (0)
; #define PG8_LDA(dst, b, h) do { _Pragma("unroll") for (int m = 0; m < 4; ++m) _Pragma("unroll") for (int k = 0; k < 2; ++k) dst[m][k] = *(const LAS bf16x8*)(lds + PG8_SA(b, h) + aoff + m * 2048 + k * 1024); } while (0)
; #define PG8_MMA(ai, bj, At, Bt) do { __builtin_amdgcn_s_setprio(1); _Pragma("unroll") for (int m = 0; m < 4; ++m) _Pragma("unroll") for (int n = 0; n < 2; ++n) _Pragma("unroll") for (int k = 0; k < 2; ++k) \
;         acc[ai][bj][m][n] = __builtin_amdgcn_mfma_f32_16x16x32_bf16(Bt[n][k], At[m][k], acc[ai][bj][m][n], 0, 0, 0); __builtin_amdgcn_s_setprio(0); } while (0)
; #define PG8_WAIT_V(n) asm volatile("s_waitcnt vmcnt(" #n ")" ::: "memory")
; #define PG8_WAIT_L(n) asm volatile("s_waitcnt lgkmcnt(" #n ")" ::: "memory")
; #define PG8_BAR __builtin_amdgcn_s_barrier()
; #define PG8_SCHED __builtin_amdgcn_sched_barrier(0)
; template <class Epi, bool ALIGN_EPI>
; __device__ __forceinline__ void gemm_phase(LAS unsigned char* lds, const Gemm g, const StaticOrder& S, const Epi& E, const int tid) {
;     ...
;             PG8_LDA(At, 1, 1); PG8_STAGE(PG8_SB(1, 0), b3, voffB); PG8_STAGE(PG8_SB(1, 1), b3 + hstepB, voffB); PG8_STAGE(PG8_SA(1, 0), a3, voffA);
;             PG8_WAIT_V(8); PG8_WAIT_L(0); PG8_BAR; PG8_MMA(1, 0, At, B0); PG8_MMA(1, 1, At, B1); PG8_BAR; PG8_SCHED;
	global_load_lds_dwordx4 v140, s[42:43]
	s_add_i32 m0, s87, 0x2000
	s_add_u32 s34, s34, 0xc000
	s_addc_u32 s35, s35, 0
	global_load_lds_dwordx4 v136, s[42:43]
	s_add_i32 s42, s88, s56
	s_mov_b32 m0, s42
	ds_read_b128 v[222:225], v155 offset:56320
	global_load_lds_dwordx4 v140, s[34:35]
	s_add_i32 m0, s42, 0x2000
	ds_read_b128 v[218:221], v155 offset:55296
	global_load_lds_dwordx4 v136, s[34:35]
	s_mov_b32 m0, s76
	ds_read_b128 v[214:217], v155 offset:54272
	global_load_lds_dwordx4 v142, s[22:23]
	s_mov_b32 m0, s77
	ds_read_b128 v[196:199], v155 offset:53248
	global_load_lds_dwordx4 v138, s[22:23]
	s_waitcnt vmcnt(8)
	s_waitcnt lgkmcnt(0)
	s_barrier


; #define PG8_MMA(ai, bj, At, Bt) do { __builtin_amdgcn_s_setprio(1); _Pragma("unroll") for (int m = 0; m < 4; ++m) _Pragma("unroll") for (int n = 0; n < 2; ++n) _Pragma("unroll") for (int k = 0; k < 2; ++k) \
;         acc[ai][bj][m][n] = __builtin_amdgcn_mfma_f32_16x16x32_bf16(Bt[n][k], At[m][k], acc[ai][bj][m][n], 0, 0, 0); __builtin_amdgcn_s_setprio(0); } while (0)
; #define PG8_WAIT_V(n) asm volatile("s_waitcnt vmcnt(" #n ")" ::: "memory")
; #define PG8_WAIT_L(n) asm volatile("s_waitcnt lgkmcnt(" #n ")" ::: "memory")
; #define PG8_BAR __builtin_amdgcn_s_barrier()
; #define PG8_SCHED __builtin_amdgcn_sched_barrier(0)
; template <class Epi, bool ALIGN_EPI>
; __device__ __forceinline__ void gemm_phase(LAS unsigned char* lds, const Gemm g, const StaticOrder& S, const Epi& E, const int tid) {
;     ...
;             PG8_WAIT_V(8); PG8_WAIT_L(0); PG8_BAR; PG8_MMA(1, 0, At, B0); PG8_MMA(1, 1, At, B1); PG8_BAR; PG8_SCHED;
	v_mfma_f32_16x16x32_bf16 v[24:27], v[132:135], v[180:183], v[24:27]
	v_mfma_f32_16x16x32_bf16 v[20:23], v[156:159], v[180:183], v[20:23]
	v_mfma_f32_16x16x32_bf16 v[64:67], v[132:135], v[188:191], v[64:67]
	v_mfma_f32_16x16x32_bf16 v[72:75], v[156:159], v[188:191], v[72:75]
	v_mfma_f32_16x16x32_bf16 v[16:19], v[132:135], v[196:199], v[16:19]
	v_mfma_f32_16x16x32_bf16 v[12:15], v[156:159], v[196:199], v[12:15]
	v_mfma_f32_16x16x32_bf16 v[60:63], v[132:135], v[218:221], v[60:63]
	v_mfma_f32_16x16x32_bf16 v[68:71], v[156:159], v[218:221], v[68:71]
	v_mfma_f32_16x16x32_bf16 v[24:27], v[148:151], v[184:187], v[24:27]
	v_mfma_f32_16x16x32_bf16 v[20:23], v[160:163], v[184:187], v[20:23]
	v_mfma_f32_16x16x32_bf16 v[64:67], v[148:151], v[192:195], v[64:67]
	v_mfma_f32_16x16x32_bf16 v[72:75], v[160:163], v[192:195], v[72:75]
	v_mfma_f32_16x16x32_bf16 v[16:19], v[148:151], v[214:217], v[16:19]
	v_mfma_f32_16x16x32_bf16 v[12:15], v[160:163], v[214:217], v[12:15]
	v_mfma_f32_16x16x32_bf16 v[60:63], v[148:151], v[222:225], v[60:63]
	v_mfma_f32_16x16x32_bf16 v[68:71], v[160:163], v[222:225], v[68:71]


; #define PG8_MMA(ai, bj, At, Bt) do { __builtin_amdgcn_s_setprio(1); _Pragma("unroll") for (int m = 0; m < 4; ++m) _Pragma("unroll") for (int n = 0; n < 2; ++n) _Pragma("unroll") for (int k = 0; k < 2; ++k) \
;         acc[ai][bj][m][n] = __builtin_amdgcn_mfma_f32_16x16x32_bf16(Bt[n][k], At[m][k], acc[ai][bj][m][n], 0, 0, 0); __builtin_amdgcn_s_setprio(0); } while (0)
; #define PG8_WAIT_V(n) asm volatile("s_waitcnt vmcnt(" #n ")" ::: "memory")
; #define PG8_WAIT_L(n) asm volatile("s_waitcnt lgkmcnt(" #n ")" ::: "memory")
; #define PG8_BAR __builtin_amdgcn_s_barrier()
; #define PG8_SCHED __builtin_amdgcn_sched_barrier(0)
; template <class Epi, bool ALIGN_EPI>
; __device__ __forceinline__ void gemm_phase(LAS unsigned char* lds, const Gemm g, const StaticOrder& S, const Epi& E, const int tid) {
;     ...
;             PG8_WAIT_V(8); PG8_WAIT_L(0); PG8_BAR; PG8_MMA(1, 0, At, B0); PG8_MMA(1, 1, At, B1); PG8_BAR; PG8_SCHED;
	v_mfma_f32_16x16x32_bf16 v[128:131], v[164:167], v[180:183], v[128:131]
	v_mfma_f32_16x16x32_bf16 v[124:127], v[172:175], v[180:183], v[124:127]
	v_mfma_f32_16x16x32_bf16 v[120:123], v[164:167], v[188:191], v[120:123]
	v_mfma_f32_16x16x32_bf16 v[116:119], v[172:175], v[188:191], v[116:119]
	v_mfma_f32_16x16x32_bf16 v[112:115], v[164:167], v[196:199], v[112:115]
	v_mfma_f32_16x16x32_bf16 v[108:111], v[172:175], v[196:199], v[108:111]
	v_mfma_f32_16x16x32_bf16 v[104:107], v[164:167], v[218:221], v[104:107]
	v_mfma_f32_16x16x32_bf16 v[100:103], v[172:175], v[218:221], v[100:103]
	v_mfma_f32_16x16x32_bf16 v[128:131], v[168:171], v[184:187], v[128:131]
	v_mfma_f32_16x16x32_bf16 v[124:127], v[176:179], v[184:187], v[124:127]
	v_mfma_f32_16x16x32_bf16 v[120:123], v[168:171], v[192:195], v[120:123]
	v_mfma_f32_16x16x32_bf16 v[116:119], v[176:179], v[192:195], v[116:119]
	v_mfma_f32_16x16x32_bf16 v[112:115], v[168:171], v[214:217], v[112:115]
	v_mfma_f32_16x16x32_bf16 v[108:111], v[176:179], v[214:217], v[108:111]
	v_mfma_f32_16x16x32_bf16 v[104:107], v[168:171], v[222:225], v[104:107]
	v_mfma_f32_16x16x32_bf16 v[100:103], v[176:179], v[222:225], v[100:103]

; #define PG8_MMA(ai, bj, At, Bt) do { __builtin_amdgcn_s_setprio(1); _Pragma("unroll") for (int m = 0; m < 4; ++m) _Pragma("unroll") for (int n = 0; n < 2; ++n) _Pragma("unroll") for (int k = 0; k < 2; ++k) \
;         acc[ai][bj][m][n] = __builtin_amdgcn_mfma_f32_16x16x32_bf16(Bt[n][k], At[m][k], acc[ai][bj][m][n], 0, 0, 0); __builtin_amdgcn_s_setprio(0); } while (0)
; #define PG8_WAIT_V(n) asm volatile("s_waitcnt vmcnt(" #n ")" ::: "memory")
; #define PG8_WAIT_L(n) asm volatile("s_waitcnt lgkmcnt(" #n ")" ::: "memory")
; #define PG8_BAR __builtin_amdgcn_s_barrier()
; #define PG8_SCHED __builtin_amdgcn_sched_barrier(0)
; template <class Epi, bool ALIGN_EPI>
; __device__ __forceinline__ void gemm_phase(LAS unsigned char* lds, const Gemm g, const StaticOrder& S, const Epi& E, const int tid) {
;     ...
;         for (int t = 0; t < nt; t += 2) {
;     ...
;             PG8_WAIT_V(8); PG8_WAIT_L(0); PG8_BAR; PG8_MMA(1, 0, At, B0); PG8_MMA(1, 1, At, B1); PG8_BAR; PG8_SCHED;
;         }
;         if constexpr (ALIGN_EPI) { if (wr == 0) PG8_BAR; }
	s_barrier
	s_add_i32 s86, s86, 2
	s_add_u32 s84, s84, 0x10000
	s_addc_u32 s85, s85, 0
	s_add_u32 s10, s10, 0x10000
	s_addc_u32 s11, s11, 0
	s_cmpk_gt_u32 s86, 0x55
	s_cbranch_scc0 .LBB0_294
	s_and_b64 vcc, exec, s[46:47]
	s_cbranch_vccz .LBB0_297
	s_barrier

; #define PG8_STAGE(bufoff, gbase, voff) do { _Pragma("unroll") for (int _i = 0; _i < 2; ++_i) \
;         __builtin_amdgcn_global_load_lds((const unsigned*)((const char*)(gbase) + (voff)[_i]), (LAS unsigned*)(lds + (bufoff) + ldsw + _i * 8192), 16, 0, 0); } while (0)
; #define PG8_LDA(dst, b, h) do { _Pragma("unroll") for (int m = 0; m < 4; ++m) _Pragma("unroll") for (int k = 0; k < 2; ++k) dst[m][k] = *(const LAS bf16x8*)(lds + PG8_SA(b, h) + aoff + m * 2048 + k * 1024); } while (0)
; #define PG8_LDB(dst, b, h) do { _Pragma("unroll") for (int n = 0; n < 2; ++n) _Pragma("unroll") for (int k = 0; k < 2; ++k) dst[n][k] = *(const LAS bf16x8*)(lds + PG8_SB(b, h) + boff + n * 2048 + k * 1024); } while (0)
; #define PG8_SCHED __builtin_amdgcn_sched_barrier(0)
; template <class Epi, bool ALIGN_EPI>
; __device__ __forceinline__ void gemm_phase(LAS unsigned char* lds, const Gemm g, const StaticOrder& S, const Epi& E, const int tid) {
;     ...
;             const bool last = (t == nt - 2);
;             const char* a1 = cA + (size_t)(t + 1) * kstepA;
;             const char* a2 = last ? nA : cA + (size_t)(t + 2) * kstepA; const char* b2 = last ? nB : cB + (size_t)(t + 2) * kstepB;
;             const char* a3 = a2 + kstepA; const char* b3 = b2 + kstepB;
;             PG8_LDB(B0, 0, 0); PG8_LDB(B1, 0, 1); PG8_SCHED; PG8_LDA(At, 0, 0); PG8_STAGE(PG8_SA(1, 1), a1 + hstepA, voffA);
.LBB0_385:
	s_add_u32 s50, s48, 0x4000
	s_addc_u32 s51, s49, 0
	s_cmp_eq_u32 s88, 28
	s_cselect_b32 s54, s84, s50
	s_cselect_b32 s55, s43, s51
	s_cselect_b32 s52, s85, s86
	s_cselect_b32 s53, s41, s87
	s_add_u32 s50, s54, 0x8000
	s_addc_u32 s51, s55, 0
	s_add_i32 s89, 0, 0x10000
	v_add_u32_e32 v0, s89, v167
	s_add_i32 s92, 0, 0x14000
	ds_read_b128 v[132:135], v0
	ds_read_b128 v[136:139], v0 offset:1024
	ds_read_b128 v[152:155], v0 offset:2048
	ds_read_b128 v[156:159], v0 offset:3072
	v_add_u32_e32 v0, s92, v167
	ds_read_b128 v[160:163], v0
	ds_read_b128 v[172:175], v0 offset:1024
	ds_read_b128 v[176:179], v0 offset:2048
	ds_read_b128 v[180:183], v0 offset:3072
	s_add_i32 m0, s71, 0xc000
	ds_read_b128 v[184:187], v171
	ds_read_b128 v[188:191], v171 offset:1024
	ds_read_b128 v[192:195], v171 offset:2048
	ds_read_b128 v[196:199], v171 offset:3072
	ds_read_b128 v[214:217], v171 offset:4096
	ds_read_b128 v[218:221], v171 offset:5120
	ds_read_b128 v[222:225], v171 offset:6144

; #define PG8_STAGE(bufoff, gbase, voff) do { _Pragma("unroll") for (int _i = 0; _i < 2; ++_i) \
;         __builtin_amdgcn_global_load_lds((const unsigned*)((const char*)(gbase) + (voff)[_i]), (LAS unsigned*)(lds + (bufoff) + ldsw + _i * 8192), 16, 0, 0); } while (0)
; #define PG8_LDA(dst, b, h) do { _Pragma("unroll") for (int m = 0; m < 4; ++m) _Pragma("unroll") for (int k = 0; k < 2; ++k) dst[m][k] = *(const LAS bf16x8*)(lds + PG8_SA(b, h) + aoff + m * 2048 + k * 1024); } while (0)
; #define PG8_LDB(dst, b, h) do { _Pragma("unroll") for (int n = 0; n < 2; ++n) _Pragma("unroll") for (int k = 0; k < 2; ++k) dst[n][k] = *(const LAS bf16x8*)(lds + PG8_SB(b, h) + boff + n * 2048 + k * 1024); } while (0)
; #define PG8_MMA(ai, bj, At, Bt) do { __builtin_amdgcn_s_setprio(1); _Pragma("unroll") for (int m = 0; m < 4; ++m) _Pragma("unroll") for (int n = 0; n < 2; ++n) _Pragma("unroll") for (int k = 0; k < 2; ++k) \
;         acc[ai][bj][m][n] = __builtin_amdgcn_mfma_f32_16x16x32_bf16(Bt[n][k], At[m][k], acc[ai][bj][m][n], 0, 0, 0); __builtin_amdgcn_s_setprio(0); } while (0)
; #define PG8_WAIT_V(n) asm volatile("s_waitcnt vmcnt(" #n ")" ::: "memory")
; #define PG8_WAIT_L(n) asm volatile("s_waitcnt lgkmcnt(" #n ")" ::: "memory")
; #define PG8_BAR __builtin_amdgcn_s_barrier()
; #define PG8_SCHED __builtin_amdgcn_sched_barrier(0)
; template <class Epi, bool ALIGN_EPI>
; __device__ __forceinline__ void gemm_phase(LAS unsigned char* lds, const Gemm g, const StaticOrder& S, const Epi& E, const int tid) {
;     ...
;             PG8_LDB(B0, 0, 0); PG8_LDB(B1, 0, 1); PG8_SCHED; PG8_LDA(At, 0, 0); PG8_STAGE(PG8_SA(1, 1), a1 + hstepA, voffA);
;             PG8_WAIT_V(8); PG8_WAIT_L(0); PG8_BAR; PG8_MMA(0, 0, At, B0); PG8_MMA(0, 1, At, B1); PG8_BAR; PG8_SCHED;
	global_load_lds_dwordx4 v148, s[48:49]
	s_add_i32 m0, s71, 0xe000
	ds_read_b128 v[226:229], v171 offset:7168
	global_load_lds_dwordx4 v150, s[48:49]
	s_waitcnt vmcnt(8)
	s_waitcnt lgkmcnt(0)
	s_barrier


; #define PG8_MMA(ai, bj, At, Bt) do { __builtin_amdgcn_s_setprio(1); _Pragma("unroll") for (int m = 0; m < 4; ++m) _Pragma("unroll") for (int n = 0; n < 2; ++n) _Pragma("unroll") for (int k = 0; k < 2; ++k) \
;         acc[ai][bj][m][n] = __builtin_amdgcn_mfma_f32_16x16x32_bf16(Bt[n][k], At[m][k], acc[ai][bj][m][n], 0, 0, 0); __builtin_amdgcn_s_setprio(0); } while (0)
; #define PG8_WAIT_V(n) asm volatile("s_waitcnt vmcnt(" #n ")" ::: "memory")
; #define PG8_WAIT_L(n) asm volatile("s_waitcnt lgkmcnt(" #n ")" ::: "memory")
; #define PG8_BAR __builtin_amdgcn_s_barrier()
; #define PG8_SCHED __builtin_amdgcn_sched_barrier(0)
; template <class Epi, bool ALIGN_EPI>
; __device__ __forceinline__ void gemm_phase(LAS unsigned char* lds, const Gemm g, const StaticOrder& S, const Epi& E, const int tid) {
;     ...
;             PG8_WAIT_V(8); PG8_WAIT_L(0); PG8_BAR; PG8_MMA(0, 0, At, B0); PG8_MMA(0, 1, At, B1); PG8_BAR; PG8_SCHED;
	v_mfma_f32_16x16x32_bf16 v[128:131], v[132:135], v[184:187], v[128:131]
	v_mfma_f32_16x16x32_bf16 v[116:119], v[152:155], v[184:187], v[116:119]
	v_mfma_f32_16x16x32_bf16 v[124:127], v[132:135], v[192:195], v[124:127]
	v_mfma_f32_16x16x32_bf16 v[108:111], v[152:155], v[192:195], v[108:111]
	v_mfma_f32_16x16x32_bf16 v[120:123], v[132:135], v[214:217], v[120:123]
	v_mfma_f32_16x16x32_bf16 v[100:103], v[152:155], v[214:217], v[100:103]
	v_mfma_f32_16x16x32_bf16 v[112:115], v[132:135], v[222:225], v[112:115]
	v_mfma_f32_16x16x32_bf16 v[92:95], v[152:155], v[222:225], v[92:95]
	v_mfma_f32_16x16x32_bf16 v[128:131], v[136:139], v[188:191], v[128:131]
	v_mfma_f32_16x16x32_bf16 v[116:119], v[156:159], v[188:191], v[116:119]
	v_mfma_f32_16x16x32_bf16 v[124:127], v[136:139], v[196:199], v[124:127]
	v_mfma_f32_16x16x32_bf16 v[108:111], v[156:159], v[196:199], v[108:111]
	v_mfma_f32_16x16x32_bf16 v[120:123], v[136:139], v[218:221], v[120:123]
	v_mfma_f32_16x16x32_bf16 v[100:103], v[156:159], v[218:221], v[100:103]
	v_mfma_f32_16x16x32_bf16 v[112:115], v[136:139], v[226:229], v[112:115]
	v_mfma_f32_16x16x32_bf16 v[92:95], v[156:159], v[226:229], v[92:95]


; #define PG8_MMA(ai, bj, At, Bt) do { __builtin_amdgcn_s_setprio(1); _Pragma("unroll") for (int m = 0; m < 4; ++m) _Pragma("unroll") for (int n = 0; n < 2; ++n) _Pragma("unroll") for (int k = 0; k < 2; ++k) \
;         acc[ai][bj][m][n] = __builtin_amdgcn_mfma_f32_16x16x32_bf16(Bt[n][k], At[m][k], acc[ai][bj][m][n], 0, 0, 0); __builtin_amdgcn_s_setprio(0); } while (0)
; #define PG8_WAIT_V(n) asm volatile("s_waitcnt vmcnt(" #n ")" ::: "memory")
; #define PG8_WAIT_L(n) asm volatile("s_waitcnt lgkmcnt(" #n ")" ::: "memory")
; #define PG8_BAR __builtin_amdgcn_s_barrier()
; #define PG8_SCHED __builtin_amdgcn_sched_barrier(0)
; template <class Epi, bool ALIGN_EPI>
; __device__ __forceinline__ void gemm_phase(LAS unsigned char* lds, const Gemm g, const StaticOrder& S, const Epi& E, const int tid) {
;     ...
;             PG8_WAIT_V(8); PG8_WAIT_L(0); PG8_BAR; PG8_MMA(0, 0, At, B0); PG8_MMA(0, 1, At, B1); PG8_BAR; PG8_SCHED;
	v_mfma_f32_16x16x32_bf16 v[104:107], v[160:163], v[184:187], v[104:107]
	v_mfma_f32_16x16x32_bf16 v[80:83], v[176:179], v[184:187], v[80:83]
	v_mfma_f32_16x16x32_bf16 v[96:99], v[160:163], v[192:195], v[96:99]
	v_mfma_f32_16x16x32_bf16 v[68:71], v[176:179], v[192:195], v[68:71]
	v_mfma_f32_16x16x32_bf16 v[88:91], v[160:163], v[214:217], v[88:91]
	v_mfma_f32_16x16x32_bf16 v[60:63], v[176:179], v[214:217], v[60:63]
	v_mfma_f32_16x16x32_bf16 v[76:79], v[160:163], v[222:225], v[76:79]
	v_mfma_f32_16x16x32_bf16 v[48:51], v[176:179], v[222:225], v[48:51]
	v_mfma_f32_16x16x32_bf16 v[104:107], v[172:175], v[188:191], v[104:107]
	v_mfma_f32_16x16x32_bf16 v[80:83], v[180:183], v[188:191], v[80:83]
	v_mfma_f32_16x16x32_bf16 v[96:99], v[172:175], v[196:199], v[96:99]
	v_mfma_f32_16x16x32_bf16 v[68:71], v[180:183], v[196:199], v[68:71]
	v_mfma_f32_16x16x32_bf16 v[88:91], v[172:175], v[218:221], v[88:91]
	v_mfma_f32_16x16x32_bf16 v[60:63], v[180:183], v[218:221], v[60:63]
	v_mfma_f32_16x16x32_bf16 v[76:79], v[172:175], v[226:229], v[76:79]
	v_mfma_f32_16x16x32_bf16 v[48:51], v[180:183], v[226:229], v[48:51]

; #define PG8_STAGE(bufoff, gbase, voff) do { _Pragma("unroll") for (int _i = 0; _i < 2; ++_i) \
;         __builtin_amdgcn_global_load_lds((const unsigned*)((const char*)(gbase) + (voff)[_i]), (LAS unsigned*)(lds + (bufoff) + ldsw + _i * 8192), 16, 0, 0); } while (0)
; #define PG8_LDA(dst, b, h) do { _Pragma("unroll") for (int m = 0; m < 4; ++m) _Pragma("unroll") for (int k = 0; k < 2; ++k) dst[m][k] = *(const LAS bf16x8*)(lds + PG8_SA(b, h) + aoff + m * 2048 + k * 1024); } while (0)
; #define PG8_MMA(ai, bj, At, Bt) do { __builtin_amdgcn_s_setprio(1); _Pragma("unroll") for (int m = 0; m < 4; ++m) _Pragma("unroll") for (int n = 0; n < 2; ++n) _Pragma("unroll") for (int k = 0; k < 2; ++k) \
;         acc[ai][bj][m][n] = __builtin_amdgcn_mfma_f32_16x16x32_bf16(Bt[n][k], At[m][k], acc[ai][bj][m][n], 0, 0, 0); __builtin_amdgcn_s_setprio(0); } while (0)
; #define PG8_WAIT_V(n) asm volatile("s_waitcnt vmcnt(" #n ")" ::: "memory")
; #define PG8_WAIT_L(n) asm volatile("s_waitcnt lgkmcnt(" #n ")" ::: "memory")
; #define PG8_BAR __builtin_amdgcn_s_barrier()
; #define PG8_SCHED __builtin_amdgcn_sched_barrier(0)
; template <class Epi, bool ALIGN_EPI>
; __device__ __forceinline__ void gemm_phase(LAS unsigned char* lds, const Gemm g, const StaticOrder& S, const Epi& E, const int tid) {
;     ...
;             PG8_WAIT_V(8); PG8_WAIT_L(0); PG8_BAR; PG8_MMA(0, 0, At, B0); PG8_MMA(0, 1, At, B1); PG8_BAR; PG8_SCHED;
;             PG8_LDA(At, 0, 1); PG8_STAGE(PG8_SB(0, 0), b2, voffB); PG8_STAGE(PG8_SB(0, 1), b2 + hstepB, voffB); PG8_STAGE(PG8_SA(0, 0), a2, voffA);
	s_barrier
	s_add_i32 s89, s89, s61
	s_mov_b32 m0, s89
	ds_read_b128 v[184:187], v171 offset:16384
	ds_read_b128 v[188:191], v171 offset:17408
	ds_read_b128 v[192:195], v171 offset:18432
	ds_read_b128 v[196:199], v171 offset:19456


; #define PG8_STAGE(bufoff, gbase, voff) do { _Pragma("unroll") for (int _i = 0; _i < 2; ++_i) \
;         __builtin_amdgcn_global_load_lds((const unsigned*)((const char*)(gbase) + (voff)[_i]), (LAS unsigned*)(lds + (bufoff) + ldsw + _i * 8192), 16, 0, 0); } while (0)
; #define PG8_LDA(dst, b, h) do { _Pragma("unroll") for (int m = 0; m < 4; ++m) _Pragma("unroll") for (int k = 0; k < 2; ++k) dst[m][k] = *(const LAS bf16x8*)(lds + PG8_SA(b, h) + aoff + m * 2048 + k * 1024); } while (0)
; #define PG8_MMA(ai, bj, At, Bt) do { __builtin_amdgcn_s_setprio(1); _Pragma("unroll") for (int m = 0; m < 4; ++m) _Pragma("unroll") for (int n = 0; n < 2; ++n) _Pragma("unroll") for (int k = 0; k < 2; ++k) \
;         acc[ai][bj][m][n] = __builtin_amdgcn_mfma_f32_16x16x32_bf16(Bt[n][k], At[m][k], acc[ai][bj][m][n], 0, 0, 0); __builtin_amdgcn_s_setprio(0); } while (0)
; #define PG8_WAIT_V(n) asm volatile("s_waitcnt vmcnt(" #n ")" ::: "memory")
; #define PG8_WAIT_L(n) asm volatile("s_waitcnt lgkmcnt(" #n ")" ::: "memory")
; #define PG8_BAR __builtin_amdgcn_s_barrier()
; #define PG8_SCHED __builtin_amdgcn_sched_barrier(0)
; template <class Epi, bool ALIGN_EPI>
; __device__ __forceinline__ void gemm_phase(LAS unsigned char* lds, const Gemm g, const StaticOrder& S, const Epi& E, const int tid) {
;     ...
;             PG8_LDA(At, 0, 1); PG8_STAGE(PG8_SB(0, 0), b2, voffB); PG8_STAGE(PG8_SB(0, 1), b2 + hstepB, voffB); PG8_STAGE(PG8_SA(0, 0), a2, voffA);
;             PG8_WAIT_V(8); PG8_WAIT_L(0); PG8_BAR; PG8_MMA(1, 0, At, B0); PG8_MMA(1, 1, At, B1); PG8_BAR; PG8_SCHED;
	global_load_lds_dwordx4 v144, s[52:53]
	s_add_i32 m0, s89, 0x2000
	s_add_u32 s90, s52, 0x4000
	s_addc_u32 s91, s53, 0
	s_add_i32 s89, s92, s61
	global_load_lds_dwordx4 v140, s[52:53]
	s_mov_b32 m0, s89
	ds_read_b128 v[226:229], v171 offset:23552
	global_load_lds_dwordx4 v144, s[90:91]
	s_add_i32 m0, s89, 0x2000
	ds_read_b128 v[222:225], v171 offset:22528
	global_load_lds_dwordx4 v140, s[90:91]
	s_mov_b32 m0, s71
	ds_read_b128 v[218:221], v171 offset:21504
	global_load_lds_dwordx4 v146, s[54:55]
	s_mov_b32 m0, s72
	ds_read_b128 v[214:217], v171 offset:20480
	global_load_lds_dwordx4 v142, s[54:55]
	s_waitcnt vmcnt(8)
	s_waitcnt lgkmcnt(0)
	s_barrier


; #define PG8_MMA(ai, bj, At, Bt) do { __builtin_amdgcn_s_setprio(1); _Pragma("unroll") for (int m = 0; m < 4; ++m) _Pragma("unroll") for (int n = 0; n < 2; ++n) _Pragma("unroll") for (int k = 0; k < 2; ++k) \
;         acc[ai][bj][m][n] = __builtin_amdgcn_mfma_f32_16x16x32_bf16(Bt[n][k], At[m][k], acc[ai][bj][m][n], 0, 0, 0); __builtin_amdgcn_s_setprio(0); } while (0)
; #define PG8_WAIT_V(n) asm volatile("s_waitcnt vmcnt(" #n ")" ::: "memory")
; #define PG8_WAIT_L(n) asm volatile("s_waitcnt lgkmcnt(" #n ")" ::: "memory")
; #define PG8_BAR __builtin_amdgcn_s_barrier()
; #define PG8_SCHED __builtin_amdgcn_sched_barrier(0)
; template <class Epi, bool ALIGN_EPI>
; __device__ __forceinline__ void gemm_phase(LAS unsigned char* lds, const Gemm g, const StaticOrder& S, const Epi& E, const int tid) {
;     ...
;             PG8_WAIT_V(8); PG8_WAIT_L(0); PG8_BAR; PG8_MMA(1, 0, At, B0); PG8_MMA(1, 1, At, B1); PG8_BAR; PG8_SCHED;
	v_mfma_f32_16x16x32_bf16 v[84:87], v[132:135], v[184:187], v[84:87]
	v_mfma_f32_16x16x32_bf16 v[56:59], v[152:155], v[184:187], v[56:59]
	v_mfma_f32_16x16x32_bf16 v[72:75], v[132:135], v[192:195], v[72:75]
	v_mfma_f32_16x16x32_bf16 v[44:47], v[152:155], v[192:195], v[44:47]
	v_mfma_f32_16x16x32_bf16 v[64:67], v[132:135], v[214:217], v[64:67]
	v_mfma_f32_16x16x32_bf16 v[36:39], v[152:155], v[214:217], v[36:39]
	v_mfma_f32_16x16x32_bf16 v[52:55], v[132:135], v[222:225], v[52:55]
	v_mfma_f32_16x16x32_bf16 v[28:31], v[152:155], v[222:225], v[28:31]
	v_mfma_f32_16x16x32_bf16 v[84:87], v[136:139], v[188:191], v[84:87]
	v_mfma_f32_16x16x32_bf16 v[56:59], v[156:159], v[188:191], v[56:59]
	v_mfma_f32_16x16x32_bf16 v[72:75], v[136:139], v[196:199], v[72:75]
	v_mfma_f32_16x16x32_bf16 v[44:47], v[156:159], v[196:199], v[44:47]
	v_mfma_f32_16x16x32_bf16 v[64:67], v[136:139], v[218:221], v[64:67]
	v_mfma_f32_16x16x32_bf16 v[36:39], v[156:159], v[218:221], v[36:39]
	v_mfma_f32_16x16x32_bf16 v[52:55], v[136:139], v[226:229], v[52:55]
	v_mfma_f32_16x16x32_bf16 v[28:31], v[156:159], v[226:229], v[28:31]


; #define PG8_MMA(ai, bj, At, Bt) do { __builtin_amdgcn_s_setprio(1); _Pragma("unroll") for (int m = 0; m < 4; ++m) _Pragma("unroll") for (int n = 0; n < 2; ++n) _Pragma("unroll") for (int k = 0; k < 2; ++k) \
;         acc[ai][bj][m][n] = __builtin_amdgcn_mfma_f32_16x16x32_bf16(Bt[n][k], At[m][k], acc[ai][bj][m][n], 0, 0, 0); __builtin_amdgcn_s_setprio(0); } while (0)
; #define PG8_WAIT_V(n) asm volatile("s_waitcnt vmcnt(" #n ")" ::: "memory")
; #define PG8_WAIT_L(n) asm volatile("s_waitcnt lgkmcnt(" #n ")" ::: "memory")
; #define PG8_BAR __builtin_amdgcn_s_barrier()
; #define PG8_SCHED __builtin_amdgcn_sched_barrier(0)
; template <class Epi, bool ALIGN_EPI>
; __device__ __forceinline__ void gemm_phase(LAS unsigned char* lds, const Gemm g, const StaticOrder& S, const Epi& E, const int tid) {
;     ...
;             PG8_WAIT_V(8); PG8_WAIT_L(0); PG8_BAR; PG8_MMA(1, 0, At, B0); PG8_MMA(1, 1, At, B1); PG8_BAR; PG8_SCHED;
	v_mfma_f32_16x16x32_bf16 v[40:43], v[160:163], v[184:187], v[40:43]
	v_mfma_f32_16x16x32_bf16 v[20:23], v[176:179], v[184:187], v[20:23]
	v_mfma_f32_16x16x32_bf16 v[32:35], v[160:163], v[192:195], v[32:35]
	v_mfma_f32_16x16x32_bf16 v[12:15], v[176:179], v[192:195], v[12:15]
	v_mfma_f32_16x16x32_bf16 v[24:27], v[160:163], v[214:217], v[24:27]
	v_mfma_f32_16x16x32_bf16 v[8:11], v[176:179], v[214:217], v[8:11]
	v_mfma_f32_16x16x32_bf16 v[16:19], v[160:163], v[222:225], v[16:19]
	v_mfma_f32_16x16x32_bf16 v[2:5], v[176:179], v[222:225], v[4:7]
	v_mfma_f32_16x16x32_bf16 v[40:43], v[172:175], v[188:191], v[40:43]
	v_mfma_f32_16x16x32_bf16 v[20:23], v[180:183], v[188:191], v[20:23]
	v_mfma_f32_16x16x32_bf16 v[32:35], v[172:175], v[196:199], v[32:35]
	v_mfma_f32_16x16x32_bf16 v[12:15], v[180:183], v[196:199], v[12:15]
	v_mfma_f32_16x16x32_bf16 v[24:27], v[172:175], v[218:221], v[24:27]
	v_mfma_f32_16x16x32_bf16 v[8:11], v[180:183], v[218:221], v[8:11]
	v_mfma_f32_16x16x32_bf16 v[16:19], v[172:175], v[226:229], v[16:19]
	v_mfma_f32_16x16x32_bf16 v[2:5], v[180:183], v[226:229], v[2:5]

; #define PG8_STAGE(bufoff, gbase, voff) do { _Pragma("unroll") for (int _i = 0; _i < 2; ++_i) \
;         __builtin_amdgcn_global_load_lds((const unsigned*)((const char*)(gbase) + (voff)[_i]), (LAS unsigned*)(lds + (bufoff) + ldsw + _i * 8192), 16, 0, 0); } while (0)
; #define PG8_LDA(dst, b, h) do { _Pragma("unroll") for (int m = 0; m < 4; ++m) _Pragma("unroll") for (int k = 0; k < 2; ++k) dst[m][k] = *(const LAS bf16x8*)(lds + PG8_SA(b, h) + aoff + m * 2048 + k * 1024); } while (0)
; #define PG8_LDB(dst, b, h) do { _Pragma("unroll") for (int n = 0; n < 2; ++n) _Pragma("unroll") for (int k = 0; k < 2; ++k) dst[n][k] = *(const LAS bf16x8*)(lds + PG8_SB(b, h) + boff + n * 2048 + k * 1024); } while (0)
; #define PG8_MMA(ai, bj, At, Bt) do { __builtin_amdgcn_s_setprio(1); _Pragma("unroll") for (int m = 0; m < 4; ++m) _Pragma("unroll") for (int n = 0; n < 2; ++n) _Pragma("unroll") for (int k = 0; k < 2; ++k) \
;         acc[ai][bj][m][n] = __builtin_amdgcn_mfma_f32_16x16x32_bf16(Bt[n][k], At[m][k], acc[ai][bj][m][n], 0, 0, 0); __builtin_amdgcn_s_setprio(0); } while (0)
; #define PG8_WAIT_V(n) asm volatile("s_waitcnt vmcnt(" #n ")" ::: "memory")
; #define PG8_WAIT_L(n) asm volatile("s_waitcnt lgkmcnt(" #n ")" ::: "memory")
; #define PG8_BAR __builtin_amdgcn_s_barrier()
; #define PG8_SCHED __builtin_amdgcn_sched_barrier(0)
; template <class Epi, bool ALIGN_EPI>
; __device__ __forceinline__ void gemm_phase(LAS unsigned char* lds, const Gemm g, const StaticOrder& S, const Epi& E, const int tid) {
;     ...
;             PG8_WAIT_V(8); PG8_WAIT_L(0); PG8_BAR; PG8_MMA(1, 0, At, B0); PG8_MMA(1, 1, At, B1); PG8_BAR; PG8_SCHED;
;             PG8_LDB(B0, 1, 0); PG8_LDB(B1, 1, 1); PG8_SCHED; PG8_LDA(At, 1, 0); PG8_STAGE(PG8_SA(0, 1), a2 + hstepA, voffA);
	s_barrier
	s_add_i32 s89, 0, 0x18000
	v_add_u32_e32 v0, s89, v167
	s_add_i32 s90, 0, 0x1c000
	ds_read_b128 v[132:135], v0
	ds_read_b128 v[136:139], v0 offset:1024
	ds_read_b128 v[152:155], v0 offset:2048
	ds_read_b128 v[156:159], v0 offset:3072
	v_add_u32_e32 v0, s90, v167
	ds_read_b128 v[160:163], v0
	ds_read_b128 v[172:175], v0 offset:1024
	ds_read_b128 v[176:179], v0 offset:2048
	ds_read_b128 v[180:183], v0 offset:3072
	s_add_u32 s54, s54, 0x4000
	s_addc_u32 s55, s55, 0
	s_mov_b32 m0, s73
	ds_read_b128 v[184:187], v171 offset:32768
	ds_read_b128 v[188:191], v171 offset:33792
	ds_read_b128 v[192:195], v171 offset:34816
	ds_read_b128 v[196:199], v171 offset:35840
	ds_read_b128 v[214:217], v171 offset:36864
	ds_read_b128 v[218:221], v171 offset:37888
	ds_read_b128 v[222:225], v171 offset:38912

; #define PG8_STAGE(bufoff, gbase, voff) do { _Pragma("unroll") for (int _i = 0; _i < 2; ++_i) \
;         __builtin_amdgcn_global_load_lds((const unsigned*)((const char*)(gbase) + (voff)[_i]), (LAS unsigned*)(lds + (bufoff) + ldsw + _i * 8192), 16, 0, 0); } while (0)
; #define PG8_LDA(dst, b, h) do { _Pragma("unroll") for (int m = 0; m < 4; ++m) _Pragma("unroll") for (int k = 0; k < 2; ++k) dst[m][k] = *(const LAS bf16x8*)(lds + PG8_SA(b, h) + aoff + m * 2048 + k * 1024); } while (0)
; #define PG8_LDB(dst, b, h) do { _Pragma("unroll") for (int n = 0; n < 2; ++n) _Pragma("unroll") for (int k = 0; k < 2; ++k) dst[n][k] = *(const LAS bf16x8*)(lds + PG8_SB(b, h) + boff + n * 2048 + k * 1024); } while (0)
; #define PG8_MMA(ai, bj, At, Bt) do { __builtin_amdgcn_s_setprio(1); _Pragma("unroll") for (int m = 0; m < 4; ++m) _Pragma("unroll") for (int n = 0; n < 2; ++n) _Pragma("unroll") for (int k = 0; k < 2; ++k) \
;         acc[ai][bj][m][n] = __builtin_amdgcn_mfma_f32_16x16x32_bf16(Bt[n][k], At[m][k], acc[ai][bj][m][n], 0, 0, 0); __builtin_amdgcn_s_setprio(0); } while (0)
; #define PG8_WAIT_V(n) asm volatile("s_waitcnt vmcnt(" #n ")" ::: "memory")
; #define PG8_WAIT_L(n) asm volatile("s_waitcnt lgkmcnt(" #n ")" ::: "memory")
; #define PG8_BAR __builtin_amdgcn_s_barrier()
; #define PG8_SCHED __builtin_amdgcn_sched_barrier(0)
; template <class Epi, bool ALIGN_EPI>
; __device__ __forceinline__ void gemm_phase(LAS unsigned char* lds, const Gemm g, const StaticOrder& S, const Epi& E, const int tid) {
;     ...
;             PG8_LDB(B0, 1, 0); PG8_LDB(B1, 1, 1); PG8_SCHED; PG8_LDA(At, 1, 0); PG8_STAGE(PG8_SA(0, 1), a2 + hstepA, voffA);
;             PG8_WAIT_V(8); PG8_WAIT_L(0); PG8_BAR; PG8_MMA(0, 0, At, B0); PG8_MMA(0, 1, At, B1); PG8_BAR; PG8_SCHED;
	global_load_lds_dwordx4 v146, s[54:55]
	s_mov_b32 m0, s74
	ds_read_b128 v[226:229], v171 offset:39936
	global_load_lds_dwordx4 v142, s[54:55]
	s_waitcnt vmcnt(8)
	s_waitcnt lgkmcnt(0)
	s_barrier


; #define PG8_MMA(ai, bj, At, Bt) do { __builtin_amdgcn_s_setprio(1); _Pragma("unroll") for (int m = 0; m < 4; ++m) _Pragma("unroll") for (int n = 0; n < 2; ++n) _Pragma("unroll") for (int k = 0; k < 2; ++k) \
;         acc[ai][bj][m][n] = __builtin_amdgcn_mfma_f32_16x16x32_bf16(Bt[n][k], At[m][k], acc[ai][bj][m][n], 0, 0, 0); __builtin_amdgcn_s_setprio(0); } while (0)
; #define PG8_WAIT_V(n) asm volatile("s_waitcnt vmcnt(" #n ")" ::: "memory")
; #define PG8_WAIT_L(n) asm volatile("s_waitcnt lgkmcnt(" #n ")" ::: "memory")
; #define PG8_BAR __builtin_amdgcn_s_barrier()
; #define PG8_SCHED __builtin_amdgcn_sched_barrier(0)
; template <class Epi, bool ALIGN_EPI>
; __device__ __forceinline__ void gemm_phase(LAS unsigned char* lds, const Gemm g, const StaticOrder& S, const Epi& E, const int tid) {
;     ...
;             PG8_WAIT_V(8); PG8_WAIT_L(0); PG8_BAR; PG8_MMA(0, 0, At, B0); PG8_MMA(0, 1, At, B1); PG8_BAR; PG8_SCHED;
	v_mfma_f32_16x16x32_bf16 v[128:131], v[132:135], v[184:187], v[128:131]
	v_mfma_f32_16x16x32_bf16 v[116:119], v[152:155], v[184:187], v[116:119]
	v_mfma_f32_16x16x32_bf16 v[124:127], v[132:135], v[192:195], v[124:127]
	v_mfma_f32_16x16x32_bf16 v[108:111], v[152:155], v[192:195], v[108:111]
	v_mfma_f32_16x16x32_bf16 v[120:123], v[132:135], v[214:217], v[120:123]
	v_mfma_f32_16x16x32_bf16 v[100:103], v[152:155], v[214:217], v[100:103]
	v_mfma_f32_16x16x32_bf16 v[112:115], v[132:135], v[222:225], v[112:115]
	v_mfma_f32_16x16x32_bf16 v[92:95], v[152:155], v[222:225], v[92:95]
	v_mfma_f32_16x16x32_bf16 v[128:131], v[136:139], v[188:191], v[128:131]
	v_mfma_f32_16x16x32_bf16 v[116:119], v[156:159], v[188:191], v[116:119]
	v_mfma_f32_16x16x32_bf16 v[124:127], v[136:139], v[196:199], v[124:127]
	v_mfma_f32_16x16x32_bf16 v[108:111], v[156:159], v[196:199], v[108:111]
	v_mfma_f32_16x16x32_bf16 v[120:123], v[136:139], v[218:221], v[120:123]
	v_mfma_f32_16x16x32_bf16 v[100:103], v[156:159], v[218:221], v[100:103]
	v_mfma_f32_16x16x32_bf16 v[112:115], v[136:139], v[226:229], v[112:115]
	v_mfma_f32_16x16x32_bf16 v[92:95], v[156:159], v[226:229], v[92:95]


; #define PG8_MMA(ai, bj, At, Bt) do { __builtin_amdgcn_s_setprio(1); _Pragma("unroll") for (int m = 0; m < 4; ++m) _Pragma("unroll") for (int n = 0; n < 2; ++n) _Pragma("unroll") for (int k = 0; k < 2; ++k) \
;         acc[ai][bj][m][n] = __builtin_amdgcn_mfma_f32_16x16x32_bf16(Bt[n][k], At[m][k], acc[ai][bj][m][n], 0, 0, 0); __builtin_amdgcn_s_setprio(0); } while (0)
; #define PG8_WAIT_V(n) asm volatile("s_waitcnt vmcnt(" #n ")" ::: "memory")
; #define PG8_WAIT_L(n) asm volatile("s_waitcnt lgkmcnt(" #n ")" ::: "memory")
; #define PG8_BAR __builtin_amdgcn_s_barrier()
; #define PG8_SCHED __builtin_amdgcn_sched_barrier(0)
; template <class Epi, bool ALIGN_EPI>
; __device__ __forceinline__ void gemm_phase(LAS unsigned char* lds, const Gemm g, const StaticOrder& S, const Epi& E, const int tid) {
;     ...
;             PG8_WAIT_V(8); PG8_WAIT_L(0); PG8_BAR; PG8_MMA(0, 0, At, B0); PG8_MMA(0, 1, At, B1); PG8_BAR; PG8_SCHED;
	v_mfma_f32_16x16x32_bf16 v[104:107], v[160:163], v[184:187], v[104:107]
	v_mfma_f32_16x16x32_bf16 v[80:83], v[176:179], v[184:187], v[80:83]
	v_mfma_f32_16x16x32_bf16 v[96:99], v[160:163], v[192:195], v[96:99]
	v_mfma_f32_16x16x32_bf16 v[68:71], v[176:179], v[192:195], v[68:71]
	v_mfma_f32_16x16x32_bf16 v[88:91], v[160:163], v[214:217], v[88:91]
	v_mfma_f32_16x16x32_bf16 v[60:63], v[176:179], v[214:217], v[60:63]
	v_mfma_f32_16x16x32_bf16 v[76:79], v[160:163], v[222:225], v[76:79]
	v_mfma_f32_16x16x32_bf16 v[48:51], v[176:179], v[222:225], v[48:51]
	v_mfma_f32_16x16x32_bf16 v[104:107], v[172:175], v[188:191], v[104:107]
	v_mfma_f32_16x16x32_bf16 v[80:83], v[180:183], v[188:191], v[80:83]
	v_mfma_f32_16x16x32_bf16 v[96:99], v[172:175], v[196:199], v[96:99]
	v_mfma_f32_16x16x32_bf16 v[68:71], v[180:183], v[196:199], v[68:71]
	v_mfma_f32_16x16x32_bf16 v[88:91], v[172:175], v[218:221], v[88:91]
	v_mfma_f32_16x16x32_bf16 v[60:63], v[180:183], v[218:221], v[60:63]
	v_mfma_f32_16x16x32_bf16 v[76:79], v[172:175], v[226:229], v[76:79]
	v_mfma_f32_16x16x32_bf16 v[48:51], v[180:183], v[226:229], v[48:51]

; #define PG8_STAGE(bufoff, gbase, voff) do { _Pragma("unroll") for (int _i = 0; _i < 2; ++_i) \
;         __builtin_amdgcn_global_load_lds((const unsigned*)((const char*)(gbase) + (voff)[_i]), (LAS unsigned*)(lds + (bufoff) + ldsw + _i * 8192), 16, 0, 0); } while (0)
; #define PG8_LDA(dst, b, h) do { _Pragma("unroll") for (int m = 0; m < 4; ++m) _Pragma("unroll") for (int k = 0; k < 2; ++k) dst[m][k] = *(const LAS bf16x8*)(lds + PG8_SA(b, h) + aoff + m * 2048 + k * 1024); } while (0)
; #define PG8_MMA(ai, bj, At, Bt) do { __builtin_amdgcn_s_setprio(1); _Pragma("unroll") for (int m = 0; m < 4; ++m) _Pragma("unroll") for (int n = 0; n < 2; ++n) _Pragma("unroll") for (int k = 0; k < 2; ++k) \
;         acc[ai][bj][m][n] = __builtin_amdgcn_mfma_f32_16x16x32_bf16(Bt[n][k], At[m][k], acc[ai][bj][m][n], 0, 0, 0); __builtin_amdgcn_s_setprio(0); } while (0)
; #define PG8_WAIT_V(n) asm volatile("s_waitcnt vmcnt(" #n ")" ::: "memory")
; #define PG8_WAIT_L(n) asm volatile("s_waitcnt lgkmcnt(" #n ")" ::: "memory")
; #define PG8_BAR __builtin_amdgcn_s_barrier()
; #define PG8_SCHED __builtin_amdgcn_sched_barrier(0)
; template <class Epi, bool ALIGN_EPI>
; __device__ __forceinline__ void gemm_phase(LAS unsigned char* lds, const Gemm g, const StaticOrder& S, const Epi& E, const int tid) {
;     ...
;             PG8_WAIT_V(8); PG8_WAIT_L(0); PG8_BAR; PG8_MMA(0, 0, At, B0); PG8_MMA(0, 1, At, B1); PG8_BAR; PG8_SCHED;
;             PG8_LDA(At, 1, 1); PG8_STAGE(PG8_SB(1, 0), b3, voffB); PG8_STAGE(PG8_SB(1, 1), b3 + hstepB, voffB); PG8_STAGE(PG8_SA(1, 0), a3, voffA);
	s_barrier
	s_add_u32 s54, s52, 0x8000
	s_addc_u32 s55, s53, 0
	s_add_i32 s89, s89, s61
	s_mov_b32 m0, s89
	ds_read_b128 v[184:187], v171 offset:49152
	ds_read_b128 v[188:191], v171 offset:50176
	ds_read_b128 v[192:195], v171 offset:51200
	ds_read_b128 v[196:199], v171 offset:52224


; #define PG8_STAGE(bufoff, gbase, voff) do { _Pragma("unroll") for (int _i = 0; _i < 2; ++_i) \
;         __builtin_amdgcn_global_load_lds((const unsigned*)((const char*)(gbase) + (voff)[_i]), (LAS unsigned*)(lds + (bufoff) + ldsw + _i * 8192), 16, 0, 0); } while (0)
; #define PG8_LDA(dst, b, h) do { _Pragma("unroll") for (int m = 0; m < 4; ++m) _Pragma("unroll") for (int k = 0; k < 2; ++k) dst[m][k] = *(const LAS bf16x8*)(lds + PG8_SA(b, h) + aoff + m * 2048 + k * 1024); } while (0)
; #define PG8_MMA(ai, bj, At, Bt) do { __builtin_amdgcn_s_setprio(1); _Pragma("unroll") for (int m = 0; m < 4; ++m) _Pragma("unroll") for (int n = 0; n < 2; ++n) _Pragma("unroll") for (int k = 0; k < 2; ++k) \
;         acc[ai][bj][m][n] = __builtin_amdgcn_mfma_f32_16x16x32_bf16(Bt[n][k], At[m][k], acc[ai][bj][m][n], 0, 0, 0); __builtin_amdgcn_s_setprio(0); } while (0)
; #define PG8_WAIT_V(n) asm volatile("s_waitcnt vmcnt(" #n ")" ::: "memory")
; #define PG8_WAIT_L(n) asm volatile("s_waitcnt lgkmcnt(" #n ")" ::: "memory")
; #define PG8_BAR __builtin_amdgcn_s_barrier()
; #define PG8_SCHED __builtin_amdgcn_sched_barrier(0)
; template <class Epi, bool ALIGN_EPI>
; __device__ __forceinline__ void gemm_phase(LAS unsigned char* lds, const Gemm g, const StaticOrder& S, const Epi& E, const int tid) {
;     ...
;             PG8_LDA(At, 1, 1); PG8_STAGE(PG8_SB(1, 0), b3, voffB); PG8_STAGE(PG8_SB(1, 1), b3 + hstepB, voffB); PG8_STAGE(PG8_SA(1, 0), a3, voffA);
;             PG8_WAIT_V(8); PG8_WAIT_L(0); PG8_BAR; PG8_MMA(1, 0, At, B0); PG8_MMA(1, 1, At, B1); PG8_BAR; PG8_SCHED;
	global_load_lds_dwordx4 v144, s[54:55]
	s_add_i32 m0, s89, 0x2000
	s_add_u32 s52, s52, 0xc000
	s_addc_u32 s53, s53, 0
	global_load_lds_dwordx4 v140, s[54:55]
	s_add_i32 s54, s90, s61
	s_mov_b32 m0, s54
	ds_read_b128 v[226:229], v171 offset:56320
	global_load_lds_dwordx4 v144, s[52:53]
	s_add_i32 m0, s54, 0x2000
	ds_read_b128 v[222:225], v171 offset:55296
	global_load_lds_dwordx4 v140, s[52:53]
	s_mov_b32 m0, s77
	ds_read_b128 v[218:221], v171 offset:54272
	global_load_lds_dwordx4 v146, s[50:51]
	s_mov_b32 m0, s78
	ds_read_b128 v[214:217], v171 offset:53248
	global_load_lds_dwordx4 v142, s[50:51]
	s_waitcnt vmcnt(8)
	s_waitcnt lgkmcnt(0)
	s_barrier


; #define PG8_MMA(ai, bj, At, Bt) do { __builtin_amdgcn_s_setprio(1); _Pragma("unroll") for (int m = 0; m < 4; ++m) _Pragma("unroll") for (int n = 0; n < 2; ++n) _Pragma("unroll") for (int k = 0; k < 2; ++k) \
;         acc[ai][bj][m][n] = __builtin_amdgcn_mfma_f32_16x16x32_bf16(Bt[n][k], At[m][k], acc[ai][bj][m][n], 0, 0, 0); __builtin_amdgcn_s_setprio(0); } while (0)
; #define PG8_WAIT_V(n) asm volatile("s_waitcnt vmcnt(" #n ")" ::: "memory")
; #define PG8_WAIT_L(n) asm volatile("s_waitcnt lgkmcnt(" #n ")" ::: "memory")
; #define PG8_BAR __builtin_amdgcn_s_barrier()
; #define PG8_SCHED __builtin_amdgcn_sched_barrier(0)
; template <class Epi, bool ALIGN_EPI>
; __device__ __forceinline__ void gemm_phase(LAS unsigned char* lds, const Gemm g, const StaticOrder& S, const Epi& E, const int tid) {
;     ...
;             PG8_WAIT_V(8); PG8_WAIT_L(0); PG8_BAR; PG8_MMA(1, 0, At, B0); PG8_MMA(1, 1, At, B1); PG8_BAR; PG8_SCHED;
	v_mfma_f32_16x16x32_bf16 v[84:87], v[132:135], v[184:187], v[84:87]
	v_mfma_f32_16x16x32_bf16 v[56:59], v[152:155], v[184:187], v[56:59]
	v_mfma_f32_16x16x32_bf16 v[72:75], v[132:135], v[192:195], v[72:75]
	v_mfma_f32_16x16x32_bf16 v[44:47], v[152:155], v[192:195], v[44:47]
	v_mfma_f32_16x16x32_bf16 v[64:67], v[132:135], v[214:217], v[64:67]
	v_mfma_f32_16x16x32_bf16 v[36:39], v[152:155], v[214:217], v[36:39]
	v_mfma_f32_16x16x32_bf16 v[52:55], v[132:135], v[222:225], v[52:55]
	v_mfma_f32_16x16x32_bf16 v[28:31], v[152:155], v[222:225], v[28:31]
	v_mfma_f32_16x16x32_bf16 v[84:87], v[136:139], v[188:191], v[84:87]
	v_mfma_f32_16x16x32_bf16 v[56:59], v[156:159], v[188:191], v[56:59]
	v_mfma_f32_16x16x32_bf16 v[72:75], v[136:139], v[196:199], v[72:75]
	v_mfma_f32_16x16x32_bf16 v[44:47], v[156:159], v[196:199], v[44:47]
	v_mfma_f32_16x16x32_bf16 v[64:67], v[136:139], v[218:221], v[64:67]
	v_mfma_f32_16x16x32_bf16 v[36:39], v[156:159], v[218:221], v[36:39]
	v_mfma_f32_16x16x32_bf16 v[52:55], v[136:139], v[226:229], v[52:55]
	v_mfma_f32_16x16x32_bf16 v[28:31], v[156:159], v[226:229], v[28:31]


; #define PG8_MMA(ai, bj, At, Bt) do { __builtin_amdgcn_s_setprio(1); _Pragma("unroll") for (int m = 0; m < 4; ++m) _Pragma("unroll") for (int n = 0; n < 2; ++n) _Pragma("unroll") for (int k = 0; k < 2; ++k) \
;         acc[ai][bj][m][n] = __builtin_amdgcn_mfma_f32_16x16x32_bf16(Bt[n][k], At[m][k], acc[ai][bj][m][n], 0, 0, 0); __builtin_amdgcn_s_setprio(0); } while (0)
; #define PG8_WAIT_V(n) asm volatile("s_waitcnt vmcnt(" #n ")" ::: "memory")
; #define PG8_WAIT_L(n) asm volatile("s_waitcnt lgkmcnt(" #n ")" ::: "memory")
; #define PG8_BAR __builtin_amdgcn_s_barrier()
; #define PG8_SCHED __builtin_amdgcn_sched_barrier(0)
; template <class Epi, bool ALIGN_EPI>
; __device__ __forceinline__ void gemm_phase(LAS unsigned char* lds, const Gemm g, const StaticOrder& S, const Epi& E, const int tid) {
;     ...
;             PG8_WAIT_V(8); PG8_WAIT_L(0); PG8_BAR; PG8_MMA(1, 0, At, B0); PG8_MMA(1, 1, At, B1); PG8_BAR; PG8_SCHED;
	v_mfma_f32_16x16x32_bf16 v[40:43], v[160:163], v[184:187], v[40:43]
	v_mfma_f32_16x16x32_bf16 v[20:23], v[176:179], v[184:187], v[20:23]
	v_mfma_f32_16x16x32_bf16 v[32:35], v[160:163], v[192:195], v[32:35]
	v_mfma_f32_16x16x32_bf16 v[12:15], v[176:179], v[192:195], v[12:15]
	v_mfma_f32_16x16x32_bf16 v[24:27], v[160:163], v[214:217], v[24:27]
	v_mfma_f32_16x16x32_bf16 v[6:9], v[176:179], v[214:217], v[8:11]
	v_mfma_f32_16x16x32_bf16 v[16:19], v[160:163], v[222:225], v[16:19]
	v_mfma_f32_16x16x32_bf16 v[2:5], v[176:179], v[222:225], v[2:5]
	v_mfma_f32_16x16x32_bf16 v[40:43], v[172:175], v[188:191], v[40:43]
	v_mfma_f32_16x16x32_bf16 v[20:23], v[180:183], v[188:191], v[20:23]
	v_mfma_f32_16x16x32_bf16 v[32:35], v[172:175], v[196:199], v[32:35]
	v_mfma_f32_16x16x32_bf16 v[12:15], v[180:183], v[196:199], v[12:15]
	v_mfma_f32_16x16x32_bf16 v[24:27], v[172:175], v[218:221], v[24:27]
	v_mfma_f32_16x16x32_bf16 v[8:11], v[180:183], v[218:221], v[6:9]
	v_mfma_f32_16x16x32_bf16 v[16:19], v[172:175], v[226:229], v[16:19]
	v_mfma_f32_16x16x32_bf16 v[4:7], v[180:183], v[226:229], v[2:5]

; #define PG8_MMA(ai, bj, At, Bt) do { __builtin_amdgcn_s_setprio(1); _Pragma("unroll") for (int m = 0; m < 4; ++m) _Pragma("unroll") for (int n = 0; n < 2; ++n) _Pragma("unroll") for (int k = 0; k < 2; ++k) \
;         acc[ai][bj][m][n] = __builtin_amdgcn_mfma_f32_16x16x32_bf16(Bt[n][k], At[m][k], acc[ai][bj][m][n], 0, 0, 0); __builtin_amdgcn_s_setprio(0); } while (0)
; #define PG8_WAIT_V(n) asm volatile("s_waitcnt vmcnt(" #n ")" ::: "memory")
; #define PG8_WAIT_L(n) asm volatile("s_waitcnt lgkmcnt(" #n ")" ::: "memory")
; #define PG8_BAR __builtin_amdgcn_s_barrier()
; #define PG8_SCHED __builtin_amdgcn_sched_barrier(0)
; template <class Epi, bool ALIGN_EPI>
; __device__ __forceinline__ void gemm_phase(LAS unsigned char* lds, const Gemm g, const StaticOrder& S, const Epi& E, const int tid) {
;     ...
;         for (int t = 0; t < nt; t += 2) {
;     ...
;             PG8_WAIT_V(8); PG8_WAIT_L(0); PG8_BAR; PG8_MMA(1, 0, At, B0); PG8_MMA(1, 1, At, B1); PG8_BAR; PG8_SCHED;
;         }
;         if constexpr (ALIGN_EPI) { if (wr == 0) PG8_BAR; }
	s_barrier
	s_add_i32 s88, s88, 2
	s_add_u32 s48, s48, 0x10000
	s_addc_u32 s49, s49, 0
	s_add_u32 s86, s86, 0x10000
	s_addc_u32 s87, s87, 0
	s_cmp_gt_u32 s88, 29
	s_cbranch_scc0 .LBB0_385
	s_and_b64 vcc, exec, s[34:35]
	s_cbranch_vccz .LBB0_388
	s_barrier

; #define PG8_STAGE(bufoff, gbase, voff) do { _Pragma("unroll") for (int _i = 0; _i < 2; ++_i) \
;         __builtin_amdgcn_global_load_lds((const unsigned*)((const char*)(gbase) + (voff)[_i]), (LAS unsigned*)(lds + (bufoff) + ldsw + _i * 8192), 16, 0, 0); } while (0)
; #define PG8_LDA(dst, b, h) do { _Pragma("unroll") for (int m = 0; m < 4; ++m) _Pragma("unroll") for (int k = 0; k < 2; ++k) dst[m][k] = *(const LAS bf16x8*)(lds + PG8_SA(b, h) + aoff + m * 2048 + k * 1024); } while (0)
; #define PG8_LDB(dst, b, h) do { _Pragma("unroll") for (int n = 0; n < 2; ++n) _Pragma("unroll") for (int k = 0; k < 2; ++k) dst[n][k] = *(const LAS bf16x8*)(lds + PG8_SB(b, h) + boff + n * 2048 + k * 1024); } while (0)
; #define PG8_SCHED __builtin_amdgcn_sched_barrier(0)
; template <class Epi, bool ALIGN_EPI>
; __device__ __forceinline__ void gemm_phase(LAS unsigned char* lds, const Gemm g, const StaticOrder& S, const Epi& E, const int tid) {
;     ...
;             const bool last = (t == nt - 2);
;             const char* a1 = cA + (size_t)(t + 1) * kstepA;
;             const char* a2 = last ? nA : cA + (size_t)(t + 2) * kstepA; const char* b2 = last ? nB : cB + (size_t)(t + 2) * kstepB;
;             const char* a3 = a2 + kstepA; const char* b3 = b2 + kstepB;
;             PG8_LDB(B0, 0, 0); PG8_LDB(B1, 0, 1); PG8_SCHED; PG8_LDA(At, 0, 0); PG8_STAGE(PG8_SA(1, 1), a1 + hstepA, voffA);
.LBB0_847:
	s_add_u32 s22, s10, 0xfff80080
	s_addc_u32 s23, s11, -1
	s_add_i32 s87, 0, 0x10000
	s_cmp_eq_u32 s86, 28
	s_cselect_b32 s35, s49, s23
	s_cselect_b32 s34, s82, s22
	v_add_u32_e32 v0, s87, v154
	s_cselect_b32 s23, s47, s85
	s_cselect_b32 s22, s83, s84
	s_add_i32 s90, 0, 0x14000
	s_waitcnt lgkmcnt(0)
	ds_read_b128 v[132:135], v0
	ds_read_b128 v[148:151], v0 offset:1024
	ds_read_b128 v[156:159], v0 offset:2048
	ds_read_b128 v[160:163], v0 offset:3072
	v_add_u32_e32 v0, s90, v154
	ds_read_b128 v[164:167], v0
	ds_read_b128 v[168:171], v0 offset:1024
	ds_read_b128 v[172:175], v0 offset:2048
	ds_read_b128 v[176:179], v0 offset:3072
	s_add_i32 m0, s70, 0xc000
	ds_read_b128 v[180:183], v155
	ds_read_b128 v[184:187], v155 offset:1024
	ds_read_b128 v[188:191], v155 offset:2048
	ds_read_b128 v[192:195], v155 offset:3072
	ds_read_b128 v[196:199], v155 offset:4096
	ds_read_b128 v[214:217], v155 offset:5120
	ds_read_b128 v[218:221], v155 offset:6144

; #define PG8_STAGE(bufoff, gbase, voff) do { _Pragma("unroll") for (int _i = 0; _i < 2; ++_i) \
;         __builtin_amdgcn_global_load_lds((const unsigned*)((const char*)(gbase) + (voff)[_i]), (LAS unsigned*)(lds + (bufoff) + ldsw + _i * 8192), 16, 0, 0); } while (0)
; #define PG8_LDA(dst, b, h) do { _Pragma("unroll") for (int m = 0; m < 4; ++m) _Pragma("unroll") for (int k = 0; k < 2; ++k) dst[m][k] = *(const LAS bf16x8*)(lds + PG8_SA(b, h) + aoff + m * 2048 + k * 1024); } while (0)
; #define PG8_LDB(dst, b, h) do { _Pragma("unroll") for (int n = 0; n < 2; ++n) _Pragma("unroll") for (int k = 0; k < 2; ++k) dst[n][k] = *(const LAS bf16x8*)(lds + PG8_SB(b, h) + boff + n * 2048 + k * 1024); } while (0)
; #define PG8_MMA(ai, bj, At, Bt) do { __builtin_amdgcn_s_setprio(1); _Pragma("unroll") for (int m = 0; m < 4; ++m) _Pragma("unroll") for (int n = 0; n < 2; ++n) _Pragma("unroll") for (int k = 0; k < 2; ++k) \
;         acc[ai][bj][m][n] = __builtin_amdgcn_mfma_f32_16x16x32_bf16(Bt[n][k], At[m][k], acc[ai][bj][m][n], 0, 0, 0); __builtin_amdgcn_s_setprio(0); } while (0)
; #define PG8_WAIT_V(n) asm volatile("s_waitcnt vmcnt(" #n ")" ::: "memory")
; #define PG8_WAIT_L(n) asm volatile("s_waitcnt lgkmcnt(" #n ")" ::: "memory")
; #define PG8_BAR __builtin_amdgcn_s_barrier()
; #define PG8_SCHED __builtin_amdgcn_sched_barrier(0)
; template <class Epi, bool ALIGN_EPI>
; __device__ __forceinline__ void gemm_phase(LAS unsigned char* lds, const Gemm g, const StaticOrder& S, const Epi& E, const int tid) {
;     ...
;             PG8_LDB(B0, 0, 0); PG8_LDB(B1, 0, 1); PG8_SCHED; PG8_LDA(At, 0, 0); PG8_STAGE(PG8_SA(1, 1), a1 + hstepA, voffA);
;             PG8_WAIT_V(8); PG8_WAIT_L(0); PG8_BAR; PG8_MMA(0, 0, At, B0); PG8_MMA(0, 1, At, B1); PG8_BAR; PG8_SCHED;
	global_load_lds_dwordx4 v144, s[10:11]
	s_add_i32 m0, s70, 0xe000
	ds_read_b128 v[222:225], v155 offset:7168
	global_load_lds_dwordx4 v146, s[10:11]
	s_waitcnt vmcnt(8)
	s_waitcnt lgkmcnt(0)
	s_barrier


; #define PG8_MMA(ai, bj, At, Bt) do { __builtin_amdgcn_s_setprio(1); _Pragma("unroll") for (int m = 0; m < 4; ++m) _Pragma("unroll") for (int n = 0; n < 2; ++n) _Pragma("unroll") for (int k = 0; k < 2; ++k) \
;         acc[ai][bj][m][n] = __builtin_amdgcn_mfma_f32_16x16x32_bf16(Bt[n][k], At[m][k], acc[ai][bj][m][n], 0, 0, 0); __builtin_amdgcn_s_setprio(0); } while (0)
; #define PG8_WAIT_V(n) asm volatile("s_waitcnt vmcnt(" #n ")" ::: "memory")
; #define PG8_WAIT_L(n) asm volatile("s_waitcnt lgkmcnt(" #n ")" ::: "memory")
; #define PG8_BAR __builtin_amdgcn_s_barrier()
; #define PG8_SCHED __builtin_amdgcn_sched_barrier(0)
; template <class Epi, bool ALIGN_EPI>
; __device__ __forceinline__ void gemm_phase(LAS unsigned char* lds, const Gemm g, const StaticOrder& S, const Epi& E, const int tid) {
;     ...
;             PG8_WAIT_V(8); PG8_WAIT_L(0); PG8_BAR; PG8_MMA(0, 0, At, B0); PG8_MMA(0, 1, At, B1); PG8_BAR; PG8_SCHED;
	v_mfma_f32_16x16x32_bf16 v[8:11], v[132:135], v[180:183], v[8:11]
	v_mfma_f32_16x16x32_bf16 v[56:59], v[156:159], v[180:183], v[56:59]
	v_mfma_f32_16x16x32_bf16 v[52:55], v[132:135], v[188:191], v[52:55]
	v_mfma_f32_16x16x32_bf16 v[48:51], v[156:159], v[188:191], v[48:51]
	v_mfma_f32_16x16x32_bf16 v[44:47], v[132:135], v[196:199], v[44:47]
	v_mfma_f32_16x16x32_bf16 v[40:43], v[156:159], v[196:199], v[40:43]
	v_mfma_f32_16x16x32_bf16 v[36:39], v[132:135], v[218:221], v[36:39]
	v_mfma_f32_16x16x32_bf16 v[32:35], v[156:159], v[218:221], v[32:35]
	v_mfma_f32_16x16x32_bf16 v[8:11], v[148:151], v[184:187], v[8:11]
	v_mfma_f32_16x16x32_bf16 v[56:59], v[160:163], v[184:187], v[56:59]
	v_mfma_f32_16x16x32_bf16 v[52:55], v[148:151], v[192:195], v[52:55]
	v_mfma_f32_16x16x32_bf16 v[48:51], v[160:163], v[192:195], v[48:51]
	v_mfma_f32_16x16x32_bf16 v[44:47], v[148:151], v[214:217], v[44:47]
	v_mfma_f32_16x16x32_bf16 v[40:43], v[160:163], v[214:217], v[40:43]
	v_mfma_f32_16x16x32_bf16 v[36:39], v[148:151], v[222:225], v[36:39]
	v_mfma_f32_16x16x32_bf16 v[32:35], v[160:163], v[222:225], v[32:35]


; #define PG8_MMA(ai, bj, At, Bt) do { __builtin_amdgcn_s_setprio(1); _Pragma("unroll") for (int m = 0; m < 4; ++m) _Pragma("unroll") for (int n = 0; n < 2; ++n) _Pragma("unroll") for (int k = 0; k < 2; ++k) \
;         acc[ai][bj][m][n] = __builtin_amdgcn_mfma_f32_16x16x32_bf16(Bt[n][k], At[m][k], acc[ai][bj][m][n], 0, 0, 0); __builtin_amdgcn_s_setprio(0); } while (0)
; #define PG8_WAIT_V(n) asm volatile("s_waitcnt vmcnt(" #n ")" ::: "memory")
; #define PG8_WAIT_L(n) asm volatile("s_waitcnt lgkmcnt(" #n ")" ::: "memory")
; #define PG8_BAR __builtin_amdgcn_s_barrier()
; #define PG8_SCHED __builtin_amdgcn_sched_barrier(0)
; template <class Epi, bool ALIGN_EPI>
; __device__ __forceinline__ void gemm_phase(LAS unsigned char* lds, const Gemm g, const StaticOrder& S, const Epi& E, const int tid) {
;     ...
;             PG8_WAIT_V(8); PG8_WAIT_L(0); PG8_BAR; PG8_MMA(0, 0, At, B0); PG8_MMA(0, 1, At, B1); PG8_BAR; PG8_SCHED;
	v_mfma_f32_16x16x32_bf16 v[2:5], v[164:167], v[180:183], v[4:7]
	v_mfma_f32_16x16x32_bf16 v[28:31], v[172:175], v[180:183], v[28:31]
	v_mfma_f32_16x16x32_bf16 v[96:99], v[164:167], v[188:191], v[96:99]
	v_mfma_f32_16x16x32_bf16 v[92:95], v[172:175], v[188:191], v[92:95]
	v_mfma_f32_16x16x32_bf16 v[88:91], v[164:167], v[196:199], v[88:91]
	v_mfma_f32_16x16x32_bf16 v[84:87], v[172:175], v[196:199], v[84:87]
	v_mfma_f32_16x16x32_bf16 v[80:83], v[164:167], v[218:221], v[80:83]
	v_mfma_f32_16x16x32_bf16 v[76:79], v[172:175], v[218:221], v[76:79]
	v_mfma_f32_16x16x32_bf16 v[2:5], v[168:171], v[184:187], v[2:5]
	v_mfma_f32_16x16x32_bf16 v[28:31], v[176:179], v[184:187], v[28:31]
	v_mfma_f32_16x16x32_bf16 v[96:99], v[168:171], v[192:195], v[96:99]
	v_mfma_f32_16x16x32_bf16 v[92:95], v[176:179], v[192:195], v[92:95]
	v_mfma_f32_16x16x32_bf16 v[88:91], v[168:171], v[214:217], v[88:91]
	v_mfma_f32_16x16x32_bf16 v[84:87], v[176:179], v[214:217], v[84:87]
	v_mfma_f32_16x16x32_bf16 v[80:83], v[168:171], v[222:225], v[80:83]
	v_mfma_f32_16x16x32_bf16 v[76:79], v[176:179], v[222:225], v[76:79]

; #define PG8_STAGE(bufoff, gbase, voff) do { _Pragma("unroll") for (int _i = 0; _i < 2; ++_i) \
;         __builtin_amdgcn_global_load_lds((const unsigned*)((const char*)(gbase) + (voff)[_i]), (LAS unsigned*)(lds + (bufoff) + ldsw + _i * 8192), 16, 0, 0); } while (0)
; #define PG8_LDA(dst, b, h) do { _Pragma("unroll") for (int m = 0; m < 4; ++m) _Pragma("unroll") for (int k = 0; k < 2; ++k) dst[m][k] = *(const LAS bf16x8*)(lds + PG8_SA(b, h) + aoff + m * 2048 + k * 1024); } while (0)
; #define PG8_MMA(ai, bj, At, Bt) do { __builtin_amdgcn_s_setprio(1); _Pragma("unroll") for (int m = 0; m < 4; ++m) _Pragma("unroll") for (int n = 0; n < 2; ++n) _Pragma("unroll") for (int k = 0; k < 2; ++k) \
;         acc[ai][bj][m][n] = __builtin_amdgcn_mfma_f32_16x16x32_bf16(Bt[n][k], At[m][k], acc[ai][bj][m][n], 0, 0, 0); __builtin_amdgcn_s_setprio(0); } while (0)
; #define PG8_WAIT_V(n) asm volatile("s_waitcnt vmcnt(" #n ")" ::: "memory")
; #define PG8_WAIT_L(n) asm volatile("s_waitcnt lgkmcnt(" #n ")" ::: "memory")
; #define PG8_BAR __builtin_amdgcn_s_barrier()
; #define PG8_SCHED __builtin_amdgcn_sched_barrier(0)
; template <class Epi, bool ALIGN_EPI>
; __device__ __forceinline__ void gemm_phase(LAS unsigned char* lds, const Gemm g, const StaticOrder& S, const Epi& E, const int tid) {
;     ...
;             PG8_WAIT_V(8); PG8_WAIT_L(0); PG8_BAR; PG8_MMA(0, 0, At, B0); PG8_MMA(0, 1, At, B1); PG8_BAR; PG8_SCHED;
;             PG8_LDA(At, 0, 1); PG8_STAGE(PG8_SB(0, 0), b2, voffB); PG8_STAGE(PG8_SB(0, 1), b2 + hstepB, voffB); PG8_STAGE(PG8_SA(0, 0), a2, voffA);
	s_barrier
	s_add_i32 s87, s87, s61
	s_mov_b32 m0, s87
	ds_read_b128 v[180:183], v155 offset:16384
	ds_read_b128 v[184:187], v155 offset:17408
	ds_read_b128 v[188:191], v155 offset:18432
	ds_read_b128 v[192:195], v155 offset:19456
	ds_read_b128 v[196:199], v155 offset:20480
	ds_read_b128 v[214:217], v155 offset:21504


; #define PG8_STAGE(bufoff, gbase, voff) do { _Pragma("unroll") for (int _i = 0; _i < 2; ++_i) \
;         __builtin_amdgcn_global_load_lds((const unsigned*)((const char*)(gbase) + (voff)[_i]), (LAS unsigned*)(lds + (bufoff) + ldsw + _i * 8192), 16, 0, 0); } while (0)
; #define PG8_LDA(dst, b, h) do { _Pragma("unroll") for (int m = 0; m < 4; ++m) _Pragma("unroll") for (int k = 0; k < 2; ++k) dst[m][k] = *(const LAS bf16x8*)(lds + PG8_SA(b, h) + aoff + m * 2048 + k * 1024); } while (0)
; #define PG8_MMA(ai, bj, At, Bt) do { __builtin_amdgcn_s_setprio(1); _Pragma("unroll") for (int m = 0; m < 4; ++m) _Pragma("unroll") for (int n = 0; n < 2; ++n) _Pragma("unroll") for (int k = 0; k < 2; ++k) \
;         acc[ai][bj][m][n] = __builtin_amdgcn_mfma_f32_16x16x32_bf16(Bt[n][k], At[m][k], acc[ai][bj][m][n], 0, 0, 0); __builtin_amdgcn_s_setprio(0); } while (0)
; #define PG8_WAIT_V(n) asm volatile("s_waitcnt vmcnt(" #n ")" ::: "memory")
; #define PG8_WAIT_L(n) asm volatile("s_waitcnt lgkmcnt(" #n ")" ::: "memory")
; #define PG8_BAR __builtin_amdgcn_s_barrier()
; #define PG8_SCHED __builtin_amdgcn_sched_barrier(0)
; template <class Epi, bool ALIGN_EPI>
; __device__ __forceinline__ void gemm_phase(LAS unsigned char* lds, const Gemm g, const StaticOrder& S, const Epi& E, const int tid) {
;     ...
;             PG8_LDA(At, 0, 1); PG8_STAGE(PG8_SB(0, 0), b2, voffB); PG8_STAGE(PG8_SB(0, 1), b2 + hstepB, voffB); PG8_STAGE(PG8_SA(0, 0), a2, voffA);
;             PG8_WAIT_V(8); PG8_WAIT_L(0); PG8_BAR; PG8_MMA(1, 0, At, B0); PG8_MMA(1, 1, At, B1); PG8_BAR; PG8_SCHED;
	global_load_lds_dwordx4 v140, s[22:23]
	s_add_i32 m0, s87, 0x2000
	s_add_u32 s88, s22, 0x4000
	s_addc_u32 s89, s23, 0
	s_add_i32 s87, s90, s61
	global_load_lds_dwordx4 v136, s[22:23]
	s_mov_b32 m0, s87
	v_lshl_add_u64 v[152:153], s[34:35], 0, v[142:143]
	global_load_lds_dwordx4 v140, s[88:89]
	s_add_i32 m0, s87, 0x2000
	v_lshl_add_u64 v[200:201], s[34:35], 0, v[138:139]
	global_load_lds_dwordx4 v136, s[88:89]
	s_mov_b32 m0, s70
	ds_read_b128 v[222:225], v155 offset:23552
	global_load_lds_dwordx4 v[152:153], off
	s_mov_b32 m0, s71
	ds_read_b128 v[218:221], v155 offset:22528
	global_load_lds_dwordx4 v[200:201], off
	s_waitcnt vmcnt(8)
	s_waitcnt lgkmcnt(0)
	s_barrier


; #define PG8_MMA(ai, bj, At, Bt) do { __builtin_amdgcn_s_setprio(1); _Pragma("unroll") for (int m = 0; m < 4; ++m) _Pragma("unroll") for (int n = 0; n < 2; ++n) _Pragma("unroll") for (int k = 0; k < 2; ++k) \
;         acc[ai][bj][m][n] = __builtin_amdgcn_mfma_f32_16x16x32_bf16(Bt[n][k], At[m][k], acc[ai][bj][m][n], 0, 0, 0); __builtin_amdgcn_s_setprio(0); } while (0)
; #define PG8_WAIT_V(n) asm volatile("s_waitcnt vmcnt(" #n ")" ::: "memory")
; #define PG8_WAIT_L(n) asm volatile("s_waitcnt lgkmcnt(" #n ")" ::: "memory")
; #define PG8_BAR __builtin_amdgcn_s_barrier()
; #define PG8_SCHED __builtin_amdgcn_sched_barrier(0)
; template <class Epi, bool ALIGN_EPI>
; __device__ __forceinline__ void gemm_phase(LAS unsigned char* lds, const Gemm g, const StaticOrder& S, const Epi& E, const int tid) {
;     ...
;             PG8_WAIT_V(8); PG8_WAIT_L(0); PG8_BAR; PG8_MMA(1, 0, At, B0); PG8_MMA(1, 1, At, B1); PG8_BAR; PG8_SCHED;
	v_mfma_f32_16x16x32_bf16 v[24:27], v[132:135], v[180:183], v[24:27]
	v_mfma_f32_16x16x32_bf16 v[20:23], v[156:159], v[180:183], v[20:23]
	v_mfma_f32_16x16x32_bf16 v[64:67], v[132:135], v[188:191], v[64:67]
	v_mfma_f32_16x16x32_bf16 v[72:75], v[156:159], v[188:191], v[72:75]
	v_mfma_f32_16x16x32_bf16 v[16:19], v[132:135], v[196:199], v[16:19]
	v_mfma_f32_16x16x32_bf16 v[12:15], v[156:159], v[196:199], v[12:15]
	v_mfma_f32_16x16x32_bf16 v[60:63], v[132:135], v[218:221], v[60:63]
	v_mfma_f32_16x16x32_bf16 v[68:71], v[156:159], v[218:221], v[68:71]
	v_mfma_f32_16x16x32_bf16 v[24:27], v[148:151], v[184:187], v[24:27]
	v_mfma_f32_16x16x32_bf16 v[20:23], v[160:163], v[184:187], v[20:23]
	v_mfma_f32_16x16x32_bf16 v[64:67], v[148:151], v[192:195], v[64:67]
	v_mfma_f32_16x16x32_bf16 v[72:75], v[160:163], v[192:195], v[72:75]
	v_mfma_f32_16x16x32_bf16 v[16:19], v[148:151], v[214:217], v[16:19]
	v_mfma_f32_16x16x32_bf16 v[12:15], v[160:163], v[214:217], v[12:15]
	v_mfma_f32_16x16x32_bf16 v[60:63], v[148:151], v[222:225], v[60:63]
	v_mfma_f32_16x16x32_bf16 v[68:71], v[160:163], v[222:225], v[68:71]


; #define PG8_MMA(ai, bj, At, Bt) do { __builtin_amdgcn_s_setprio(1); _Pragma("unroll") for (int m = 0; m < 4; ++m) _Pragma("unroll") for (int n = 0; n < 2; ++n) _Pragma("unroll") for (int k = 0; k < 2; ++k) \
;         acc[ai][bj][m][n] = __builtin_amdgcn_mfma_f32_16x16x32_bf16(Bt[n][k], At[m][k], acc[ai][bj][m][n], 0, 0, 0); __builtin_amdgcn_s_setprio(0); } while (0)
; #define PG8_WAIT_V(n) asm volatile("s_waitcnt vmcnt(" #n ")" ::: "memory")
; #define PG8_WAIT_L(n) asm volatile("s_waitcnt lgkmcnt(" #n ")" ::: "memory")
; #define PG8_BAR __builtin_amdgcn_s_barrier()
; #define PG8_SCHED __builtin_amdgcn_sched_barrier(0)
; template <class Epi, bool ALIGN_EPI>
; __device__ __forceinline__ void gemm_phase(LAS unsigned char* lds, const Gemm g, const StaticOrder& S, const Epi& E, const int tid) {
;     ...
;             PG8_WAIT_V(8); PG8_WAIT_L(0); PG8_BAR; PG8_MMA(1, 0, At, B0); PG8_MMA(1, 1, At, B1); PG8_BAR; PG8_SCHED;
	v_mfma_f32_16x16x32_bf16 v[128:131], v[164:167], v[180:183], v[128:131]
	v_mfma_f32_16x16x32_bf16 v[124:127], v[172:175], v[180:183], v[124:127]
	v_mfma_f32_16x16x32_bf16 v[120:123], v[164:167], v[188:191], v[120:123]
	v_mfma_f32_16x16x32_bf16 v[116:119], v[172:175], v[188:191], v[116:119]
	v_mfma_f32_16x16x32_bf16 v[112:115], v[164:167], v[196:199], v[112:115]
	v_mfma_f32_16x16x32_bf16 v[108:111], v[172:175], v[196:199], v[108:111]
	v_mfma_f32_16x16x32_bf16 v[104:107], v[164:167], v[218:221], v[104:107]
	v_mfma_f32_16x16x32_bf16 v[100:103], v[172:175], v[218:221], v[100:103]
	v_mfma_f32_16x16x32_bf16 v[128:131], v[168:171], v[184:187], v[128:131]
	v_mfma_f32_16x16x32_bf16 v[124:127], v[176:179], v[184:187], v[124:127]
	v_mfma_f32_16x16x32_bf16 v[120:123], v[168:171], v[192:195], v[120:123]
	v_mfma_f32_16x16x32_bf16 v[116:119], v[176:179], v[192:195], v[116:119]
	v_mfma_f32_16x16x32_bf16 v[112:115], v[168:171], v[214:217], v[112:115]
	v_mfma_f32_16x16x32_bf16 v[108:111], v[176:179], v[214:217], v[108:111]
	v_mfma_f32_16x16x32_bf16 v[104:107], v[168:171], v[222:225], v[104:107]
	v_mfma_f32_16x16x32_bf16 v[100:103], v[176:179], v[222:225], v[100:103]

; #define PG8_STAGE(bufoff, gbase, voff) do { _Pragma("unroll") for (int _i = 0; _i < 2; ++_i) \
;         __builtin_amdgcn_global_load_lds((const unsigned*)((const char*)(gbase) + (voff)[_i]), (LAS unsigned*)(lds + (bufoff) + ldsw + _i * 8192), 16, 0, 0); } while (0)
; #define PG8_LDA(dst, b, h) do { _Pragma("unroll") for (int m = 0; m < 4; ++m) _Pragma("unroll") for (int k = 0; k < 2; ++k) dst[m][k] = *(const LAS bf16x8*)(lds + PG8_SA(b, h) + aoff + m * 2048 + k * 1024); } while (0)
; #define PG8_LDB(dst, b, h) do { _Pragma("unroll") for (int n = 0; n < 2; ++n) _Pragma("unroll") for (int k = 0; k < 2; ++k) dst[n][k] = *(const LAS bf16x8*)(lds + PG8_SB(b, h) + boff + n * 2048 + k * 1024); } while (0)
; #define PG8_SCHED __builtin_amdgcn_sched_barrier(0)
; template <class Epi, bool ALIGN_EPI>
; __device__ __forceinline__ void gemm_phase(LAS unsigned char* lds, const Gemm g, const StaticOrder& S, const Epi& E, const int tid) {
;     ...
;             PG8_LDB(B0, 1, 0); PG8_LDB(B1, 1, 1); PG8_SCHED; PG8_LDA(At, 1, 0); PG8_STAGE(PG8_SA(0, 1), a2 + hstepA, voffA);
	s_barrier
	s_add_i32 s87, 0, 0x18000
	v_add_u32_e32 v0, s87, v154
	s_add_i32 s88, 0, 0x1c000
	ds_read_b128 v[132:135], v0
	ds_read_b128 v[148:151], v0 offset:1024
	ds_read_b128 v[156:159], v0 offset:2048
	ds_read_b128 v[160:163], v0 offset:3072
	v_add_u32_e32 v0, s88, v154
	ds_read_b128 v[164:167], v0
	ds_read_b128 v[168:171], v0 offset:1024
	ds_read_b128 v[172:175], v0 offset:2048
	ds_read_b128 v[176:179], v0 offset:3072
	s_add_u32 s34, s34, 0x80000
	s_addc_u32 s35, s35, 0
	s_mov_b32 m0, s72
	ds_read_b128 v[180:183], v155 offset:32768
	ds_read_b128 v[184:187], v155 offset:33792
	ds_read_b128 v[188:191], v155 offset:34816
	ds_read_b128 v[192:195], v155 offset:35840
	ds_read_b128 v[196:199], v155 offset:36864
	ds_read_b128 v[214:217], v155 offset:37888
	ds_read_b128 v[218:221], v155 offset:38912

; #define PG8_STAGE(bufoff, gbase, voff) do { _Pragma("unroll") for (int _i = 0; _i < 2; ++_i) \
;         __builtin_amdgcn_global_load_lds((const unsigned*)((const char*)(gbase) + (voff)[_i]), (LAS unsigned*)(lds + (bufoff) + ldsw + _i * 8192), 16, 0, 0); } while (0)
; #define PG8_LDA(dst, b, h) do { _Pragma("unroll") for (int m = 0; m < 4; ++m) _Pragma("unroll") for (int k = 0; k < 2; ++k) dst[m][k] = *(const LAS bf16x8*)(lds + PG8_SA(b, h) + aoff + m * 2048 + k * 1024); } while (0)
; #define PG8_LDB(dst, b, h) do { _Pragma("unroll") for (int n = 0; n < 2; ++n) _Pragma("unroll") for (int k = 0; k < 2; ++k) dst[n][k] = *(const LAS bf16x8*)(lds + PG8_SB(b, h) + boff + n * 2048 + k * 1024); } while (0)
; #define PG8_MMA(ai, bj, At, Bt) do { __builtin_amdgcn_s_setprio(1); _Pragma("unroll") for (int m = 0; m < 4; ++m) _Pragma("unroll") for (int n = 0; n < 2; ++n) _Pragma("unroll") for (int k = 0; k < 2; ++k) \
;         acc[ai][bj][m][n] = __builtin_amdgcn_mfma_f32_16x16x32_bf16(Bt[n][k], At[m][k], acc[ai][bj][m][n], 0, 0, 0); __builtin_amdgcn_s_setprio(0); } while (0)
; #define PG8_WAIT_V(n) asm volatile("s_waitcnt vmcnt(" #n ")" ::: "memory")
; #define PG8_WAIT_L(n) asm volatile("s_waitcnt lgkmcnt(" #n ")" ::: "memory")
; #define PG8_BAR __builtin_amdgcn_s_barrier()
; #define PG8_SCHED __builtin_amdgcn_sched_barrier(0)
; template <class Epi, bool ALIGN_EPI>
; __device__ __forceinline__ void gemm_phase(LAS unsigned char* lds, const Gemm g, const StaticOrder& S, const Epi& E, const int tid) {
;     ...
;             PG8_LDB(B0, 1, 0); PG8_LDB(B1, 1, 1); PG8_SCHED; PG8_LDA(At, 1, 0); PG8_STAGE(PG8_SA(0, 1), a2 + hstepA, voffA);
;             PG8_WAIT_V(8); PG8_WAIT_L(0); PG8_BAR; PG8_MMA(0, 0, At, B0); PG8_MMA(0, 1, At, B1); PG8_BAR; PG8_SCHED;
	global_load_lds_dwordx4 v142, s[34:35]
	s_mov_b32 m0, s73
	ds_read_b128 v[222:225], v155 offset:39936
	global_load_lds_dwordx4 v138, s[34:35]
	s_waitcnt vmcnt(8)
	s_waitcnt lgkmcnt(0)
	s_barrier


; #define PG8_MMA(ai, bj, At, Bt) do { __builtin_amdgcn_s_setprio(1); _Pragma("unroll") for (int m = 0; m < 4; ++m) _Pragma("unroll") for (int n = 0; n < 2; ++n) _Pragma("unroll") for (int k = 0; k < 2; ++k) \
;         acc[ai][bj][m][n] = __builtin_amdgcn_mfma_f32_16x16x32_bf16(Bt[n][k], At[m][k], acc[ai][bj][m][n], 0, 0, 0); __builtin_amdgcn_s_setprio(0); } while (0)
; #define PG8_WAIT_V(n) asm volatile("s_waitcnt vmcnt(" #n ")" ::: "memory")
; #define PG8_WAIT_L(n) asm volatile("s_waitcnt lgkmcnt(" #n ")" ::: "memory")
; #define PG8_BAR __builtin_amdgcn_s_barrier()
; #define PG8_SCHED __builtin_amdgcn_sched_barrier(0)
; template <class Epi, bool ALIGN_EPI>
; __device__ __forceinline__ void gemm_phase(LAS unsigned char* lds, const Gemm g, const StaticOrder& S, const Epi& E, const int tid) {
;     ...
;             PG8_WAIT_V(8); PG8_WAIT_L(0); PG8_BAR; PG8_MMA(0, 0, At, B0); PG8_MMA(0, 1, At, B1); PG8_BAR; PG8_SCHED;
	v_mfma_f32_16x16x32_bf16 v[6:9], v[132:135], v[180:183], v[8:11]
	v_mfma_f32_16x16x32_bf16 v[56:59], v[156:159], v[180:183], v[56:59]
	v_mfma_f32_16x16x32_bf16 v[52:55], v[132:135], v[188:191], v[52:55]
	v_mfma_f32_16x16x32_bf16 v[48:51], v[156:159], v[188:191], v[48:51]
	v_mfma_f32_16x16x32_bf16 v[44:47], v[132:135], v[196:199], v[44:47]
	v_mfma_f32_16x16x32_bf16 v[40:43], v[156:159], v[196:199], v[40:43]
	v_mfma_f32_16x16x32_bf16 v[36:39], v[132:135], v[218:221], v[36:39]
	v_mfma_f32_16x16x32_bf16 v[32:35], v[156:159], v[218:221], v[32:35]
	v_mfma_f32_16x16x32_bf16 v[8:11], v[148:151], v[184:187], v[6:9]
	v_mfma_f32_16x16x32_bf16 v[56:59], v[160:163], v[184:187], v[56:59]
	v_mfma_f32_16x16x32_bf16 v[52:55], v[148:151], v[192:195], v[52:55]
	v_mfma_f32_16x16x32_bf16 v[48:51], v[160:163], v[192:195], v[48:51]
	v_mfma_f32_16x16x32_bf16 v[44:47], v[148:151], v[214:217], v[44:47]
	v_mfma_f32_16x16x32_bf16 v[40:43], v[160:163], v[214:217], v[40:43]
	v_mfma_f32_16x16x32_bf16 v[36:39], v[148:151], v[222:225], v[36:39]
	v_mfma_f32_16x16x32_bf16 v[32:35], v[160:163], v[222:225], v[32:35]


; #define PG8_MMA(ai, bj, At, Bt) do { __builtin_amdgcn_s_setprio(1); _Pragma("unroll") for (int m = 0; m < 4; ++m) _Pragma("unroll") for (int n = 0; n < 2; ++n) _Pragma("unroll") for (int k = 0; k < 2; ++k) \
;         acc[ai][bj][m][n] = __builtin_amdgcn_mfma_f32_16x16x32_bf16(Bt[n][k], At[m][k], acc[ai][bj][m][n], 0, 0, 0); __builtin_amdgcn_s_setprio(0); } while (0)
; #define PG8_WAIT_V(n) asm volatile("s_waitcnt vmcnt(" #n ")" ::: "memory")
; #define PG8_WAIT_L(n) asm volatile("s_waitcnt lgkmcnt(" #n ")" ::: "memory")
; #define PG8_BAR __builtin_amdgcn_s_barrier()
; #define PG8_SCHED __builtin_amdgcn_sched_barrier(0)
; template <class Epi, bool ALIGN_EPI>
; __device__ __forceinline__ void gemm_phase(LAS unsigned char* lds, const Gemm g, const StaticOrder& S, const Epi& E, const int tid) {
;     ...
;             PG8_WAIT_V(8); PG8_WAIT_L(0); PG8_BAR; PG8_MMA(0, 0, At, B0); PG8_MMA(0, 1, At, B1); PG8_BAR; PG8_SCHED;
	v_mfma_f32_16x16x32_bf16 v[2:5], v[164:167], v[180:183], v[2:5]
	v_mfma_f32_16x16x32_bf16 v[28:31], v[172:175], v[180:183], v[28:31]
	v_mfma_f32_16x16x32_bf16 v[96:99], v[164:167], v[188:191], v[96:99]
	v_mfma_f32_16x16x32_bf16 v[92:95], v[172:175], v[188:191], v[92:95]
	v_mfma_f32_16x16x32_bf16 v[88:91], v[164:167], v[196:199], v[88:91]
	v_mfma_f32_16x16x32_bf16 v[84:87], v[172:175], v[196:199], v[84:87]
	v_mfma_f32_16x16x32_bf16 v[80:83], v[164:167], v[218:221], v[80:83]
	v_mfma_f32_16x16x32_bf16 v[76:79], v[172:175], v[218:221], v[76:79]
	v_mfma_f32_16x16x32_bf16 v[4:7], v[168:171], v[184:187], v[2:5]
	v_mfma_f32_16x16x32_bf16 v[28:31], v[176:179], v[184:187], v[28:31]
	v_mfma_f32_16x16x32_bf16 v[96:99], v[168:171], v[192:195], v[96:99]
	v_mfma_f32_16x16x32_bf16 v[92:95], v[176:179], v[192:195], v[92:95]
	v_mfma_f32_16x16x32_bf16 v[88:91], v[168:171], v[214:217], v[88:91]
	v_mfma_f32_16x16x32_bf16 v[84:87], v[176:179], v[214:217], v[84:87]
	v_mfma_f32_16x16x32_bf16 v[80:83], v[168:171], v[222:225], v[80:83]
	v_mfma_f32_16x16x32_bf16 v[76:79], v[176:179], v[222:225], v[76:79]

; #define PG8_STAGE(bufoff, gbase, voff) do { _Pragma("unroll") for (int _i = 0; _i < 2; ++_i) \
;         __builtin_amdgcn_global_load_lds((const unsigned*)((const char*)(gbase) + (voff)[_i]), (LAS unsigned*)(lds + (bufoff) + ldsw + _i * 8192), 16, 0, 0); } while (0)
; #define PG8_LDA(dst, b, h) do { _Pragma("unroll") for (int m = 0; m < 4; ++m) _Pragma("unroll") for (int k = 0; k < 2; ++k) dst[m][k] = *(const LAS bf16x8*)(lds + PG8_SA(b, h) + aoff + m * 2048 + k * 1024); } while (0)
; template <class Epi, bool ALIGN_EPI>
; __device__ __forceinline__ void gemm_phase(LAS unsigned char* lds, const Gemm g, const StaticOrder& S, const Epi& E, const int tid) {
;     ...
;             PG8_LDA(At, 1, 1); PG8_STAGE(PG8_SB(1, 0), b3, voffB); PG8_STAGE(PG8_SB(1, 1), b3 + hstepB, voffB); PG8_STAGE(PG8_SA(1, 0), a3, voffA);
	s_barrier
	s_add_u32 s34, s22, 0x8000
	s_addc_u32 s35, s23, 0
	s_add_i32 s87, s87, s61
	s_mov_b32 m0, s87
	ds_read_b128 v[180:183], v155 offset:49152
	ds_read_b128 v[184:187], v155 offset:50176
	ds_read_b128 v[188:191], v155 offset:51200
	ds_read_b128 v[192:195], v155 offset:52224


; #define PG8_STAGE(bufoff, gbase, voff) do { _Pragma("unroll") for (int _i = 0; _i < 2; ++_i) \
;         __builtin_amdgcn_global_load_lds((const unsigned*)((const char*)(gbase) + (voff)[_i]), (LAS unsigned*)(lds + (bufoff) + ldsw + _i * 8192), 16, 0, 0); } while (0)
; #define PG8_LDA(dst, b, h) do { _Pragma("unroll") for (int m = 0; m < 4; ++m) _Pragma("unroll") for (int k = 0; k < 2; ++k) dst[m][k] = *(const LAS bf16x8*)(lds + PG8_SA(b, h) + aoff + m * 2048 + k * 1024); } while (0)
; #define PG8_MMA(ai, bj, At, Bt) do { __builtin_amdgcn_s_setprio(1); _Pragma("unroll") for (int m = 0; m < 4; ++m) _Pragma("unroll") for (int n = 0; n < 2; ++n) _Pragma("unroll") for (int k = 0; k < 2; ++k) \
;         acc[ai][bj][m][n] = __builtin_amdgcn_mfma_f32_16x16x32_bf16(Bt[n][k], At[m][k], acc[ai][bj][m][n], 0, 0, 0); __builtin_amdgcn_s_setprio(0); } while (0)
; #define PG8_WAIT_V(n) asm volatile("s_waitcnt vmcnt(" #n ")" ::: "memory")
; #define PG8_WAIT_L(n) asm volatile("s_waitcnt lgkmcnt(" #n ")" ::: "memory")
; #define PG8_BAR __builtin_amdgcn_s_barrier()
; #define PG8_SCHED __builtin_amdgcn_sched_barrier(0)
; template <class Epi, bool ALIGN_EPI>
; __device__ __forceinline__ void gemm_phase(LAS unsigned char* lds, const Gemm g, const StaticOrder& S, const Epi& E, const int tid) {
;     ...
;             PG8_LDA(At, 1, 1); PG8_STAGE(PG8_SB(1, 0), b3, voffB); PG8_STAGE(PG8_SB(1, 1), b3 + hstepB, voffB); PG8_STAGE(PG8_SA(1, 0), a3, voffA);
;             PG8_WAIT_V(8); PG8_WAIT_L(0); PG8_BAR; PG8_MMA(1, 0, At, B0); PG8_MMA(1, 1, At, B1); PG8_BAR; PG8_SCHED;
	global_load_lds_dwordx4 v140, s[34:35]
	s_add_i32 m0, s87, 0x2000
	s_add_u32 s22, s22, 0xc000
	s_addc_u32 s23, s23, 0
	global_load_lds_dwordx4 v136, s[34:35]
	s_add_i32 s34, s88, s61
	s_mov_b32 m0, s34
	ds_read_b128 v[222:225], v155 offset:56320
	global_load_lds_dwordx4 v140, s[22:23]
	s_add_i32 m0, s34, 0x2000
	ds_read_b128 v[218:221], v155 offset:55296
	global_load_lds_dwordx4 v136, s[22:23]
	v_lshl_add_u64 v[2:3], v[152:153], 0, s[6:7]
	s_mov_b32 m0, s78
	ds_read_b128 v[214:217], v155 offset:54272
	global_load_lds_dwordx4 v[2:3], off
	v_lshl_add_u64 v[2:3], v[200:201], 0, s[6:7]
	s_mov_b32 m0, s79
	ds_read_b128 v[196:199], v155 offset:53248
	global_load_lds_dwordx4 v[2:3], off
	s_waitcnt vmcnt(8)
	s_waitcnt lgkmcnt(0)
	s_barrier


; #define PG8_MMA(ai, bj, At, Bt) do { __builtin_amdgcn_s_setprio(1); _Pragma("unroll") for (int m = 0; m < 4; ++m) _Pragma("unroll") for (int n = 0; n < 2; ++n) _Pragma("unroll") for (int k = 0; k < 2; ++k) \
;         acc[ai][bj][m][n] = __builtin_amdgcn_mfma_f32_16x16x32_bf16(Bt[n][k], At[m][k], acc[ai][bj][m][n], 0, 0, 0); __builtin_amdgcn_s_setprio(0); } while (0)
; #define PG8_WAIT_V(n) asm volatile("s_waitcnt vmcnt(" #n ")" ::: "memory")
; #define PG8_WAIT_L(n) asm volatile("s_waitcnt lgkmcnt(" #n ")" ::: "memory")
; #define PG8_BAR __builtin_amdgcn_s_barrier()
; #define PG8_SCHED __builtin_amdgcn_sched_barrier(0)
; template <class Epi, bool ALIGN_EPI>
; __device__ __forceinline__ void gemm_phase(LAS unsigned char* lds, const Gemm g, const StaticOrder& S, const Epi& E, const int tid) {
;     ...
;             PG8_WAIT_V(8); PG8_WAIT_L(0); PG8_BAR; PG8_MMA(1, 0, At, B0); PG8_MMA(1, 1, At, B1); PG8_BAR; PG8_SCHED;
	v_mfma_f32_16x16x32_bf16 v[24:27], v[132:135], v[180:183], v[24:27]
	v_mfma_f32_16x16x32_bf16 v[20:23], v[156:159], v[180:183], v[20:23]
	v_mfma_f32_16x16x32_bf16 v[64:67], v[132:135], v[188:191], v[64:67]
	v_mfma_f32_16x16x32_bf16 v[72:75], v[156:159], v[188:191], v[72:75]
	v_mfma_f32_16x16x32_bf16 v[16:19], v[132:135], v[196:199], v[16:19]
	v_mfma_f32_16x16x32_bf16 v[12:15], v[156:159], v[196:199], v[12:15]
	v_mfma_f32_16x16x32_bf16 v[60:63], v[132:135], v[218:221], v[60:63]
	v_mfma_f32_16x16x32_bf16 v[68:71], v[156:159], v[218:221], v[68:71]
	v_mfma_f32_16x16x32_bf16 v[24:27], v[148:151], v[184:187], v[24:27]
	v_mfma_f32_16x16x32_bf16 v[20:23], v[160:163], v[184:187], v[20:23]
	v_mfma_f32_16x16x32_bf16 v[64:67], v[148:151], v[192:195], v[64:67]
	v_mfma_f32_16x16x32_bf16 v[72:75], v[160:163], v[192:195], v[72:75]
	v_mfma_f32_16x16x32_bf16 v[16:19], v[148:151], v[214:217], v[16:19]
	v_mfma_f32_16x16x32_bf16 v[12:15], v[160:163], v[214:217], v[12:15]
	v_mfma_f32_16x16x32_bf16 v[60:63], v[148:151], v[222:225], v[60:63]
	v_mfma_f32_16x16x32_bf16 v[68:71], v[160:163], v[222:225], v[68:71]


; #define PG8_MMA(ai, bj, At, Bt) do { __builtin_amdgcn_s_setprio(1); _Pragma("unroll") for (int m = 0; m < 4; ++m) _Pragma("unroll") for (int n = 0; n < 2; ++n) _Pragma("unroll") for (int k = 0; k < 2; ++k) \
;         acc[ai][bj][m][n] = __builtin_amdgcn_mfma_f32_16x16x32_bf16(Bt[n][k], At[m][k], acc[ai][bj][m][n], 0, 0, 0); __builtin_amdgcn_s_setprio(0); } while (0)
; #define PG8_WAIT_V(n) asm volatile("s_waitcnt vmcnt(" #n ")" ::: "memory")
; #define PG8_WAIT_L(n) asm volatile("s_waitcnt lgkmcnt(" #n ")" ::: "memory")
; #define PG8_BAR __builtin_amdgcn_s_barrier()
; #define PG8_SCHED __builtin_amdgcn_sched_barrier(0)
; template <class Epi, bool ALIGN_EPI>
; __device__ __forceinline__ void gemm_phase(LAS unsigned char* lds, const Gemm g, const StaticOrder& S, const Epi& E, const int tid) {
;     ...
;             PG8_WAIT_V(8); PG8_WAIT_L(0); PG8_BAR; PG8_MMA(1, 0, At, B0); PG8_MMA(1, 1, At, B1); PG8_BAR; PG8_SCHED;
	v_mfma_f32_16x16x32_bf16 v[128:131], v[164:167], v[180:183], v[128:131]
	v_mfma_f32_16x16x32_bf16 v[124:127], v[172:175], v[180:183], v[124:127]
	v_mfma_f32_16x16x32_bf16 v[120:123], v[164:167], v[188:191], v[120:123]
	v_mfma_f32_16x16x32_bf16 v[116:119], v[172:175], v[188:191], v[116:119]
	v_mfma_f32_16x16x32_bf16 v[112:115], v[164:167], v[196:199], v[112:115]
	v_mfma_f32_16x16x32_bf16 v[108:111], v[172:175], v[196:199], v[108:111]
	v_mfma_f32_16x16x32_bf16 v[104:107], v[164:167], v[218:221], v[104:107]
	v_mfma_f32_16x16x32_bf16 v[100:103], v[172:175], v[218:221], v[100:103]
	v_mfma_f32_16x16x32_bf16 v[128:131], v[168:171], v[184:187], v[128:131]
	v_mfma_f32_16x16x32_bf16 v[124:127], v[176:179], v[184:187], v[124:127]
	v_mfma_f32_16x16x32_bf16 v[120:123], v[168:171], v[192:195], v[120:123]
	v_mfma_f32_16x16x32_bf16 v[116:119], v[176:179], v[192:195], v[116:119]
	v_mfma_f32_16x16x32_bf16 v[112:115], v[168:171], v[214:217], v[112:115]
	v_mfma_f32_16x16x32_bf16 v[108:111], v[176:179], v[214:217], v[108:111]
	v_mfma_f32_16x16x32_bf16 v[104:107], v[168:171], v[222:225], v[104:107]
	v_mfma_f32_16x16x32_bf16 v[100:103], v[176:179], v[222:225], v[100:103]

; #define PG8_STAGE(bufoff, gbase, voff) do { _Pragma("unroll") for (int _i = 0; _i < 2; ++_i) \
;         __builtin_amdgcn_global_load_lds((const unsigned*)((const char*)(gbase) + (voff)[_i]), (LAS unsigned*)(lds + (bufoff) + ldsw + _i * 8192), 16, 0, 0); } while (0)
; #define PG8_LDA(dst, b, h) do { _Pragma("unroll") for (int m = 0; m < 4; ++m) _Pragma("unroll") for (int k = 0; k < 2; ++k) dst[m][k] = *(const LAS bf16x8*)(lds + PG8_SA(b, h) + aoff + m * 2048 + k * 1024); } while (0)
; #define PG8_LDB(dst, b, h) do { _Pragma("unroll") for (int n = 0; n < 2; ++n) _Pragma("unroll") for (int k = 0; k < 2; ++k) dst[n][k] = *(const LAS bf16x8*)(lds + PG8_SB(b, h) + boff + n * 2048 + k * 1024); } while (0)
; #define PG8_BAR __builtin_amdgcn_s_barrier()
; template <class Epi, bool ALIGN_EPI>
; __device__ __forceinline__ void gemm_phase(LAS unsigned char* lds, const Gemm g, const StaticOrder& S, const Epi& E, const int tid) {
;     ...
;         for (int t = 0; t < nt; t += 2) {
;             const bool last = (t == nt - 2);
;             const char* a1 = cA + (size_t)(t + 1) * kstepA;
;             const char* a2 = last ? nA : cA + (size_t)(t + 2) * kstepA; const char* b2 = last ? nB : cB + (size_t)(t + 2) * kstepB;
;             const char* a3 = a2 + kstepA; const char* b3 = b2 + kstepB;
;             PG8_LDB(B0, 0, 0); PG8_LDB(B1, 0, 1); PG8_SCHED; PG8_LDA(At, 0, 0); PG8_STAGE(PG8_SA(1, 1), a1 + hstepA, voffA);
;             PG8_WAIT_V(8); PG8_WAIT_L(0); PG8_BAR; PG8_MMA(0, 0, At, B0); PG8_MMA(0, 1, At, B1); PG8_BAR; PG8_SCHED;
;             PG8_LDA(At, 0, 1); PG8_STAGE(PG8_SB(0, 0), b2, voffB); PG8_STAGE(PG8_SB(0, 1), b2 + hstepB, voffB); PG8_STAGE(PG8_SA(0, 0), a2, voffA);
;             PG8_WAIT_V(8); PG8_WAIT_L(0); PG8_BAR; PG8_MMA(1, 0, At, B0); PG8_MMA(1, 1, At, B1); PG8_BAR; PG8_SCHED;
;             PG8_LDB(B0, 1, 0); PG8_LDB(B1, 1, 1); PG8_SCHED; PG8_LDA(At, 1, 0); PG8_STAGE(PG8_SA(0, 1), a2 + hstepA, voffA);
;             PG8_WAIT_V(8); PG8_WAIT_L(0); PG8_BAR; PG8_MMA(0, 0, At, B0); PG8_MMA(0, 1, At, B1); PG8_BAR; PG8_SCHED;
;             PG8_LDA(At, 1, 1); PG8_STAGE(PG8_SB(1, 0), b3, voffB); PG8_STAGE(PG8_SB(1, 1), b3 + hstepB, voffB); PG8_STAGE(PG8_SA(1, 0), a3, voffA);
;             PG8_WAIT_V(8); PG8_WAIT_L(0); PG8_BAR; PG8_MMA(1, 0, At, B0); PG8_MMA(1, 1, At, B1); PG8_BAR; PG8_SCHED;
;         }
;         if constexpr (ALIGN_EPI) { if (wr == 0) PG8_BAR; }
	s_barrier
	s_add_i32 s86, s86, 2
	s_add_u32 s10, s10, 0x100
	s_addc_u32 s11, s11, 0
	s_add_u32 s84, s84, 0x10000
	s_addc_u32 s85, s85, 0
	s_cmp_gt_u32 s86, 29
	s_cbranch_scc0 .LBB0_847
	s_and_b64 vcc, exec, s[44:45]
	s_cbranch_vccz .LBB0_850
	s_barrier
